# scan: S/P-specialized bodies, y k-reduction deferred to trip end via LDS partials, loader Wd unpack deferred; fixup chain matmul loads batched; first barrier = counter barrier; unit-entry drain only a
# speedup vs baseline: 1.0600x; 1.0153x over previous
; __device__ void phase_fixup(const float* FS, const bf16_t* Q, bf16_t* Y, float* sm) {
;     ...
;             const int v = tid >> 3, kc = (tid & 7) * 8;
;             const float* P = PF + (size_t)jj * 4096 + kc;
;             f32x4 a0 = *(const f32x4*)(SL + (size_t)jj * 4096 + v * 64 + kc), a1 = *(const f32x4*)(SL + (size_t)jj * 4096 + v * 64 + kc + 4);
;             for (int m = 0; m < 64; ++m) { const float cv = cur[v * 65 + m]; a0 += cv * *(const f32x4*)(P + m * 64); a1 += cv * *(const f32x4*)(P + m * 64 + 4); }
; #pragma unroll
;             for (int e = 0; e < 4; ++e) { nxt[v * 65 + kc + e] = a0[e]; nxt[v * 65 + kc + 4 + e] = a1[e]; }
;             __syncthreads();
.LBB0_35:
	v_add_u32_e32 v25, s15, v24
	ds_read2_b32 v[168:169], v25 offset0:0 offset1:1
	ds_read2_b32 v[170:171], v25 offset0:2 offset1:3
	ds_read2_b32 v[172:173], v25 offset0:4 offset1:5
	ds_read2_b32 v[174:175], v25 offset0:6 offset1:7
	global_load_dwordx4 v[104:107], v[22:23], off offset:-1024
	global_load_dwordx4 v[108:111], v[22:23], off offset:-1008
	global_load_dwordx4 v[112:115], v[22:23], off offset:-768
	global_load_dwordx4 v[116:119], v[22:23], off offset:-752
	global_load_dwordx4 v[120:123], v[22:23], off offset:-512
	global_load_dwordx4 v[124:127], v[22:23], off offset:-496
	global_load_dwordx4 v[128:131], v[22:23], off offset:-256
	global_load_dwordx4 v[132:135], v[22:23], off offset:-240
	global_load_dwordx4 v[136:139], v[22:23], off offset:0
	global_load_dwordx4 v[140:143], v[22:23], off offset:16
	global_load_dwordx4 v[144:147], v[22:23], off offset:256
	global_load_dwordx4 v[148:151], v[22:23], off offset:272
	global_load_dwordx4 v[152:155], v[22:23], off offset:512
	global_load_dwordx4 v[156:159], v[22:23], off offset:528
	global_load_dwordx4 v[160:163], v[22:23], off offset:768
	global_load_dwordx4 v[164:167], v[22:23], off offset:784
	s_add_i32 s15, s15, 32
	v_lshl_add_u64 v[22:23], v[22:23], 0, s[60:61]
	s_waitcnt lgkmcnt(0)
	s_waitcnt vmcnt(14)
	v_pk_fma_f32 v[6:7], v[104:105], v[168:169], v[6:7] op_sel_hi:[1,0,1]
	v_pk_fma_f32 v[8:9], v[106:107], v[168:169], v[8:9] op_sel_hi:[1,0,1]
	v_pk_fma_f32 v[2:3], v[108:109], v[168:169], v[2:3] op_sel_hi:[1,0,1]
	v_pk_fma_f32 v[4:5], v[110:111], v[168:169], v[4:5] op_sel_hi:[1,0,1]
	s_waitcnt vmcnt(12)
	v_pk_fma_f32 v[6:7], v[112:113], v[168:169], v[6:7] op_sel:[0,1,0]
	v_pk_fma_f32 v[8:9], v[114:115], v[168:169], v[8:9] op_sel:[0,1,0]
	v_pk_fma_f32 v[2:3], v[116:117], v[168:169], v[2:3] op_sel:[0,1,0]
	v_pk_fma_f32 v[4:5], v[118:119], v[168:169], v[4:5] op_sel:[0,1,0]
	s_waitcnt vmcnt(10)
	v_pk_fma_f32 v[6:7], v[120:121], v[170:171], v[6:7] op_sel_hi:[1,0,1]
	v_pk_fma_f32 v[8:9], v[122:123], v[170:171], v[8:9] op_sel_hi:[1,0,1]
	v_pk_fma_f32 v[2:3], v[124:125], v[170:171], v[2:3] op_sel_hi:[1,0,1]
	v_pk_fma_f32 v[4:5], v[126:127], v[170:171], v[4:5] op_sel_hi:[1,0,1]
	s_waitcnt vmcnt(8)
	v_pk_fma_f32 v[6:7], v[128:129], v[170:171], v[6:7] op_sel:[0,1,0]
	v_pk_fma_f32 v[8:9], v[130:131], v[170:171], v[8:9] op_sel:[0,1,0]
	v_pk_fma_f32 v[2:3], v[132:133], v[170:171], v[2:3] op_sel:[0,1,0]
	v_pk_fma_f32 v[4:5], v[134:135], v[170:171], v[4:5] op_sel:[0,1,0]
	s_waitcnt vmcnt(6)
	v_pk_fma_f32 v[6:7], v[136:137], v[172:173], v[6:7] op_sel_hi:[1,0,1]
	v_pk_fma_f32 v[8:9], v[138:139], v[172:173], v[8:9] op_sel_hi:[1,0,1]
	v_pk_fma_f32 v[2:3], v[140:141], v[172:173], v[2:3] op_sel_hi:[1,0,1]
	v_pk_fma_f32 v[4:5], v[142:143], v[172:173], v[4:5] op_sel_hi:[1,0,1]
	s_waitcnt vmcnt(4)
	v_pk_fma_f32 v[6:7], v[144:145], v[172:173], v[6:7] op_sel:[0,1,0]
	v_pk_fma_f32 v[8:9], v[146:147], v[172:173], v[8:9] op_sel:[0,1,0]
	v_pk_fma_f32 v[2:3], v[148:149], v[172:173], v[2:3] op_sel:[0,1,0]
	v_pk_fma_f32 v[4:5], v[150:151], v[172:173], v[4:5] op_sel:[0,1,0]
	s_waitcnt vmcnt(2)
	v_pk_fma_f32 v[6:7], v[152:153], v[174:175], v[6:7] op_sel_hi:[1,0,1]
	v_pk_fma_f32 v[8:9], v[154:155], v[174:175], v[8:9] op_sel_hi:[1,0,1]
	v_pk_fma_f32 v[2:3], v[156:157], v[174:175], v[2:3] op_sel_hi:[1,0,1]
	v_pk_fma_f32 v[4:5], v[158:159], v[174:175], v[4:5] op_sel_hi:[1,0,1]
	s_waitcnt vmcnt(0)
	v_pk_fma_f32 v[6:7], v[160:161], v[174:175], v[6:7] op_sel:[0,1,0]
	v_pk_fma_f32 v[8:9], v[162:163], v[174:175], v[8:9] op_sel:[0,1,0]
	v_pk_fma_f32 v[2:3], v[164:165], v[174:175], v[2:3] op_sel:[0,1,0]
	v_pk_fma_f32 v[4:5], v[166:167], v[174:175], v[4:5] op_sel:[0,1,0]
	s_cmpk_eq_i32 s15, 0x100
	s_cbranch_scc0 .LBB0_35
	s_add_i32 s40, s28, 1
	s_mov_b64 s[42:43], 0x4000
	v_add3_u32 v22, s13, v15, v0
	s_cmp_eq_u32 s28, s12
	v_lshl_add_u64 v[20:21], v[20:21], 0, s[42:43]
	ds_write2_b32 v22, v6, v7 offset1:1
	ds_write2_b32 v22, v2, v3 offset0:4 offset1:5
	ds_write2_b32 v22, v8, v9 offset0:2 offset1:3
	ds_write2_b32 v22, v4, v5 offset0:6 offset1:7
	s_waitcnt lgkmcnt(0)
	s_barrier
	s_cbranch_scc1 .LBB0_38
	s_mov_b32 s15, s13
	s_mov_b32 s13, s14
	s_mov_b32 s28, s40
	s_branch .LBB0_34

; __device__ __forceinline__ float bflo(unsigned u) { return __uint_as_float(u << 16); }
; __device__ void phase_scan(int c, const bf16_t* PROJ, const float* k_k, const bf16_t* Wd, const bf16_t* Bd, const float* k_a, bf16_t* Y, bf16_t* Q, float* FS, float* sm) {
;     ...
;         const bool roleP = (ub == 1), ldr = (ub == 1);
;         const int base = (c == 0) ? (u >> 2) : u, j = (c == 0) ? (u & 3) : 0; const bool hasP = j > 0; const int g0 = 2048 * j;
;         const int dir = base & 1, h = (base >> 1) & 7, seq = base >> 4;
;         const size_t hc = (size_t)h * 64 + k4;
;         const bool act = !roleP || hasP;
;         f32x2 X[8];
; #pragma unroll
;         for (int jj = 0; jj < 8; ++jj) { const int rw = 16 * wq + 2 * vp + (jj >> 2), kx = 8 * q + 2 * (jj & 3);
;             X[jj].x = (roleP && kx == rw) ? 1.f : 0.f; X[jj].y = (roleP && kx + 1 == rw) ? 1.f : 0.f; }
;         float* obw = roleP ? qbw : ybw; bf16_t* gout = roleP ? Q : Y;
;         f32x4 pw = (f32x4){0.f, 0.f, 0.f, 0.f}; uint2 pkk = make_uint2(0, 0), pb = pkk, pkd = pkk, pr = pkk, pv = pkk;
;         const f32x4 ka4 = *(const f32x4*)(k_a + hc), kk4 = *(const f32x4*)(k_k + hc);
;         auto issue = [&](int ci) {
;             const int g = g0 + ci * 16 + ild; const int t = dir ? (L - 1 - g) : g;
;             const size_t row = (size_t)seq * L + t;
;             { const uint2 wq2 = *(const uint2*)(Wd + ((size_t)dir * TCH + row) * 512 + hc); pw = (f32x4){bflo(wq2.x), bfhi(wq2.x), bflo(wq2.y), bfhi(wq2.y)}; }
;             pb = *(const uint2*)(Bd + ((size_t)dir * TCH + row) * 512 + hc);
;             pkd = *(const uint2*)(PROJ + row * LDP + C_K + hc);
;             pr = *(const uint2*)(PROJ + row * LDP + C_R + hc);
;             pv = *(const uint2*)(PROJ + row * LDP + C_V + hc);
;         };
;         auto stash = [&](int buf) {
;             float* o = opb + buf * 6144 + ild * 64 + k4;
;             const float ap[4] = {bflo(pb.x), bfhi(pb.x), bflo(pb.y), bfhi(pb.y)}, kv[4] = {bflo(pkd.x), bfhi(pkd.x), bflo(pkd.y), bfhi(pkd.y)};
;             float kkv[4]; float ss = 0.f;
; #pragma unroll
;             for (int e = 0; e < 4; ++e) { kkv[e] = kv[e] * kk4[e]; ss += kkv[e] * kkv[e]; }
;             ss = sum16(ss); const float rn = 1.0f / fmaxf(sqrtf(ss), 1e-12f);
; #pragma unroll
;             for (int e = 0; e < 4; ++e) kkv[e] *= rn;
;             f32x4 wv, bv, kdv;
; #pragma unroll
.LBB0_66:
	s_ashr_i32 s38, s19, 2
	s_and_b64 s[10:11], s[24:25], exec
	s_cselect_b32 s12, s38, s19
	s_and_b32 s39, s19, 3
	s_and_b64 s[10:11], s[24:25], exec
	s_cselect_b32 s43, s39, 0
	s_lshl_b32 s10, s12, 5
	s_and_b32 s41, s10, 0x1c0
	v_or_b32_e32 v0, s41, v65
	s_waitcnt vmcnt(0)
	v_lshlrev_b32_e32 v6, 2, v0
	global_load_dwordx4 v[2:5], v6, s[52:53]
	s_nop 0
	global_load_dwordx4 v[6:9], v6, s[26:27]
	s_and_b32 s42, s12, 1
	s_ashr_i32 s12, s12, 4
	s_barrier
	s_and_saveexec_b64 s[44:45], s[6:7]
	s_xor_b64 s[54:55], exec, s[44:45]
	s_ashr_i32 s13, s12, 31
	s_lshl_b64 s[10:11], s[12:13], s31
	s_lshl_b32 s28, s42, 25
	s_or_saveexec_b64 s[54:55], s[54:55]
	s_lshl_b32 s44, s43, 11
	v_mov_b32_e32 v52, 0
	v_mov_b64_e32 v[10:11], s[28:29]
	v_mov_b64_e32 v[54:55], s[10:11]
	v_lshlrev_b32_e32 v0, 1, v0
	v_mov_b32_e32 v53, 0
	v_mov_b32_e32 v50, 0
	v_mov_b32_e32 v51, 0
	v_mov_b32_e32 v48, 0
	v_mov_b32_e32 v49, 0
	v_mov_b32_e32 v46, 0
	v_mov_b32_e32 v47, 0
	v_mov_b32_e32 v76, 0
	v_mov_b32_e32 v77, 0
	v_mov_b32_e32 v78, 0
	v_mov_b32_e32 v79, 0
	s_xor_b64 exec, exec, s[54:55]
	s_cbranch_execz .LBB0_70
	v_or_b32_e32 v52, s44, v64
	s_cmp_eq_u32 s42, 0
	s_cselect_b64 s[10:11], -1, 0
	v_xad_u32 v10, v52, -1, s2
	v_cndmask_b32_e64 v10, v10, v52, s[10:11]
	s_ashr_i32 s13, s12, 31
	s_lshl_b64 s[56:57], s[12:13], s31
	v_ashrrev_i32_e32 v11, 31, v10
	s_lshl_b32 s28, s42, 25
	v_lshl_add_u64 v[10:11], s[56:57], 0, v[10:11]
	s_add_u32 s58, s34, s28
	s_addc_u32 s59, s35, 0
	v_lshlrev_b64 v[12:13], 10, v[10:11]
	v_lshl_add_u64 v[14:15], s[58:59], 0, v[12:13]
	v_lshl_add_u64 v[14:15], v[14:15], 0, v[0:1]
	global_load_dwordx2 v[14:15], v[14:15], off
	s_add_u32 s60, s50, s28
	s_addc_u32 s61, s51, 0
	v_lshl_add_u64 v[12:13], s[60:61], 0, v[12:13]
	v_lshl_add_u64 v[12:13], v[12:13], 0, v[0:1]
	global_load_dwordx2 v[12:13], v[12:13], off
	v_mov_b64_e32 v[18:19], s[0:1]
	s_waitcnt vmcnt(1)
	v_lshlrev_b32_e32 v24, 16, v14
	v_and_b32_e32 v25, 0xffff0000, v14
	v_lshlrev_b32_e32 v48, 16, v15
	v_and_b32_e32 v49, 0xffff0000, v15
	v_mad_u64_u32 v[14:15], s[12:13], v10, s47, v[18:19]
	v_mad_i32_i24 v15, v11, s47, v15
	v_lshl_add_u64 v[10:11], v[14:15], 0, v[0:1]
	v_add_co_u32_e32 v14, vcc, s3, v10
	s_waitcnt vmcnt(0)
	v_lshlrev_b32_e32 v53, 16, v13
	v_addc_co_u32_e32 v15, vcc, 0, v11, vcc
	global_load_dwordx2 v[16:17], v[14:15], off
	global_load_dwordx2 v[22:23], v[10:11], off offset:3072
	global_load_dwordx2 v[20:21], v[14:15], off offset:1024
	v_mul_f32_e64 v15, |v24|, s68
	v_exp_f32_e32 v15, v15
	v_max_f32_e64 v10, -v24, -v24
	v_max_f32_e32 v10, 0, v10
	v_lshlrev_b32_e32 v11, 16, v12
	v_add_f32_e32 v15, 1.0, v15
	v_cmp_gt_f32_e32 vcc, s67, v15
	v_mul_f32_e32 v11, 0xbfb8aa3b, v11
	v_exp_f32_e32 v11, v11
	v_cndmask_b32_e64 v24, 0, 32, vcc
	v_ldexp_f32 v15, v15, v24
	v_log_f32_e32 v15, v15
	v_add_f32_e32 v11, 1.0, v11
	v_and_b32_e32 v14, 0xffff0000, v12
	v_mul_f32_e32 v14, 0xbfb8aa3b, v14
	v_mul_f32_e32 v24, 0x3f317217, v15
	v_fma_f32 v24, v15, s69, -v24
	v_fmac_f32_e32 v24, 0x3377d1cf, v15
	v_fmac_f32_e32 v24, 0x3f317217, v15
	v_cmp_lt_f32_e64 s[12:13], |v15|, s70
	v_exp_f32_e32 v14, v14
	v_and_b32_e32 v54, 0xffff0000, v13
	v_cndmask_b32_e64 v15, v15, v24, s[12:13]
	v_cndmask_b32_e32 v24, 0, v188, vcc
	v_sub_f32_e32 v15, v15, v24
	v_add_f32_e32 v10, v10, v15
	v_mul_f32_e64 v15, |v25|, s68
	v_exp_f32_e32 v15, v15
	v_rcp_f32_e32 v24, v11
	v_max_f32_e64 v11, -v25, -v25
	v_add_f32_e32 v14, 1.0, v14
	v_add_f32_e32 v15, 1.0, v15
	v_cmp_gt_f32_e32 vcc, s67, v15
	v_max_f32_e32 v11, 0, v11
	v_sub_f32_e32 v10, -0.5, v10
	v_cndmask_b32_e64 v25, 0, 32, vcc
	v_ldexp_f32 v15, v15, v25
	v_log_f32_e32 v15, v15
	v_mul_f32_e32 v10, 0x3fb8aa3b, v10
	v_exp_f32_e32 v10, v10
	v_mul_f32_e32 v25, 0x3f317217, v15
	v_fma_f32 v25, v15, s69, -v25
	v_fmac_f32_e32 v25, 0x3377d1cf, v15
	v_fmac_f32_e32 v25, 0x3f317217, v15
	v_cmp_lt_f32_e64 s[12:13], |v15|, s70
	v_mul_f32_e32 v10, 0xbfb8aa3b, v10
	v_exp_f32_e32 v10, v10
	v_cndmask_b32_e64 v15, v15, v25, s[12:13]
	v_cndmask_b32_e32 v25, 0, v188, vcc
	v_sub_f32_e32 v15, v15, v25
	v_rcp_f32_e32 v25, v14
	v_add_f32_e32 v11, v11, v15
	v_sub_f32_e32 v11, -0.5, v11
	v_mul_f32_e32 v11, 0x3fb8aa3b, v11
	v_pk_add_f32 v[14:15], v[24:25], -1.0 op_sel_hi:[1,0]
	v_exp_f32_e32 v11, v11
	v_pk_fma_f32 v[14:15], v[2:3], v[14:15], 1.0 op_sel_hi:[1,1,0]
	v_mul_f32_e32 v11, 0xbfb8aa3b, v11
	v_exp_f32_e32 v11, v11
	s_waitcnt vmcnt(2)
; __device__ __forceinline__ float bflo(unsigned u) { return __uint_as_float(u << 16); }
; __device__ __forceinline__ float bfhi(unsigned u) { return __uint_as_float(u & 0xffff0000u); }
; __device__ __forceinline__ float sigmoidf_(float x) { return __builtin_amdgcn_rcpf(1.0f + __expf(-x)); }
; __device__ __forceinline__ float sum16(float x) { x += dpp_xor1(x); x += dpp_xor2(x); x += dpp_hmirror(x); x += dpp_rmirror(x); return x; }
; __device__ void phase_scan(int c, const bf16_t* PROJ, const float* k_k, const bf16_t* Wd, const bf16_t* Bd, const float* k_a, bf16_t* Y, bf16_t* Q, float* FS, float* sm) {
;     ...
;         auto stash = [&](int buf) {
;             float* o = opb + buf * 6144 + ild * 64 + k4;
;             const float ap[4] = {bflo(pb.x), bfhi(pb.x), bflo(pb.y), bfhi(pb.y)}, kv[4] = {bflo(pkd.x), bfhi(pkd.x), bflo(pkd.y), bfhi(pkd.y)};
;             float kkv[4]; float ss = 0.f;
; #pragma unroll
;             for (int e = 0; e < 4; ++e) { kkv[e] = kv[e] * kk4[e]; ss += kkv[e] * kkv[e]; }
;             ss = sum16(ss); const float rn = 1.0f / fmaxf(sqrtf(ss), 1e-12f);
; #pragma unroll
;             for (int e = 0; e < 4; ++e) kkv[e] *= rn;
;             f32x4 wv, bv, kdv;
; #pragma unroll
;             for (int e = 0; e < 4; ++e) { const float zz = -pw[e]; const float sp = fmaxf(zz, 0.f) + __logf(1.0f + __expf(-fabsf(zz)));
;                 wv[e] = __expf(-__expf(-sp - 0.5f)); const float a = sigmoidf_(ap[e]); bv[e] = kkv[e] * a; kdv[e] = kv[e] * (1.0f + (a - 1.0f) * ka4[e]); }
;             *(f32x4*)(o) = wv;
;             *(f32x4*)(o + 1024) = (f32x4){kkv[0], kkv[1], kkv[2], kkv[3]};
;             *(f32x4*)(o + 2048) = bv;
;             *(f32x4*)(o + 3072) = kdv;
;             *(f32x4*)(o + 4096) = (f32x4){bflo(pr.x), bfhi(pr.x), bflo(pr.y), bfhi(pr.y)};
;             *(f32x4*)(o + 5120) = (f32x4){bflo(pv.x), bfhi(pv.x), bflo(pv.y), bfhi(pv.y)};
;         };
;         __syncthreads();
;         if (ldr) { issue(0); stash(0); issue(1); }
	v_lshlrev_b32_e32 v12, 16, v16
	v_and_b32_e32 v13, 0xffff0000, v16
	v_pk_mul_f32 v[46:47], v[6:7], v[12:13]
	v_pk_mul_f32 v[14:15], v[14:15], v[12:13]
	v_mul_f32_e64 v13, |v48|, s68
	v_exp_f32_e32 v13, v13
	v_max_f32_e64 v12, -v48, -v48
	v_max_f32_e32 v12, 0, v12
	v_lshlrev_b32_e32 v16, 16, v17
	v_add_f32_e32 v13, 1.0, v13
	v_cmp_gt_f32_e32 vcc, s67, v13
	v_and_b32_e32 v17, 0xffff0000, v17
	v_pk_mul_f32 v[50:51], v[46:47], v[46:47]
	v_cndmask_b32_e64 v48, 0, 32, vcc
	v_ldexp_f32 v13, v13, v48
	v_log_f32_e32 v13, v13
	v_pk_mul_f32 v[56:57], v[8:9], v[16:17]
	v_add_f32_e32 v50, v50, v51
	v_mul_f32_e32 v48, 0x3f317217, v13
	v_fma_f32 v48, v13, s69, -v48
	v_fmac_f32_e32 v48, 0x3377d1cf, v13
	v_fmac_f32_e32 v48, 0x3f317217, v13
	v_cmp_lt_f32_e64 s[12:13], |v13|, s70
	s_nop 1
	v_cndmask_b32_e64 v13, v13, v48, s[12:13]
	v_cndmask_b32_e32 v48, 0, v188, vcc
	v_sub_f32_e32 v13, v13, v48
	v_add_f32_e32 v12, v12, v13
	v_mul_f32_e32 v13, 0xbfb8aa3b, v53
	v_exp_f32_e32 v13, v13
	v_sub_f32_e32 v12, -0.5, v12
	v_mul_f32_e32 v12, 0x3fb8aa3b, v12
	v_exp_f32_e32 v12, v12
	v_add_f32_e32 v13, 1.0, v13
	v_rcp_f32_e32 v48, v13
	v_mul_f32_e32 v12, 0xbfb8aa3b, v12
	v_exp_f32_e32 v12, v12
	v_add_f32_e32 v13, -1.0, v48
	v_fma_f32 v53, v4, v13, 1.0
	v_max_f32_e64 v13, -v49, -v49
	v_mul_f32_e64 v49, |v49|, s68
	v_exp_f32_e32 v49, v49
	v_max_f32_e32 v13, 0, v13
	v_mul_f32_e32 v16, v53, v16
	v_add_f32_e32 v49, 1.0, v49
	v_cmp_gt_f32_e32 vcc, s67, v49
	s_nop 1
	v_cndmask_b32_e64 v55, 0, 32, vcc
	v_ldexp_f32 v49, v49, v55
	v_log_f32_e32 v49, v49
	s_nop 0
	v_mul_f32_e32 v55, 0x3f317217, v49
	v_fma_f32 v55, v49, s69, -v55
	v_fmac_f32_e32 v55, 0x3377d1cf, v49
	v_fmac_f32_e32 v55, 0x3f317217, v49
	v_cmp_lt_f32_e64 s[12:13], |v49|, s70
	s_nop 1
	v_cndmask_b32_e64 v49, v49, v55, s[12:13]
	v_cndmask_b32_e32 v55, 0, v188, vcc
	v_sub_f32_e32 v49, v49, v55
	v_add_f32_e32 v13, v13, v49
	v_mul_f32_e32 v49, 0xbfb8aa3b, v54
	v_pk_mul_f32 v[54:55], v[56:57], v[56:57]
	v_sub_f32_e32 v13, -0.5, v13
	v_add_f32_e32 v50, v50, v54
	v_add_f32_e32 v50, v55, v50
	v_exp_f32_e32 v49, v49
	v_mul_f32_e32 v13, 0x3fb8aa3b, v13
	v_add_f32_dpp v50, v50, v50 quad_perm:[1,0,3,2] row_mask:0xf bank_mask:0xf bound_ctrl:1
	v_exp_f32_e32 v13, v13
	v_add_f32_e32 v49, 1.0, v49
	v_add_f32_dpp v50, v50, v50 quad_perm:[2,3,0,1] row_mask:0xf bank_mask:0xf bound_ctrl:1
	v_rcp_f32_e32 v49, v49
	v_mul_f32_e32 v13, 0xbfb8aa3b, v13
	v_add_f32_dpp v50, v50, v50 row_half_mirror row_mask:0xf bank_mask:0xf bound_ctrl:1
	v_exp_f32_e32 v13, v13
	s_nop 0
	v_add_f32_dpp v50, v50, v50 row_mirror row_mask:0xf bank_mask:0xf bound_ctrl:1
	v_cmp_gt_f32_e32 vcc, s72, v50
	v_mul_f32_e32 v51, 0x4f800000, v50
	s_nop 0
	v_cndmask_b32_e32 v50, v50, v51, vcc
	v_sqrt_f32_e32 v51, v50
	s_nop 0
	v_add_u32_e32 v54, -1, v51
	v_fma_f32 v55, -v54, v51, v50
	v_cmp_ge_f32_e64 s[12:13], 0, v55
	v_add_u32_e32 v55, 1, v51
	s_nop 0
	v_cndmask_b32_e64 v54, v51, v54, s[12:13]
	v_fma_f32 v51, -v55, v51, v50
	v_cmp_lt_f32_e64 s[12:13], 0, v51
	s_nop 1
	v_cndmask_b32_e64 v51, v54, v55, s[12:13]
	v_mul_f32_e32 v54, 0x37800000, v51
	v_cndmask_b32_e32 v51, v51, v54, vcc
	v_cmp_class_f32_e32 vcc, v50, v182
	s_nop 1
	v_cndmask_b32_e32 v50, v51, v50, vcc
	v_max_f32_e32 v50, 0x2b8cbccc, v50
	v_div_scale_f32 v51, s[12:13], v50, v50, 1.0
	v_rcp_f32_e32 v54, v51
	s_nop 0
	v_fma_f32 v55, -v51, v54, 1.0
	v_fmac_f32_e32 v54, v55, v54
	v_div_scale_f32 v55, vcc, 1.0, v50, 1.0
	v_mul_f32_e32 v58, v55, v54
	v_fma_f32 v59, -v51, v58, v55
	v_fmac_f32_e32 v58, v59, v54
	v_fma_f32 v51, -v51, v58, v55
	v_div_fmas_f32 v51, v51, v54, v58
	v_div_fixup_f32 v50, v51, v50, 1.0
	v_pk_mul_f32 v[54:55], v[46:47], v[50:51] op_sel_hi:[1,0]
	v_pk_mul_f32 v[56:57], v[56:57], v[50:51] op_sel_hi:[1,0]
	v_pk_mul_f32 v[58:59], v[24:25], v[54:55]
	v_add_f32_e32 v24, -1.0, v49
	v_fma_f32 v24, v5, v24, 1.0
	v_pk_mul_f32 v[60:61], v[48:49], v[56:57]
	v_mul_f32_e32 v17, v24, v17
	ds_write_b128 v69, v[10:13]
	ds_write_b128 v69, v[54:57] offset:4096
	ds_write_b128 v69, v[58:61] offset:8192
	ds_write_b128 v69, v[14:17] offset:12288
	s_waitcnt vmcnt(1)
	v_lshlrev_b32_e32 v10, 16, v22
	v_and_b32_e32 v11, 0xffff0000, v22
	v_lshlrev_b32_e32 v12, 16, v23
	v_and_b32_e32 v13, 0xffff0000, v23
	ds_write_b128 v69, v[10:13] offset:16384
	s_waitcnt vmcnt(0)
	v_lshlrev_b32_e32 v10, 16, v20
	v_and_b32_e32 v11, 0xffff0000, v20
	v_lshlrev_b32_e32 v12, 16, v21
	v_and_b32_e32 v13, 0xffff0000, v21
	ds_write_b128 v69, v[10:13] offset:20480
	v_bitop3_b32 v11, s44, v189, v64 bitop3:0x36
	v_or_b32_e32 v10, 16, v52
	v_add_u32_e32 v11, s2, v11
	v_cndmask_b32_e64 v10, v11, v10, s[10:11]
	v_ashrrev_i32_e32 v11, 31, v10
	v_lshl_add_u64 v[10:11], s[56:57], 0, v[10:11]
	v_lshlrev_b64 v[12:13], 10, v[10:11]
	v_lshl_add_u64 v[14:15], s[58:59], 0, v[12:13]
	v_lshl_add_u64 v[12:13], s[60:61], 0, v[12:13]
	v_lshl_add_u64 v[14:15], v[14:15], 0, v[0:1]
	v_lshl_add_u64 v[12:13], v[12:13], 0, v[0:1]
	global_load_dwordx2 v[14:15], v[14:15], off
	v_mov_b64_e32 v[54:55], s[56:57]
	global_load_dwordx2 v[46:47], v[12:13], off
	v_mad_u64_u32 v[12:13], s[10:11], v10, s47, v[18:19]
	v_mad_i32_i24 v13, v11, s47, v13
	v_lshl_add_u64 v[10:11], v[12:13], 0, v[0:1]
	v_add_co_u32_e32 v12, vcc, 0x1000, v10
	s_waitcnt vmcnt(1)
	v_lshlrev_b32_e32 v76, 16, v14
	v_addc_co_u32_e32 v13, vcc, 0, v11, vcc
	global_load_dwordx2 v[48:49], v[12:13], off
	global_load_dwordx2 v[50:51], v[10:11], off offset:3072
	global_load_dwordx2 v[52:53], v[12:13], off offset:1024
	v_and_b32_e32 v77, 0xffff0000, v14
	v_lshlrev_b32_e32 v78, 16, v15
	v_and_b32_e32 v79, 0xffff0000, v15
	v_mov_b32_e32 v232, v14
	v_mov_b32_e32 v233, v15
	v_mov_b64_e32 v[10:11], s[28:29]

; __device__ __forceinline__ float bflo(unsigned u) { return __uint_as_float(u << 16); }
; __device__ __forceinline__ float bfhi(unsigned u) { return __uint_as_float(u & 0xffff0000u); }
; __device__ __forceinline__ float sigmoidf_(float x) { return __builtin_amdgcn_rcpf(1.0f + __expf(-x)); }
; __device__ __forceinline__ float sum16(float x) { x += dpp_xor1(x); x += dpp_xor2(x); x += dpp_hmirror(x); x += dpp_rmirror(x); return x; }
; __device__ void phase_scan(int c, const bf16_t* PROJ, const float* k_k, const bf16_t* Wd, const bf16_t* Bd, const float* k_a, bf16_t* Y, bf16_t* Q, float* FS, float* sm) {
;     ...
;         auto stash = [&](int buf) {
;             float* o = opb + buf * 6144 + ild * 64 + k4;
;             const float ap[4] = {bflo(pb.x), bfhi(pb.x), bflo(pb.y), bfhi(pb.y)}, kv[4] = {bflo(pkd.x), bfhi(pkd.x), bflo(pkd.y), bfhi(pkd.y)};
;             float kkv[4]; float ss = 0.f;
; #pragma unroll
;             for (int e = 0; e < 4; ++e) { kkv[e] = kv[e] * kk4[e]; ss += kkv[e] * kkv[e]; }
;             ss = sum16(ss); const float rn = 1.0f / fmaxf(sqrtf(ss), 1e-12f);
; #pragma unroll
;             for (int e = 0; e < 4; ++e) kkv[e] *= rn;
;             f32x4 wv, bv, kdv;
; #pragma unroll
;             for (int e = 0; e < 4; ++e) { const float zz = -pw[e]; const float sp = fmaxf(zz, 0.f) + __logf(1.0f + __expf(-fabsf(zz)));
;                 wv[e] = __expf(-__expf(-sp - 0.5f)); const float a = sigmoidf_(ap[e]); bv[e] = kkv[e] * a; kdv[e] = kv[e] * (1.0f + (a - 1.0f) * ka4[e]); }
;             *(f32x4*)(o) = wv;
;             *(f32x4*)(o + 1024) = (f32x4){kkv[0], kkv[1], kkv[2], kkv[3]};
;             *(f32x4*)(o + 2048) = bv;
;             *(f32x4*)(o + 3072) = kdv;
;             *(f32x4*)(o + 4096) = (f32x4){bflo(pr.x), bfhi(pr.x), bflo(pr.y), bfhi(pr.y)};
;             *(f32x4*)(o + 5120) = (f32x4){bflo(pv.x), bfhi(pv.x), bflo(pv.y), bfhi(pv.y)};
;         };
;     ...
;             if (ldr && ci + 1 < nch) { stash((ci + 1) & 1); if (ci + 2 < nch) issue(ci + 2); }
.LBB0_72:
	s_cmpk_lg_i32 s40, 0x7f0
	s_cselect_b64 s[12:13], -1, 0
	s_and_b64 s[12:13], s[8:9], s[12:13]
	s_and_saveexec_b64 s[56:57], s[12:13]
	s_cbranch_execz .LBB0_75
	s_waitcnt vmcnt(4)
	v_lshlrev_b32_e32 v76, 16, v232
	v_and_b32_e32 v77, 0xffff0000, v232
	v_lshlrev_b32_e32 v78, 16, v233
	v_and_b32_e32 v79, 0xffff0000, v233
	v_mul_f32_e64 v88, |v76|, s68
	v_exp_f32_e32 v88, v88
	s_waitcnt vmcnt(3)
	v_lshlrev_b32_e32 v84, 16, v46
	v_mul_f32_e32 v84, 0xbfb8aa3b, v84
	v_and_b32_e32 v85, 0xffff0000, v46
	v_add_f32_e32 v88, 1.0, v88
	v_cmp_gt_f32_e32 vcc, s67, v88
	v_mul_f32_e32 v85, 0xbfb8aa3b, v85
	v_lshlrev_b32_e32 v86, 16, v47
	v_cndmask_b32_e64 v89, 0, 32, vcc
	v_ldexp_f32 v88, v88, v89
	v_log_f32_e32 v88, v88
	v_max_f32_e64 v89, -v76, -v76
	v_max_f32_e32 v89, 0, v89
	v_mul_f32_e32 v86, 0xbfb8aa3b, v86
	v_mul_f32_e32 v90, 0x3f317217, v88
	v_fma_f32 v90, v88, s69, -v90
	v_fmac_f32_e32 v90, 0x3377d1cf, v88
	v_fmac_f32_e32 v90, 0x3f317217, v88
	v_cmp_lt_f32_e64 s[12:13], |v88|, s70
	s_waitcnt vmcnt(2)
	v_lshlrev_b32_e32 v96, 16, v48
	v_and_b32_e32 v97, 0xffff0000, v48
	v_cndmask_b32_e64 v88, v88, v90, s[12:13]
	v_cndmask_b32_e32 v90, 0, v188, vcc
	v_sub_f32_e32 v88, v88, v90
	v_add_f32_e32 v88, v89, v88
	v_sub_f32_e32 v88, -0.5, v88
	v_mul_f32_e32 v88, 0x3fb8aa3b, v88
	v_exp_f32_e32 v89, v84
	v_mul_f32_e64 v84, |v77|, s68
	v_exp_f32_e32 v88, v88
	v_exp_f32_e32 v90, v84
	v_lshlrev_b32_e32 v98, 16, v49
	v_and_b32_e32 v99, 0xffff0000, v49
	v_mul_f32_e32 v84, 0xbfb8aa3b, v88
	v_add_f32_e32 v88, 1.0, v89
	v_add_f32_e32 v89, 1.0, v90
	v_cmp_gt_f32_e32 vcc, s67, v89
	v_rcp_f32_e32 v100, v88
	v_max_f32_e64 v88, -v77, -v77
	v_cndmask_b32_e64 v90, 0, 32, vcc
	v_ldexp_f32 v89, v89, v90
	v_log_f32_e32 v89, v89
	v_max_f32_e32 v88, 0, v88
	s_waitcnt vmcnt(0)
	v_pk_mul_f32 v[92:93], v[8:9], v[98:99]
	v_and_b32_e32 v87, 0xffff0000, v47
	v_mul_f32_e32 v90, 0x3f317217, v89
	v_fma_f32 v90, v89, s69, -v90
	v_fmac_f32_e32 v90, 0x3377d1cf, v89
	v_fmac_f32_e32 v90, 0x3f317217, v89
	v_cmp_lt_f32_e64 s[12:13], |v89|, s70
	v_pk_mul_f32 v[94:95], v[92:93], v[92:93]
	v_mul_f32_e32 v87, 0xbfb8aa3b, v87
	v_cndmask_b32_e64 v89, v89, v90, s[12:13]
	v_cndmask_b32_e32 v90, 0, v188, vcc
	v_sub_f32_e32 v89, v89, v90
	v_add_f32_e32 v88, v88, v89
	v_sub_f32_e32 v88, -0.5, v88
	v_mul_f32_e32 v88, 0x3fb8aa3b, v88
	v_exp_f32_e32 v89, v85
	v_mul_f32_e64 v85, |v78|, s68
	v_exp_f32_e32 v88, v88
	v_exp_f32_e32 v90, v85
	v_exp_f32_e32 v84, v84
	s_andn2_b32 s41, 1, s28
	v_mul_f32_e32 v85, 0xbfb8aa3b, v88
	v_add_f32_e32 v88, 1.0, v89
	v_add_f32_e32 v89, 1.0, v90
	v_cmp_gt_f32_e32 vcc, s67, v89
	v_rcp_f32_e32 v101, v88
	v_max_f32_e64 v88, -v78, -v78
	v_cndmask_b32_e64 v90, 0, 32, vcc
	v_ldexp_f32 v89, v89, v90
	v_log_f32_e32 v89, v89
	v_max_f32_e32 v88, 0, v88
	v_exp_f32_e32 v85, v85
	s_mulk_i32 s41, 0x6000
	v_mul_f32_e32 v90, 0x3f317217, v89
	v_fma_f32 v90, v89, s69, -v90
	v_fmac_f32_e32 v90, 0x3377d1cf, v89
	v_fmac_f32_e32 v90, 0x3f317217, v89
	v_cmp_lt_f32_e64 s[12:13], |v89|, s70
	s_cmpk_gt_u32 s28, 0x7d
	s_nop 0
	v_cndmask_b32_e64 v89, v89, v90, s[12:13]
	v_cndmask_b32_e32 v90, 0, v188, vcc
	v_sub_f32_e32 v89, v89, v90
	v_add_f32_e32 v88, v88, v89
	v_sub_f32_e32 v88, -0.5, v88
	v_mul_f32_e32 v88, 0x3fb8aa3b, v88
	v_exp_f32_e32 v89, v86
	v_mul_f32_e64 v86, |v79|, s68
	v_exp_f32_e32 v88, v88
	v_exp_f32_e32 v90, v86
	v_mul_f32_e32 v86, 0xbfb8aa3b, v88
	v_add_f32_e32 v88, 1.0, v89
	v_add_f32_e32 v89, 1.0, v90
	v_cmp_gt_f32_e32 vcc, s67, v89
	v_rcp_f32_e32 v102, v88
	v_max_f32_e64 v88, -v79, -v79
	v_cndmask_b32_e64 v90, 0, 32, vcc
	v_ldexp_f32 v89, v89, v90
	v_log_f32_e32 v89, v89
	v_max_f32_e32 v88, 0, v88
	v_exp_f32_e32 v86, v86
	v_mul_f32_e32 v90, 0x3f317217, v89
	v_fma_f32 v90, v89, s69, -v90
	v_fmac_f32_e32 v90, 0x3377d1cf, v89
	v_fmac_f32_e32 v90, 0x3f317217, v89
	v_cmp_lt_f32_e64 s[12:13], |v89|, s70
	s_nop 1
	v_cndmask_b32_e64 v89, v89, v90, s[12:13]
	v_cndmask_b32_e32 v90, 0, v188, vcc
	v_sub_f32_e32 v89, v89, v90
	v_add_f32_e32 v88, v88, v89
	v_sub_f32_e32 v88, -0.5, v88
	v_mul_f32_e32 v88, 0x3fb8aa3b, v88
	v_exp_f32_e32 v103, v88
	v_pk_mul_f32 v[88:89], v[6:7], v[96:97]
	s_nop 0
	v_pk_mul_f32 v[90:91], v[88:89], v[88:89]
	s_nop 0
	v_add_f32_e32 v90, v90, v91
	v_add_f32_e32 v90, v94, v90
	v_add_f32_e32 v90, v95, v90
	v_exp_f32_e32 v95, v87
	v_mul_f32_e32 v94, 0xbfb8aa3b, v103
	v_add_f32_dpp v90, v90, v90 quad_perm:[1,0,3,2] row_mask:0xf bank_mask:0xf bound_ctrl:1
	s_nop 1
	v_add_f32_dpp v90, v90, v90 quad_perm:[2,3,0,1] row_mask:0xf bank_mask:0xf bound_ctrl:1
	s_nop 1
	v_add_f32_dpp v90, v90, v90 row_half_mirror row_mask:0xf bank_mask:0xf bound_ctrl:1
	s_nop 1
	v_add_f32_dpp v90, v90, v90 row_mirror row_mask:0xf bank_mask:0xf bound_ctrl:1
	v_mul_f32_e32 v91, 0x4f800000, v90
	v_cmp_gt_f32_e32 vcc, s72, v90
	s_nop 1
	v_cndmask_b32_e32 v90, v90, v91, vcc
	v_sqrt_f32_e32 v91, v90
	s_nop 0
	v_add_u32_e32 v87, -1, v91
	v_fma_f32 v103, -v87, v91, v90
	v_cmp_ge_f32_e64 s[12:13], 0, v103
	v_add_u32_e32 v103, 1, v91
	s_nop 0
	v_cndmask_b32_e64 v87, v91, v87, s[12:13]
	v_fma_f32 v91, -v103, v91, v90
	v_cmp_lt_f32_e64 s[12:13], 0, v91
	s_nop 1
	v_cndmask_b32_e64 v87, v87, v103, s[12:13]
	v_mul_f32_e32 v91, 0x37800000, v87
	v_cndmask_b32_e32 v87, v87, v91, vcc
	v_cmp_class_f32_e32 vcc, v90, v182
	s_nop 1
	v_cndmask_b32_e32 v87, v87, v90, vcc
	v_max_f32_e32 v90, 0x2b8cbccc, v87
	v_div_scale_f32 v91, s[12:13], v90, v90, 1.0
	v_rcp_f32_e32 v104, v91
	v_exp_f32_e32 v87, v94
	v_add_f32_e32 v94, 1.0, v95
	v_rcp_f32_e32 v103, v94
	v_fma_f32 v94, -v91, v104, 1.0
	v_fmac_f32_e32 v104, v94, v104
	v_div_scale_f32 v94, vcc, 1.0, v90, 1.0
	v_mul_f32_e32 v95, v94, v104
	v_fma_f32 v105, -v91, v95, v94
	v_fmac_f32_e32 v95, v105, v104
	v_fma_f32 v91, -v91, v95, v94
	v_div_fmas_f32 v91, v91, v104, v95
	v_div_fixup_f32 v90, v91, v90, 1.0
	v_pk_mul_f32 v[88:89], v[88:89], v[90:91] op_sel_hi:[1,0]
	v_pk_mul_f32 v[90:91], v[92:93], v[90:91] op_sel_hi:[1,0]
	v_pk_mul_f32 v[92:93], v[100:101], v[88:89]
	v_pk_add_f32 v[100:101], v[100:101], -1.0 op_sel_hi:[1,0]
	v_pk_mul_f32 v[94:95], v[102:103], v[90:91]
	v_pk_add_f32 v[102:103], v[102:103], -1.0 op_sel_hi:[1,0]
	v_pk_fma_f32 v[100:101], v[2:3], v[100:101], 1.0 op_sel_hi:[1,1,0]
	v_pk_fma_f32 v[102:103], v[4:5], v[102:103], 1.0 op_sel_hi:[1,1,0]
	v_pk_mul_f32 v[96:97], v[100:101], v[96:97]
	v_add_u32_e32 v100, s41, v69
	v_pk_mul_f32 v[98:99], v[102:103], v[98:99]
	ds_write_b128 v100, v[84:87]
	ds_write_b128 v100, v[88:91] offset:4096
	ds_write_b128 v100, v[92:95] offset:8192
	ds_write_b128 v100, v[96:99] offset:12288
	v_lshlrev_b32_e32 v84, 16, v50
	v_and_b32_e32 v85, 0xffff0000, v50
	v_lshlrev_b32_e32 v86, 16, v51
	v_and_b32_e32 v87, 0xffff0000, v51
	ds_write_b128 v100, v[84:87] offset:16384
	v_lshlrev_b32_e32 v84, 16, v52
	v_and_b32_e32 v85, 0xffff0000, v52
	v_lshlrev_b32_e32 v86, 16, v53
	v_and_b32_e32 v87, 0xffff0000, v53
	ds_write_b128 v100, v[84:87] offset:20480
	s_cbranch_scc1 .LBB0_75
; __device__ __forceinline__ float bflo(unsigned u) { return __uint_as_float(u << 16); }
; __device__ __forceinline__ void scan_rows(f32x2 (&X)[8], const ScanOps& o, const f32x4 (&b)[2], const f32x4 (&kd)[2], const f32x4 (&r)[2], const bool use_v, float& yA, float& yB) {
;     f32x2 aA = X[0] * o.kk[0].xy, aB = X[4] * o.kk[0].xy;
;     aA += X[1] * o.kk[0].zw; aB += X[5] * o.kk[0].zw;
;     aA += X[2] * o.kk[1].xy; aB += X[6] * o.kk[1].xy;
;     aA += X[3] * o.kk[1].zw; aB += X[7] * o.kk[1].zw;
;     const float saA = sum8(aA.x + aA.y), saB = sum8(aB.x + aB.y);
;     const f32x2 nA = (f32x2){-saA, -saA}, nB = (f32x2){-saB, -saB}, vA = (f32x2){o.v.x, o.v.x}, vB = (f32x2){o.v.y, o.v.y};
;     f32x2 tA, tB, accA, accB;
;     tA = X[0] * o.w[0].xy; tA += nA * b[0].xy; if (use_v) tA += vA * kd[0].xy; X[0] = tA; accA = tA * r[0].xy;
;     tB = X[4] * o.w[0].xy; tB += nB * b[0].xy; if (use_v) tB += vB * kd[0].xy; X[4] = tB; accB = tB * r[0].xy;
;     tA = X[1] * o.w[0].zw; tA += nA * b[0].zw; if (use_v) tA += vA * kd[0].zw; X[1] = tA; accA += tA * r[0].zw;
;     tB = X[5] * o.w[0].zw; tB += nB * b[0].zw; if (use_v) tB += vB * kd[0].zw; X[5] = tB; accB += tB * r[0].zw;
;     tA = X[2] * o.w[1].xy; tA += nA * b[1].xy; if (use_v) tA += vA * kd[1].xy; X[2] = tA; accA += tA * r[1].xy;
;     tB = X[6] * o.w[1].xy; tB += nB * b[1].xy; if (use_v) tB += vB * kd[1].xy; X[6] = tB; accB += tB * r[1].xy;
;     tA = X[3] * o.w[1].zw; tA += nA * b[1].zw; if (use_v) tA += vA * kd[1].zw; X[3] = tA; accA += tA * r[1].zw;
;     tB = X[7] * o.w[1].zw; tB += nB * b[1].zw; if (use_v) tB += vB * kd[1].zw; X[7] = tB; accB += tB * r[1].zw;
;     yA = sum8(accA.x + accA.y); yB = sum8(accB.x + accB.y);
; __device__ void phase_scan(int c, const bf16_t* PROJ, const float* k_k, const bf16_t* Wd, const bf16_t* Bd, const float* k_a, bf16_t* Y, bf16_t* Q, float* FS, float* sm) {
;     ...
;             const size_t row = (size_t)seq * L + t;
;             { const uint2 wq2 = *(const uint2*)(Wd + ((size_t)dir * TCH + row) * 512 + hc); pw = (f32x4){bflo(wq2.x), bfhi(wq2.x), bflo(wq2.y), bfhi(wq2.y)}; }
;             pb = *(const uint2*)(Bd + ((size_t)dir * TCH + row) * 512 + hc);
;             pkd = *(const uint2*)(PROJ + row * LDP + C_K + hc);
;             pr = *(const uint2*)(PROJ + row * LDP + C_R + hc);
;             pv = *(const uint2*)(PROJ + row * LDP + C_V + hc);
	v_add_u32_e32 v46, s40, v80
	v_cndmask_b32_e64 v46, v81, v46, s[10:11]
	v_ashrrev_i32_e32 v47, 31, v46
	v_lshl_add_u64 v[48:49], v[54:55], 0, v[46:47]
	v_lshlrev_b64 v[46:47], 10, v[48:49]
	v_lshl_add_u64 v[50:51], v[56:57], 0, v[46:47]
	global_load_dwordx2 v[232:233], v[50:51], off
	v_lshl_add_u64 v[46:47], v[58:59], 0, v[46:47]
	global_load_dwordx2 v[46:47], v[46:47], off
	v_mov_b64_e32 v[50:51], s[0:1]
	v_mad_u64_u32 v[50:51], s[12:13], v48, s47, v[50:51]
	v_mov_b32_e32 v48, v51
	v_mad_u64_u32 v[48:49], s[12:13], v49, s47, v[48:49]
	v_mov_b32_e32 v51, v48
	v_lshl_add_u64 v[50:51], v[50:51], 0, v[0:1]
	v_add_co_u32_e32 v52, vcc, 0x1000, v50
	s_nop 1
	v_addc_co_u32_e32 v53, vcc, 0, v51, vcc
	global_load_dwordx2 v[48:49], v[52:53], off
	s_nop 0
	global_load_dwordx2 v[50:51], v[50:51], off offset:3072
	s_nop 0
	global_load_dwordx2 v[52:53], v[52:53], off offset:1024
.LBB0_75:
	s_or_b64 exec, exec, s[56:57]
	s_and_saveexec_b64 s[12:13], s[54:55]
	s_cbranch_execz .LBB0_71
	s_bitcmp1_b32 s28, 0
	s_cselect_b32 s41, 0x6000, 0
	s_add_i32 s41, s41, 0
	v_lshl_add_u32 v84, v68, 2, s41
	v_lshlrev_b32_e32 v85, 2, v66
	v_lshlrev_b32_e32 v86, 2, v67
	v_add3_u32 v85, s41, v85, v86
	v_lshrrev_b32_e32 v228, 6, v180
	v_mul_u32_u24_e32 v228, 0x2400, v228
	v_add_u32_e32 v228, 0xe000, v228
	v_bfe_u32 v229, v180, 2, 4
	v_mul_u32_u24_e32 v229, 0x240, v229
	v_add_u32_e32 v229, v229, v228
	v_and_b32_e32 v230, 3, v180
	v_lshl_add_u32 v229, v230, 4, v229
	v_and_b32_e32 v230, 7, v180
	v_lshl_add_u32 v228, v230, 6, v228
	v_bfe_u32 v230, v180, 3, 3
	v_lshl_add_u32 v228, v230, 3, v228
	s_cmp_lg_u64 s[8:9], 0
	s_cbranch_scc1 .Lscan_p_body
	ds_read_b128 v[86:89], v84 offset:0
	ds_read_b128 v[90:93], v84 offset:16
	ds_read_b128 v[94:97], v84 offset:4096
	ds_read_b128 v[98:101], v84 offset:4112
	ds_read_b128 v[102:105], v84 offset:8192
	ds_read_b128 v[106:109], v84 offset:8208
	ds_read_b128 v[110:113], v84 offset:12288
	ds_read_b128 v[114:117], v84 offset:12304
	ds_read_b128 v[118:121], v84 offset:16384
	ds_read_b128 v[122:125], v84 offset:16400
	ds_read_b64 v[126:127], v85 offset:20480
	s_waitcnt lgkmcnt(0)
	ds_read_b128 v[128:131], v84 offset:256
	ds_read_b128 v[132:135], v84 offset:272
	ds_read_b128 v[136:139], v84 offset:4352
	ds_read_b128 v[140:143], v84 offset:4368
	ds_read_b128 v[144:147], v84 offset:8448
	ds_read_b128 v[148:151], v84 offset:8464
	ds_read_b128 v[152:155], v84 offset:12544
	ds_read_b128 v[156:159], v84 offset:12560
	ds_read_b128 v[160:163], v84 offset:16640
	ds_read_b128 v[164:167], v84 offset:16656
	ds_read_b64 v[168:169], v85 offset:20736
	v_pk_mul_f32 v[212:213], v[22:23], v[94:95]
	v_pk_mul_f32 v[216:217], v[14:15], v[94:95]
	v_pk_mul_f32 v[196:197], v[22:23], v[86:87]
	v_pk_mul_f32 v[204:205], v[14:15], v[86:87]
	v_pk_fma_f32 v[212:213], v[24:25], v[96:97], v[212:213]
	v_pk_fma_f32 v[216:217], v[16:17], v[96:97], v[216:217]
	v_pk_mul_f32 v[198:199], v[24:25], v[88:89]
	v_pk_mul_f32 v[206:207], v[16:17], v[88:89]
	v_pk_fma_f32 v[212:213], v[18:19], v[98:99], v[212:213]
	v_pk_fma_f32 v[216:217], v[10:11], v[98:99], v[216:217]
	v_pk_mul_f32 v[200:201], v[18:19], v[90:91]
	v_pk_mul_f32 v[208:209], v[10:11], v[90:91]
	v_pk_fma_f32 v[212:213], v[20:21], v[100:101], v[212:213]
	v_pk_fma_f32 v[216:217], v[12:13], v[100:101], v[216:217]
	v_pk_mul_f32 v[202:203], v[20:21], v[92:93]
	v_pk_mul_f32 v[210:211], v[12:13], v[92:93]
	v_add_f32_e32 v220, v212, v213
	v_add_f32_e32 v221, v216, v217
	v_pk_fma_f32 v[196:197], v[126:127], v[110:111], v[196:197] op_sel_hi:[0,1,1]
	v_pk_fma_f32 v[204:205], v[126:127], v[110:111], v[204:205] op_sel:[1,0,0] op_sel_hi:[1,1,1]
	v_add_f32_dpp v220, v220, v220 quad_perm:[1,0,3,2] row_mask:0xf bank_mask:0xf bound_ctrl:1
	v_add_f32_dpp v221, v221, v221 quad_perm:[1,0,3,2] row_mask:0xf bank_mask:0xf bound_ctrl:1
	v_pk_fma_f32 v[198:199], v[126:127], v[112:113], v[198:199] op_sel_hi:[0,1,1]
	v_pk_fma_f32 v[206:207], v[126:127], v[112:113], v[206:207] op_sel:[1,0,0] op_sel_hi:[1,1,1]
	v_add_f32_dpp v220, v220, v220 quad_perm:[2,3,0,1] row_mask:0xf bank_mask:0xf bound_ctrl:1
	v_add_f32_dpp v221, v221, v221 quad_perm:[2,3,0,1] row_mask:0xf bank_mask:0xf bound_ctrl:1
	v_pk_fma_f32 v[200:201], v[126:127], v[114:115], v[200:201] op_sel_hi:[0,1,1]
	v_pk_fma_f32 v[208:209], v[126:127], v[114:115], v[208:209] op_sel:[1,0,0] op_sel_hi:[1,1,1]
	v_add_f32_dpp v220, v220, v220 row_half_mirror row_mask:0xf bank_mask:0xf bound_ctrl:1
	v_add_f32_dpp v221, v221, v221 row_half_mirror row_mask:0xf bank_mask:0xf bound_ctrl:1
	v_pk_fma_f32 v[202:203], v[126:127], v[116:117], v[202:203] op_sel_hi:[0,1,1]
	v_pk_fma_f32 v[210:211], v[126:127], v[116:117], v[210:211] op_sel:[1,0,0] op_sel_hi:[1,1,1]
	v_pk_fma_f32 v[22:23], v[220:221], v[102:103], v[196:197] op_sel_hi:[0,1,1] neg_lo:[1,0,0] neg_hi:[1,0,0]
	v_pk_fma_f32 v[14:15], v[220:221], v[102:103], v[204:205] op_sel:[1,0,0] op_sel_hi:[1,1,1] neg_lo:[1,0,0] neg_hi:[1,0,0]
	v_pk_fma_f32 v[24:25], v[220:221], v[104:105], v[198:199] op_sel_hi:[0,1,1] neg_lo:[1,0,0] neg_hi:[1,0,0]
	v_pk_fma_f32 v[16:17], v[220:221], v[104:105], v[206:207] op_sel:[1,0,0] op_sel_hi:[1,1,1] neg_lo:[1,0,0] neg_hi:[1,0,0]
	v_pk_fma_f32 v[18:19], v[220:221], v[106:107], v[200:201] op_sel_hi:[0,1,1] neg_lo:[1,0,0] neg_hi:[1,0,0]
	v_pk_fma_f32 v[10:11], v[220:221], v[106:107], v[208:209] op_sel:[1,0,0] op_sel_hi:[1,1,1] neg_lo:[1,0,0] neg_hi:[1,0,0]
	v_pk_fma_f32 v[20:21], v[220:221], v[108:109], v[202:203] op_sel_hi:[0,1,1] neg_lo:[1,0,0] neg_hi:[1,0,0]
	v_pk_fma_f32 v[12:13], v[220:221], v[108:109], v[210:211] op_sel:[1,0,0] op_sel_hi:[1,1,1] neg_lo:[1,0,0] neg_hi:[1,0,0]
	v_pk_mul_f32 v[222:223], v[22:23], v[118:119]
	v_pk_mul_f32 v[224:225], v[14:15], v[118:119]
	v_pk_fma_f32 v[222:223], v[24:25], v[120:121], v[222:223]
	v_pk_fma_f32 v[224:225], v[16:17], v[120:121], v[224:225]
	v_pk_fma_f32 v[222:223], v[18:19], v[122:123], v[222:223]
	v_pk_fma_f32 v[224:225], v[10:11], v[122:123], v[224:225]
	v_pk_fma_f32 v[222:223], v[20:21], v[124:125], v[222:223]
	v_pk_fma_f32 v[224:225], v[12:13], v[124:125], v[224:225]
	s_waitcnt lgkmcnt(0)
; __device__ __forceinline__ void scan_rows(f32x2 (&X)[8], const ScanOps& o, const f32x4 (&b)[2], const f32x4 (&kd)[2], const f32x4 (&r)[2], const bool use_v, float& yA, float& yB) {
;     f32x2 aA = X[0] * o.kk[0].xy, aB = X[4] * o.kk[0].xy;
;     aA += X[1] * o.kk[0].zw; aB += X[5] * o.kk[0].zw;
;     aA += X[2] * o.kk[1].xy; aB += X[6] * o.kk[1].xy;
;     aA += X[3] * o.kk[1].zw; aB += X[7] * o.kk[1].zw;
;     const float saA = sum8(aA.x + aA.y), saB = sum8(aB.x + aB.y);
;     const f32x2 nA = (f32x2){-saA, -saA}, nB = (f32x2){-saB, -saB}, vA = (f32x2){o.v.x, o.v.x}, vB = (f32x2){o.v.y, o.v.y};
;     f32x2 tA, tB, accA, accB;
;     tA = X[0] * o.w[0].xy; tA += nA * b[0].xy; if (use_v) tA += vA * kd[0].xy; X[0] = tA; accA = tA * r[0].xy;
;     tB = X[4] * o.w[0].xy; tB += nB * b[0].xy; if (use_v) tB += vB * kd[0].xy; X[4] = tB; accB = tB * r[0].xy;
;     tA = X[1] * o.w[0].zw; tA += nA * b[0].zw; if (use_v) tA += vA * kd[0].zw; X[1] = tA; accA += tA * r[0].zw;
;     tB = X[5] * o.w[0].zw; tB += nB * b[0].zw; if (use_v) tB += vB * kd[0].zw; X[5] = tB; accB += tB * r[0].zw;
;     tA = X[2] * o.w[1].xy; tA += nA * b[1].xy; if (use_v) tA += vA * kd[1].xy; X[2] = tA; accA += tA * r[1].xy;
;     tB = X[6] * o.w[1].xy; tB += nB * b[1].xy; if (use_v) tB += vB * kd[1].xy; X[6] = tB; accB += tB * r[1].xy;
;     tA = X[3] * o.w[1].zw; tA += nA * b[1].zw; if (use_v) tA += vA * kd[1].zw; X[3] = tA; accA += tA * r[1].zw;
;     tB = X[7] * o.w[1].zw; tB += nB * b[1].zw; if (use_v) tB += vB * kd[1].zw; X[7] = tB; accB += tB * r[1].zw;
;     yA = sum8(accA.x + accA.y); yB = sum8(accB.x + accB.y);
; __device__ void phase_scan(int c, const bf16_t* PROJ, const float* k_k, const bf16_t* Wd, const bf16_t* Bd, const float* k_a, bf16_t* Y, bf16_t* Q, float* FS, float* sm) {
;     ...
;                 ScanOps A, B;
;                 scan_ld(ob, obv, 0, A);
; #pragma unroll
;                 for (int i = 0; i < 16; i += 2) {
;                     float yA = 0.f, yB = 0.f;
;                     scan_ld(ob, obv, i + 1, B);
;                     if (roleP) A.v = (f32x2){0.f, 0.f};
;                     scan_step1(X, A, ob + i * 64, yA, yB);
;                     *(f32x2*)(obw + i * 16 + 2 * vp) = (f32x2){yA, yB};
;                     if (i + 2 < 16) scan_ld(ob, obv, i + 2, A);
;                     if (roleP) B.v = (f32x2){0.f, 0.f};
	ds_read_b128 v[86:89], v84 offset:512
	ds_read_b128 v[90:93], v84 offset:528
	ds_read_b128 v[94:97], v84 offset:4608
	ds_read_b128 v[98:101], v84 offset:4624
	ds_read_b128 v[102:105], v84 offset:8704
	ds_read_b128 v[106:109], v84 offset:8720
	ds_read_b128 v[110:113], v84 offset:12800
	ds_read_b128 v[114:117], v84 offset:12816
	ds_read_b128 v[118:121], v84 offset:16896
	ds_read_b128 v[122:125], v84 offset:16912
	ds_read_b64 v[126:127], v85 offset:20992
	v_pk_mul_f32 v[212:213], v[22:23], v[136:137]
	v_pk_mul_f32 v[216:217], v[14:15], v[136:137]
	v_pk_mul_f32 v[196:197], v[22:23], v[128:129]
	v_pk_mul_f32 v[204:205], v[14:15], v[128:129]
	v_pk_fma_f32 v[212:213], v[24:25], v[138:139], v[212:213]
	v_pk_fma_f32 v[216:217], v[16:17], v[138:139], v[216:217]
	v_pk_mul_f32 v[198:199], v[24:25], v[130:131]
	v_pk_mul_f32 v[206:207], v[16:17], v[130:131]
	v_pk_fma_f32 v[212:213], v[18:19], v[140:141], v[212:213]
	v_pk_fma_f32 v[216:217], v[10:11], v[140:141], v[216:217]
	v_pk_mul_f32 v[200:201], v[18:19], v[132:133]
	v_pk_mul_f32 v[208:209], v[10:11], v[132:133]
	v_pk_fma_f32 v[212:213], v[20:21], v[142:143], v[212:213]
	v_pk_fma_f32 v[216:217], v[12:13], v[142:143], v[216:217]
	v_pk_mul_f32 v[202:203], v[20:21], v[134:135]
	v_pk_mul_f32 v[210:211], v[12:13], v[134:135]
	v_add_f32_e32 v226, v222, v223
	v_add_f32_e32 v227, v224, v225
	v_add_f32_e32 v220, v212, v213
	v_add_f32_e32 v221, v216, v217
	v_pk_fma_f32 v[196:197], v[168:169], v[152:153], v[196:197] op_sel_hi:[0,1,1]
	v_pk_fma_f32 v[204:205], v[168:169], v[152:153], v[204:205] op_sel:[1,0,0] op_sel_hi:[1,1,1]
	ds_write_b64 v228, v[226:227]
	v_add_f32_dpp v220, v220, v220 quad_perm:[1,0,3,2] row_mask:0xf bank_mask:0xf bound_ctrl:1
	v_add_f32_dpp v221, v221, v221 quad_perm:[1,0,3,2] row_mask:0xf bank_mask:0xf bound_ctrl:1
	v_pk_fma_f32 v[198:199], v[168:169], v[154:155], v[198:199] op_sel_hi:[0,1,1]
	v_pk_fma_f32 v[206:207], v[168:169], v[154:155], v[206:207] op_sel:[1,0,0] op_sel_hi:[1,1,1]
	v_add_f32_dpp v220, v220, v220 quad_perm:[2,3,0,1] row_mask:0xf bank_mask:0xf bound_ctrl:1
	v_add_f32_dpp v221, v221, v221 quad_perm:[2,3,0,1] row_mask:0xf bank_mask:0xf bound_ctrl:1
	v_pk_fma_f32 v[200:201], v[168:169], v[156:157], v[200:201] op_sel_hi:[0,1,1]
	v_pk_fma_f32 v[208:209], v[168:169], v[156:157], v[208:209] op_sel:[1,0,0] op_sel_hi:[1,1,1]
	v_add_f32_dpp v220, v220, v220 row_half_mirror row_mask:0xf bank_mask:0xf bound_ctrl:1
	v_add_f32_dpp v221, v221, v221 row_half_mirror row_mask:0xf bank_mask:0xf bound_ctrl:1
	v_pk_fma_f32 v[202:203], v[168:169], v[158:159], v[202:203] op_sel_hi:[0,1,1]
	v_pk_fma_f32 v[210:211], v[168:169], v[158:159], v[210:211] op_sel:[1,0,0] op_sel_hi:[1,1,1]
	v_pk_fma_f32 v[22:23], v[220:221], v[144:145], v[196:197] op_sel_hi:[0,1,1] neg_lo:[1,0,0] neg_hi:[1,0,0]
	v_pk_fma_f32 v[14:15], v[220:221], v[144:145], v[204:205] op_sel:[1,0,0] op_sel_hi:[1,1,1] neg_lo:[1,0,0] neg_hi:[1,0,0]
	v_pk_fma_f32 v[24:25], v[220:221], v[146:147], v[198:199] op_sel_hi:[0,1,1] neg_lo:[1,0,0] neg_hi:[1,0,0]
	v_pk_fma_f32 v[16:17], v[220:221], v[146:147], v[206:207] op_sel:[1,0,0] op_sel_hi:[1,1,1] neg_lo:[1,0,0] neg_hi:[1,0,0]
	v_pk_fma_f32 v[18:19], v[220:221], v[148:149], v[200:201] op_sel_hi:[0,1,1] neg_lo:[1,0,0] neg_hi:[1,0,0]
	v_pk_fma_f32 v[10:11], v[220:221], v[148:149], v[208:209] op_sel:[1,0,0] op_sel_hi:[1,1,1] neg_lo:[1,0,0] neg_hi:[1,0,0]
	v_pk_fma_f32 v[20:21], v[220:221], v[150:151], v[202:203] op_sel_hi:[0,1,1] neg_lo:[1,0,0] neg_hi:[1,0,0]
	v_pk_fma_f32 v[12:13], v[220:221], v[150:151], v[210:211] op_sel:[1,0,0] op_sel_hi:[1,1,1] neg_lo:[1,0,0] neg_hi:[1,0,0]
	v_pk_mul_f32 v[222:223], v[22:23], v[160:161]
	v_pk_mul_f32 v[224:225], v[14:15], v[160:161]
	v_pk_fma_f32 v[222:223], v[24:25], v[162:163], v[222:223]
	v_pk_fma_f32 v[224:225], v[16:17], v[162:163], v[224:225]
	v_pk_fma_f32 v[222:223], v[18:19], v[164:165], v[222:223]
	v_pk_fma_f32 v[224:225], v[10:11], v[164:165], v[224:225]
	v_pk_fma_f32 v[222:223], v[20:21], v[166:167], v[222:223]
	v_pk_fma_f32 v[224:225], v[12:13], v[166:167], v[224:225]
	s_waitcnt lgkmcnt(0)
	ds_read_b128 v[128:131], v84 offset:768
	ds_read_b128 v[132:135], v84 offset:784
	ds_read_b128 v[136:139], v84 offset:4864
	ds_read_b128 v[140:143], v84 offset:4880
	ds_read_b128 v[144:147], v84 offset:8960
	ds_read_b128 v[148:151], v84 offset:8976
	ds_read_b128 v[152:155], v84 offset:13056
	ds_read_b128 v[156:159], v84 offset:13072
	ds_read_b128 v[160:163], v84 offset:17152
	ds_read_b128 v[164:167], v84 offset:17168
	ds_read_b64 v[168:169], v85 offset:21248
	v_pk_mul_f32 v[212:213], v[22:23], v[94:95]
	v_pk_mul_f32 v[216:217], v[14:15], v[94:95]
	v_pk_mul_f32 v[196:197], v[22:23], v[86:87]
	v_pk_mul_f32 v[204:205], v[14:15], v[86:87]
	v_pk_fma_f32 v[212:213], v[24:25], v[96:97], v[212:213]
	v_pk_fma_f32 v[216:217], v[16:17], v[96:97], v[216:217]
	v_pk_mul_f32 v[198:199], v[24:25], v[88:89]
	v_pk_mul_f32 v[206:207], v[16:17], v[88:89]
	v_pk_fma_f32 v[212:213], v[18:19], v[98:99], v[212:213]
	v_pk_fma_f32 v[216:217], v[10:11], v[98:99], v[216:217]
	v_pk_mul_f32 v[200:201], v[18:19], v[90:91]
	v_pk_mul_f32 v[208:209], v[10:11], v[90:91]
	v_pk_fma_f32 v[212:213], v[20:21], v[100:101], v[212:213]
	v_pk_fma_f32 v[216:217], v[12:13], v[100:101], v[216:217]
	v_pk_mul_f32 v[202:203], v[20:21], v[92:93]
	v_pk_mul_f32 v[210:211], v[12:13], v[92:93]
	v_add_f32_e32 v226, v222, v223
	v_add_f32_e32 v227, v224, v225
	v_add_f32_e32 v220, v212, v213
	v_add_f32_e32 v221, v216, v217
	v_pk_fma_f32 v[196:197], v[126:127], v[110:111], v[196:197] op_sel_hi:[0,1,1]
	v_pk_fma_f32 v[204:205], v[126:127], v[110:111], v[204:205] op_sel:[1,0,0] op_sel_hi:[1,1,1]
; __device__ __forceinline__ void scan_rows(f32x2 (&X)[8], const ScanOps& o, const f32x4 (&b)[2], const f32x4 (&kd)[2], const f32x4 (&r)[2], const bool use_v, float& yA, float& yB) {
;     f32x2 aA = X[0] * o.kk[0].xy, aB = X[4] * o.kk[0].xy;
;     aA += X[1] * o.kk[0].zw; aB += X[5] * o.kk[0].zw;
;     aA += X[2] * o.kk[1].xy; aB += X[6] * o.kk[1].xy;
;     aA += X[3] * o.kk[1].zw; aB += X[7] * o.kk[1].zw;
;     const float saA = sum8(aA.x + aA.y), saB = sum8(aB.x + aB.y);
;     const f32x2 nA = (f32x2){-saA, -saA}, nB = (f32x2){-saB, -saB}, vA = (f32x2){o.v.x, o.v.x}, vB = (f32x2){o.v.y, o.v.y};
;     f32x2 tA, tB, accA, accB;
;     tA = X[0] * o.w[0].xy; tA += nA * b[0].xy; if (use_v) tA += vA * kd[0].xy; X[0] = tA; accA = tA * r[0].xy;
;     tB = X[4] * o.w[0].xy; tB += nB * b[0].xy; if (use_v) tB += vB * kd[0].xy; X[4] = tB; accB = tB * r[0].xy;
;     tA = X[1] * o.w[0].zw; tA += nA * b[0].zw; if (use_v) tA += vA * kd[0].zw; X[1] = tA; accA += tA * r[0].zw;
;     tB = X[5] * o.w[0].zw; tB += nB * b[0].zw; if (use_v) tB += vB * kd[0].zw; X[5] = tB; accB += tB * r[0].zw;
;     tA = X[2] * o.w[1].xy; tA += nA * b[1].xy; if (use_v) tA += vA * kd[1].xy; X[2] = tA; accA += tA * r[1].xy;
;     tB = X[6] * o.w[1].xy; tB += nB * b[1].xy; if (use_v) tB += vB * kd[1].xy; X[6] = tB; accB += tB * r[1].xy;
;     tA = X[3] * o.w[1].zw; tA += nA * b[1].zw; if (use_v) tA += vA * kd[1].zw; X[3] = tA; accA += tA * r[1].zw;
;     tB = X[7] * o.w[1].zw; tB += nB * b[1].zw; if (use_v) tB += vB * kd[1].zw; X[7] = tB; accB += tB * r[1].zw;
;     yA = sum8(accA.x + accA.y); yB = sum8(accB.x + accB.y);
; __device__ void phase_scan(int c, const bf16_t* PROJ, const float* k_k, const bf16_t* Wd, const bf16_t* Bd, const float* k_a, bf16_t* Y, bf16_t* Q, float* FS, float* sm) {
;     ...
;                 ScanOps A, B;
;                 scan_ld(ob, obv, 0, A);
; #pragma unroll
;                 for (int i = 0; i < 16; i += 2) {
;                     float yA = 0.f, yB = 0.f;
;                     scan_ld(ob, obv, i + 1, B);
;                     if (roleP) A.v = (f32x2){0.f, 0.f};
;                     scan_step1(X, A, ob + i * 64, yA, yB);
;                     *(f32x2*)(obw + i * 16 + 2 * vp) = (f32x2){yA, yB};
;                     if (i + 2 < 16) scan_ld(ob, obv, i + 2, A);
;                     if (roleP) B.v = (f32x2){0.f, 0.f};
	ds_write_b64 v228, v[226:227] offset:576
	v_add_f32_dpp v220, v220, v220 quad_perm:[1,0,3,2] row_mask:0xf bank_mask:0xf bound_ctrl:1
	v_add_f32_dpp v221, v221, v221 quad_perm:[1,0,3,2] row_mask:0xf bank_mask:0xf bound_ctrl:1
	v_pk_fma_f32 v[198:199], v[126:127], v[112:113], v[198:199] op_sel_hi:[0,1,1]
	v_pk_fma_f32 v[206:207], v[126:127], v[112:113], v[206:207] op_sel:[1,0,0] op_sel_hi:[1,1,1]
	v_add_f32_dpp v220, v220, v220 quad_perm:[2,3,0,1] row_mask:0xf bank_mask:0xf bound_ctrl:1
	v_add_f32_dpp v221, v221, v221 quad_perm:[2,3,0,1] row_mask:0xf bank_mask:0xf bound_ctrl:1
	v_pk_fma_f32 v[200:201], v[126:127], v[114:115], v[200:201] op_sel_hi:[0,1,1]
	v_pk_fma_f32 v[208:209], v[126:127], v[114:115], v[208:209] op_sel:[1,0,0] op_sel_hi:[1,1,1]
	v_add_f32_dpp v220, v220, v220 row_half_mirror row_mask:0xf bank_mask:0xf bound_ctrl:1
	v_add_f32_dpp v221, v221, v221 row_half_mirror row_mask:0xf bank_mask:0xf bound_ctrl:1
	v_pk_fma_f32 v[202:203], v[126:127], v[116:117], v[202:203] op_sel_hi:[0,1,1]
	v_pk_fma_f32 v[210:211], v[126:127], v[116:117], v[210:211] op_sel:[1,0,0] op_sel_hi:[1,1,1]
	v_pk_fma_f32 v[22:23], v[220:221], v[102:103], v[196:197] op_sel_hi:[0,1,1] neg_lo:[1,0,0] neg_hi:[1,0,0]
	v_pk_fma_f32 v[14:15], v[220:221], v[102:103], v[204:205] op_sel:[1,0,0] op_sel_hi:[1,1,1] neg_lo:[1,0,0] neg_hi:[1,0,0]
	v_pk_fma_f32 v[24:25], v[220:221], v[104:105], v[198:199] op_sel_hi:[0,1,1] neg_lo:[1,0,0] neg_hi:[1,0,0]
	v_pk_fma_f32 v[16:17], v[220:221], v[104:105], v[206:207] op_sel:[1,0,0] op_sel_hi:[1,1,1] neg_lo:[1,0,0] neg_hi:[1,0,0]
	v_pk_fma_f32 v[18:19], v[220:221], v[106:107], v[200:201] op_sel_hi:[0,1,1] neg_lo:[1,0,0] neg_hi:[1,0,0]
	v_pk_fma_f32 v[10:11], v[220:221], v[106:107], v[208:209] op_sel:[1,0,0] op_sel_hi:[1,1,1] neg_lo:[1,0,0] neg_hi:[1,0,0]
	v_pk_fma_f32 v[20:21], v[220:221], v[108:109], v[202:203] op_sel_hi:[0,1,1] neg_lo:[1,0,0] neg_hi:[1,0,0]
	v_pk_fma_f32 v[12:13], v[220:221], v[108:109], v[210:211] op_sel:[1,0,0] op_sel_hi:[1,1,1] neg_lo:[1,0,0] neg_hi:[1,0,0]
	v_pk_mul_f32 v[222:223], v[22:23], v[118:119]
	v_pk_mul_f32 v[224:225], v[14:15], v[118:119]
	v_pk_fma_f32 v[222:223], v[24:25], v[120:121], v[222:223]
	v_pk_fma_f32 v[224:225], v[16:17], v[120:121], v[224:225]
	v_pk_fma_f32 v[222:223], v[18:19], v[122:123], v[222:223]
	v_pk_fma_f32 v[224:225], v[10:11], v[122:123], v[224:225]
	v_pk_fma_f32 v[222:223], v[20:21], v[124:125], v[222:223]
	v_pk_fma_f32 v[224:225], v[12:13], v[124:125], v[224:225]
	s_waitcnt lgkmcnt(0)
	ds_read_b128 v[86:89], v84 offset:1024
	ds_read_b128 v[90:93], v84 offset:1040
	ds_read_b128 v[94:97], v84 offset:5120
	ds_read_b128 v[98:101], v84 offset:5136
	ds_read_b128 v[102:105], v84 offset:9216
	ds_read_b128 v[106:109], v84 offset:9232
	ds_read_b128 v[110:113], v84 offset:13312
	ds_read_b128 v[114:117], v84 offset:13328
	ds_read_b128 v[118:121], v84 offset:17408
	ds_read_b128 v[122:125], v84 offset:17424
	ds_read_b64 v[126:127], v85 offset:21504
	v_pk_mul_f32 v[212:213], v[22:23], v[136:137]
	v_pk_mul_f32 v[216:217], v[14:15], v[136:137]
	v_pk_mul_f32 v[196:197], v[22:23], v[128:129]
	v_pk_mul_f32 v[204:205], v[14:15], v[128:129]
	v_pk_fma_f32 v[212:213], v[24:25], v[138:139], v[212:213]
	v_pk_fma_f32 v[216:217], v[16:17], v[138:139], v[216:217]
	v_pk_mul_f32 v[198:199], v[24:25], v[130:131]
	v_pk_mul_f32 v[206:207], v[16:17], v[130:131]
	v_pk_fma_f32 v[212:213], v[18:19], v[140:141], v[212:213]
	v_pk_fma_f32 v[216:217], v[10:11], v[140:141], v[216:217]
	v_pk_mul_f32 v[200:201], v[18:19], v[132:133]
	v_pk_mul_f32 v[208:209], v[10:11], v[132:133]
	v_pk_fma_f32 v[212:213], v[20:21], v[142:143], v[212:213]
	v_pk_fma_f32 v[216:217], v[12:13], v[142:143], v[216:217]
	v_pk_mul_f32 v[202:203], v[20:21], v[134:135]
	v_pk_mul_f32 v[210:211], v[12:13], v[134:135]
	v_add_f32_e32 v226, v222, v223
	v_add_f32_e32 v227, v224, v225
	v_add_f32_e32 v220, v212, v213
	v_add_f32_e32 v221, v216, v217
	v_pk_fma_f32 v[196:197], v[168:169], v[152:153], v[196:197] op_sel_hi:[0,1,1]
	v_pk_fma_f32 v[204:205], v[168:169], v[152:153], v[204:205] op_sel:[1,0,0] op_sel_hi:[1,1,1]
	ds_write_b64 v228, v[226:227] offset:1152
	v_add_f32_dpp v220, v220, v220 quad_perm:[1,0,3,2] row_mask:0xf bank_mask:0xf bound_ctrl:1
	v_add_f32_dpp v221, v221, v221 quad_perm:[1,0,3,2] row_mask:0xf bank_mask:0xf bound_ctrl:1
	v_pk_fma_f32 v[198:199], v[168:169], v[154:155], v[198:199] op_sel_hi:[0,1,1]
	v_pk_fma_f32 v[206:207], v[168:169], v[154:155], v[206:207] op_sel:[1,0,0] op_sel_hi:[1,1,1]
	v_add_f32_dpp v220, v220, v220 quad_perm:[2,3,0,1] row_mask:0xf bank_mask:0xf bound_ctrl:1
	v_add_f32_dpp v221, v221, v221 quad_perm:[2,3,0,1] row_mask:0xf bank_mask:0xf bound_ctrl:1
	v_pk_fma_f32 v[200:201], v[168:169], v[156:157], v[200:201] op_sel_hi:[0,1,1]
	v_pk_fma_f32 v[208:209], v[168:169], v[156:157], v[208:209] op_sel:[1,0,0] op_sel_hi:[1,1,1]
	v_add_f32_dpp v220, v220, v220 row_half_mirror row_mask:0xf bank_mask:0xf bound_ctrl:1
	v_add_f32_dpp v221, v221, v221 row_half_mirror row_mask:0xf bank_mask:0xf bound_ctrl:1
	v_pk_fma_f32 v[202:203], v[168:169], v[158:159], v[202:203] op_sel_hi:[0,1,1]
	v_pk_fma_f32 v[210:211], v[168:169], v[158:159], v[210:211] op_sel:[1,0,0] op_sel_hi:[1,1,1]
	v_pk_fma_f32 v[22:23], v[220:221], v[144:145], v[196:197] op_sel_hi:[0,1,1] neg_lo:[1,0,0] neg_hi:[1,0,0]
	v_pk_fma_f32 v[14:15], v[220:221], v[144:145], v[204:205] op_sel:[1,0,0] op_sel_hi:[1,1,1] neg_lo:[1,0,0] neg_hi:[1,0,0]
	v_pk_fma_f32 v[24:25], v[220:221], v[146:147], v[198:199] op_sel_hi:[0,1,1] neg_lo:[1,0,0] neg_hi:[1,0,0]
	v_pk_fma_f32 v[16:17], v[220:221], v[146:147], v[206:207] op_sel:[1,0,0] op_sel_hi:[1,1,1] neg_lo:[1,0,0] neg_hi:[1,0,0]
	v_pk_fma_f32 v[18:19], v[220:221], v[148:149], v[200:201] op_sel_hi:[0,1,1] neg_lo:[1,0,0] neg_hi:[1,0,0]
	v_pk_fma_f32 v[10:11], v[220:221], v[148:149], v[208:209] op_sel:[1,0,0] op_sel_hi:[1,1,1] neg_lo:[1,0,0] neg_hi:[1,0,0]
	v_pk_fma_f32 v[20:21], v[220:221], v[150:151], v[202:203] op_sel_hi:[0,1,1] neg_lo:[1,0,0] neg_hi:[1,0,0]
	v_pk_fma_f32 v[12:13], v[220:221], v[150:151], v[210:211] op_sel:[1,0,0] op_sel_hi:[1,1,1] neg_lo:[1,0,0] neg_hi:[1,0,0]
	v_pk_mul_f32 v[222:223], v[22:23], v[160:161]
	v_pk_mul_f32 v[224:225], v[14:15], v[160:161]
	v_pk_fma_f32 v[222:223], v[24:25], v[162:163], v[222:223]
	v_pk_fma_f32 v[224:225], v[16:17], v[162:163], v[224:225]
	v_pk_fma_f32 v[222:223], v[18:19], v[164:165], v[222:223]
	v_pk_fma_f32 v[224:225], v[10:11], v[164:165], v[224:225]
	v_pk_fma_f32 v[222:223], v[20:21], v[166:167], v[222:223]
	v_pk_fma_f32 v[224:225], v[12:13], v[166:167], v[224:225]
	s_waitcnt lgkmcnt(0)
; __device__ __forceinline__ void scan_rows(f32x2 (&X)[8], const ScanOps& o, const f32x4 (&b)[2], const f32x4 (&kd)[2], const f32x4 (&r)[2], const bool use_v, float& yA, float& yB) {
;     f32x2 aA = X[0] * o.kk[0].xy, aB = X[4] * o.kk[0].xy;
;     aA += X[1] * o.kk[0].zw; aB += X[5] * o.kk[0].zw;
;     aA += X[2] * o.kk[1].xy; aB += X[6] * o.kk[1].xy;
;     aA += X[3] * o.kk[1].zw; aB += X[7] * o.kk[1].zw;
;     const float saA = sum8(aA.x + aA.y), saB = sum8(aB.x + aB.y);
;     const f32x2 nA = (f32x2){-saA, -saA}, nB = (f32x2){-saB, -saB}, vA = (f32x2){o.v.x, o.v.x}, vB = (f32x2){o.v.y, o.v.y};
;     f32x2 tA, tB, accA, accB;
;     tA = X[0] * o.w[0].xy; tA += nA * b[0].xy; if (use_v) tA += vA * kd[0].xy; X[0] = tA; accA = tA * r[0].xy;
;     tB = X[4] * o.w[0].xy; tB += nB * b[0].xy; if (use_v) tB += vB * kd[0].xy; X[4] = tB; accB = tB * r[0].xy;
;     tA = X[1] * o.w[0].zw; tA += nA * b[0].zw; if (use_v) tA += vA * kd[0].zw; X[1] = tA; accA += tA * r[0].zw;
;     tB = X[5] * o.w[0].zw; tB += nB * b[0].zw; if (use_v) tB += vB * kd[0].zw; X[5] = tB; accB += tB * r[0].zw;
;     tA = X[2] * o.w[1].xy; tA += nA * b[1].xy; if (use_v) tA += vA * kd[1].xy; X[2] = tA; accA += tA * r[1].xy;
;     tB = X[6] * o.w[1].xy; tB += nB * b[1].xy; if (use_v) tB += vB * kd[1].xy; X[6] = tB; accB += tB * r[1].xy;
;     tA = X[3] * o.w[1].zw; tA += nA * b[1].zw; if (use_v) tA += vA * kd[1].zw; X[3] = tA; accA += tA * r[1].zw;
;     tB = X[7] * o.w[1].zw; tB += nB * b[1].zw; if (use_v) tB += vB * kd[1].zw; X[7] = tB; accB += tB * r[1].zw;
;     yA = sum8(accA.x + accA.y); yB = sum8(accB.x + accB.y);
; __device__ void phase_scan(int c, const bf16_t* PROJ, const float* k_k, const bf16_t* Wd, const bf16_t* Bd, const float* k_a, bf16_t* Y, bf16_t* Q, float* FS, float* sm) {
;     ...
;                 ScanOps A, B;
;                 scan_ld(ob, obv, 0, A);
; #pragma unroll
;                 for (int i = 0; i < 16; i += 2) {
;                     float yA = 0.f, yB = 0.f;
;                     scan_ld(ob, obv, i + 1, B);
;                     if (roleP) A.v = (f32x2){0.f, 0.f};
;                     scan_step1(X, A, ob + i * 64, yA, yB);
;                     *(f32x2*)(obw + i * 16 + 2 * vp) = (f32x2){yA, yB};
;                     if (i + 2 < 16) scan_ld(ob, obv, i + 2, A);
;                     if (roleP) B.v = (f32x2){0.f, 0.f};
	ds_read_b128 v[128:131], v84 offset:1280
	ds_read_b128 v[132:135], v84 offset:1296
	ds_read_b128 v[136:139], v84 offset:5376
	ds_read_b128 v[140:143], v84 offset:5392
	ds_read_b128 v[144:147], v84 offset:9472
	ds_read_b128 v[148:151], v84 offset:9488
	ds_read_b128 v[152:155], v84 offset:13568
	ds_read_b128 v[156:159], v84 offset:13584
	ds_read_b128 v[160:163], v84 offset:17664
	ds_read_b128 v[164:167], v84 offset:17680
	ds_read_b64 v[168:169], v85 offset:21760
	v_pk_mul_f32 v[212:213], v[22:23], v[94:95]
	v_pk_mul_f32 v[216:217], v[14:15], v[94:95]
	v_pk_mul_f32 v[196:197], v[22:23], v[86:87]
	v_pk_mul_f32 v[204:205], v[14:15], v[86:87]
	v_pk_fma_f32 v[212:213], v[24:25], v[96:97], v[212:213]
	v_pk_fma_f32 v[216:217], v[16:17], v[96:97], v[216:217]
	v_pk_mul_f32 v[198:199], v[24:25], v[88:89]
	v_pk_mul_f32 v[206:207], v[16:17], v[88:89]
	v_pk_fma_f32 v[212:213], v[18:19], v[98:99], v[212:213]
	v_pk_fma_f32 v[216:217], v[10:11], v[98:99], v[216:217]
	v_pk_mul_f32 v[200:201], v[18:19], v[90:91]
	v_pk_mul_f32 v[208:209], v[10:11], v[90:91]
	v_pk_fma_f32 v[212:213], v[20:21], v[100:101], v[212:213]
	v_pk_fma_f32 v[216:217], v[12:13], v[100:101], v[216:217]
	v_pk_mul_f32 v[202:203], v[20:21], v[92:93]
	v_pk_mul_f32 v[210:211], v[12:13], v[92:93]
	v_add_f32_e32 v226, v222, v223
	v_add_f32_e32 v227, v224, v225
	v_add_f32_e32 v220, v212, v213
	v_add_f32_e32 v221, v216, v217
	v_pk_fma_f32 v[196:197], v[126:127], v[110:111], v[196:197] op_sel_hi:[0,1,1]
	v_pk_fma_f32 v[204:205], v[126:127], v[110:111], v[204:205] op_sel:[1,0,0] op_sel_hi:[1,1,1]
	ds_write_b64 v228, v[226:227] offset:1728
	v_add_f32_dpp v220, v220, v220 quad_perm:[1,0,3,2] row_mask:0xf bank_mask:0xf bound_ctrl:1
	v_add_f32_dpp v221, v221, v221 quad_perm:[1,0,3,2] row_mask:0xf bank_mask:0xf bound_ctrl:1
	v_pk_fma_f32 v[198:199], v[126:127], v[112:113], v[198:199] op_sel_hi:[0,1,1]
	v_pk_fma_f32 v[206:207], v[126:127], v[112:113], v[206:207] op_sel:[1,0,0] op_sel_hi:[1,1,1]
	v_add_f32_dpp v220, v220, v220 quad_perm:[2,3,0,1] row_mask:0xf bank_mask:0xf bound_ctrl:1
	v_add_f32_dpp v221, v221, v221 quad_perm:[2,3,0,1] row_mask:0xf bank_mask:0xf bound_ctrl:1
	v_pk_fma_f32 v[200:201], v[126:127], v[114:115], v[200:201] op_sel_hi:[0,1,1]
	v_pk_fma_f32 v[208:209], v[126:127], v[114:115], v[208:209] op_sel:[1,0,0] op_sel_hi:[1,1,1]
	v_add_f32_dpp v220, v220, v220 row_half_mirror row_mask:0xf bank_mask:0xf bound_ctrl:1
	v_add_f32_dpp v221, v221, v221 row_half_mirror row_mask:0xf bank_mask:0xf bound_ctrl:1
	v_pk_fma_f32 v[202:203], v[126:127], v[116:117], v[202:203] op_sel_hi:[0,1,1]
	v_pk_fma_f32 v[210:211], v[126:127], v[116:117], v[210:211] op_sel:[1,0,0] op_sel_hi:[1,1,1]
	v_pk_fma_f32 v[22:23], v[220:221], v[102:103], v[196:197] op_sel_hi:[0,1,1] neg_lo:[1,0,0] neg_hi:[1,0,0]
	v_pk_fma_f32 v[14:15], v[220:221], v[102:103], v[204:205] op_sel:[1,0,0] op_sel_hi:[1,1,1] neg_lo:[1,0,0] neg_hi:[1,0,0]
	v_pk_fma_f32 v[24:25], v[220:221], v[104:105], v[198:199] op_sel_hi:[0,1,1] neg_lo:[1,0,0] neg_hi:[1,0,0]
	v_pk_fma_f32 v[16:17], v[220:221], v[104:105], v[206:207] op_sel:[1,0,0] op_sel_hi:[1,1,1] neg_lo:[1,0,0] neg_hi:[1,0,0]
	v_pk_fma_f32 v[18:19], v[220:221], v[106:107], v[200:201] op_sel_hi:[0,1,1] neg_lo:[1,0,0] neg_hi:[1,0,0]
	v_pk_fma_f32 v[10:11], v[220:221], v[106:107], v[208:209] op_sel:[1,0,0] op_sel_hi:[1,1,1] neg_lo:[1,0,0] neg_hi:[1,0,0]
	v_pk_fma_f32 v[20:21], v[220:221], v[108:109], v[202:203] op_sel_hi:[0,1,1] neg_lo:[1,0,0] neg_hi:[1,0,0]
	v_pk_fma_f32 v[12:13], v[220:221], v[108:109], v[210:211] op_sel:[1,0,0] op_sel_hi:[1,1,1] neg_lo:[1,0,0] neg_hi:[1,0,0]
	v_pk_mul_f32 v[222:223], v[22:23], v[118:119]
	v_pk_mul_f32 v[224:225], v[14:15], v[118:119]
	v_pk_fma_f32 v[222:223], v[24:25], v[120:121], v[222:223]
	v_pk_fma_f32 v[224:225], v[16:17], v[120:121], v[224:225]
	v_pk_fma_f32 v[222:223], v[18:19], v[122:123], v[222:223]
	v_pk_fma_f32 v[224:225], v[10:11], v[122:123], v[224:225]
	v_pk_fma_f32 v[222:223], v[20:21], v[124:125], v[222:223]
	v_pk_fma_f32 v[224:225], v[12:13], v[124:125], v[224:225]
	s_waitcnt lgkmcnt(0)
	ds_read_b128 v[86:89], v84 offset:1536
	ds_read_b128 v[90:93], v84 offset:1552
	ds_read_b128 v[94:97], v84 offset:5632
	ds_read_b128 v[98:101], v84 offset:5648
	ds_read_b128 v[102:105], v84 offset:9728
	ds_read_b128 v[106:109], v84 offset:9744
	ds_read_b128 v[110:113], v84 offset:13824
	ds_read_b128 v[114:117], v84 offset:13840
	ds_read_b128 v[118:121], v84 offset:17920
	ds_read_b128 v[122:125], v84 offset:17936
	ds_read_b64 v[126:127], v85 offset:22016
	v_pk_mul_f32 v[212:213], v[22:23], v[136:137]
	v_pk_mul_f32 v[216:217], v[14:15], v[136:137]
	v_pk_mul_f32 v[196:197], v[22:23], v[128:129]
	v_pk_mul_f32 v[204:205], v[14:15], v[128:129]
	v_pk_fma_f32 v[212:213], v[24:25], v[138:139], v[212:213]
	v_pk_fma_f32 v[216:217], v[16:17], v[138:139], v[216:217]
	v_pk_mul_f32 v[198:199], v[24:25], v[130:131]
	v_pk_mul_f32 v[206:207], v[16:17], v[130:131]
	v_pk_fma_f32 v[212:213], v[18:19], v[140:141], v[212:213]
	v_pk_fma_f32 v[216:217], v[10:11], v[140:141], v[216:217]
	v_pk_mul_f32 v[200:201], v[18:19], v[132:133]
	v_pk_mul_f32 v[208:209], v[10:11], v[132:133]
	v_pk_fma_f32 v[212:213], v[20:21], v[142:143], v[212:213]
	v_pk_fma_f32 v[216:217], v[12:13], v[142:143], v[216:217]
	v_pk_mul_f32 v[202:203], v[20:21], v[134:135]
	v_pk_mul_f32 v[210:211], v[12:13], v[134:135]
	v_add_f32_e32 v226, v222, v223
	v_add_f32_e32 v227, v224, v225
	v_add_f32_e32 v220, v212, v213
	v_add_f32_e32 v221, v216, v217
	v_pk_fma_f32 v[196:197], v[168:169], v[152:153], v[196:197] op_sel_hi:[0,1,1]
	v_pk_fma_f32 v[204:205], v[168:169], v[152:153], v[204:205] op_sel:[1,0,0] op_sel_hi:[1,1,1]
; __device__ __forceinline__ void scan_rows(f32x2 (&X)[8], const ScanOps& o, const f32x4 (&b)[2], const f32x4 (&kd)[2], const f32x4 (&r)[2], const bool use_v, float& yA, float& yB) {
;     f32x2 aA = X[0] * o.kk[0].xy, aB = X[4] * o.kk[0].xy;
;     aA += X[1] * o.kk[0].zw; aB += X[5] * o.kk[0].zw;
;     aA += X[2] * o.kk[1].xy; aB += X[6] * o.kk[1].xy;
;     aA += X[3] * o.kk[1].zw; aB += X[7] * o.kk[1].zw;
;     const float saA = sum8(aA.x + aA.y), saB = sum8(aB.x + aB.y);
;     const f32x2 nA = (f32x2){-saA, -saA}, nB = (f32x2){-saB, -saB}, vA = (f32x2){o.v.x, o.v.x}, vB = (f32x2){o.v.y, o.v.y};
;     f32x2 tA, tB, accA, accB;
;     tA = X[0] * o.w[0].xy; tA += nA * b[0].xy; if (use_v) tA += vA * kd[0].xy; X[0] = tA; accA = tA * r[0].xy;
;     tB = X[4] * o.w[0].xy; tB += nB * b[0].xy; if (use_v) tB += vB * kd[0].xy; X[4] = tB; accB = tB * r[0].xy;
;     tA = X[1] * o.w[0].zw; tA += nA * b[0].zw; if (use_v) tA += vA * kd[0].zw; X[1] = tA; accA += tA * r[0].zw;
;     tB = X[5] * o.w[0].zw; tB += nB * b[0].zw; if (use_v) tB += vB * kd[0].zw; X[5] = tB; accB += tB * r[0].zw;
;     tA = X[2] * o.w[1].xy; tA += nA * b[1].xy; if (use_v) tA += vA * kd[1].xy; X[2] = tA; accA += tA * r[1].xy;
;     tB = X[6] * o.w[1].xy; tB += nB * b[1].xy; if (use_v) tB += vB * kd[1].xy; X[6] = tB; accB += tB * r[1].xy;
;     tA = X[3] * o.w[1].zw; tA += nA * b[1].zw; if (use_v) tA += vA * kd[1].zw; X[3] = tA; accA += tA * r[1].zw;
;     tB = X[7] * o.w[1].zw; tB += nB * b[1].zw; if (use_v) tB += vB * kd[1].zw; X[7] = tB; accB += tB * r[1].zw;
;     yA = sum8(accA.x + accA.y); yB = sum8(accB.x + accB.y);
; __device__ void phase_scan(int c, const bf16_t* PROJ, const float* k_k, const bf16_t* Wd, const bf16_t* Bd, const float* k_a, bf16_t* Y, bf16_t* Q, float* FS, float* sm) {
;     ...
;                 for (int i = 0; i < 16; i += 2) {
;                     float yA = 0.f, yB = 0.f;
;                     scan_ld(ob, obv, i + 1, B);
;                     if (roleP) A.v = (f32x2){0.f, 0.f};
;                     scan_step1(X, A, ob + i * 64, yA, yB);
;                     *(f32x2*)(obw + i * 16 + 2 * vp) = (f32x2){yA, yB};
;                     if (i + 2 < 16) scan_ld(ob, obv, i + 2, A);
;                     if (roleP) B.v = (f32x2){0.f, 0.f};
;                     scan_step1(X, B, ob + (i + 1) * 64, yA, yB);
;                     *(f32x2*)(obw + (i + 1) * 16 + 2 * vp) = (f32x2){yA, yB};
	ds_write_b64 v228, v[226:227] offset:2304
	v_add_f32_dpp v220, v220, v220 quad_perm:[1,0,3,2] row_mask:0xf bank_mask:0xf bound_ctrl:1
	v_add_f32_dpp v221, v221, v221 quad_perm:[1,0,3,2] row_mask:0xf bank_mask:0xf bound_ctrl:1
	v_pk_fma_f32 v[198:199], v[168:169], v[154:155], v[198:199] op_sel_hi:[0,1,1]
	v_pk_fma_f32 v[206:207], v[168:169], v[154:155], v[206:207] op_sel:[1,0,0] op_sel_hi:[1,1,1]
	v_add_f32_dpp v220, v220, v220 quad_perm:[2,3,0,1] row_mask:0xf bank_mask:0xf bound_ctrl:1
	v_add_f32_dpp v221, v221, v221 quad_perm:[2,3,0,1] row_mask:0xf bank_mask:0xf bound_ctrl:1
	v_pk_fma_f32 v[200:201], v[168:169], v[156:157], v[200:201] op_sel_hi:[0,1,1]
	v_pk_fma_f32 v[208:209], v[168:169], v[156:157], v[208:209] op_sel:[1,0,0] op_sel_hi:[1,1,1]
	v_add_f32_dpp v220, v220, v220 row_half_mirror row_mask:0xf bank_mask:0xf bound_ctrl:1
	v_add_f32_dpp v221, v221, v221 row_half_mirror row_mask:0xf bank_mask:0xf bound_ctrl:1
	v_pk_fma_f32 v[202:203], v[168:169], v[158:159], v[202:203] op_sel_hi:[0,1,1]
	v_pk_fma_f32 v[210:211], v[168:169], v[158:159], v[210:211] op_sel:[1,0,0] op_sel_hi:[1,1,1]
	v_pk_fma_f32 v[22:23], v[220:221], v[144:145], v[196:197] op_sel_hi:[0,1,1] neg_lo:[1,0,0] neg_hi:[1,0,0]
	v_pk_fma_f32 v[14:15], v[220:221], v[144:145], v[204:205] op_sel:[1,0,0] op_sel_hi:[1,1,1] neg_lo:[1,0,0] neg_hi:[1,0,0]
	v_pk_fma_f32 v[24:25], v[220:221], v[146:147], v[198:199] op_sel_hi:[0,1,1] neg_lo:[1,0,0] neg_hi:[1,0,0]
	v_pk_fma_f32 v[16:17], v[220:221], v[146:147], v[206:207] op_sel:[1,0,0] op_sel_hi:[1,1,1] neg_lo:[1,0,0] neg_hi:[1,0,0]
	v_pk_fma_f32 v[18:19], v[220:221], v[148:149], v[200:201] op_sel_hi:[0,1,1] neg_lo:[1,0,0] neg_hi:[1,0,0]
	v_pk_fma_f32 v[10:11], v[220:221], v[148:149], v[208:209] op_sel:[1,0,0] op_sel_hi:[1,1,1] neg_lo:[1,0,0] neg_hi:[1,0,0]
	v_pk_fma_f32 v[20:21], v[220:221], v[150:151], v[202:203] op_sel_hi:[0,1,1] neg_lo:[1,0,0] neg_hi:[1,0,0]
	v_pk_fma_f32 v[12:13], v[220:221], v[150:151], v[210:211] op_sel:[1,0,0] op_sel_hi:[1,1,1] neg_lo:[1,0,0] neg_hi:[1,0,0]
	v_pk_mul_f32 v[222:223], v[22:23], v[160:161]
	v_pk_mul_f32 v[224:225], v[14:15], v[160:161]
	v_pk_fma_f32 v[222:223], v[24:25], v[162:163], v[222:223]
	v_pk_fma_f32 v[224:225], v[16:17], v[162:163], v[224:225]
	v_pk_fma_f32 v[222:223], v[18:19], v[164:165], v[222:223]
	v_pk_fma_f32 v[224:225], v[10:11], v[164:165], v[224:225]
	v_pk_fma_f32 v[222:223], v[20:21], v[166:167], v[222:223]
	v_pk_fma_f32 v[224:225], v[12:13], v[166:167], v[224:225]
	s_waitcnt lgkmcnt(0)
	ds_read_b128 v[128:131], v84 offset:1792
	ds_read_b128 v[132:135], v84 offset:1808
	ds_read_b128 v[136:139], v84 offset:5888
	ds_read_b128 v[140:143], v84 offset:5904
	ds_read_b128 v[144:147], v84 offset:9984
	ds_read_b128 v[148:151], v84 offset:10000
	ds_read_b128 v[152:155], v84 offset:14080
	ds_read_b128 v[156:159], v84 offset:14096
	ds_read_b128 v[160:163], v84 offset:18176
	ds_read_b128 v[164:167], v84 offset:18192
	ds_read_b64 v[168:169], v85 offset:22272
	v_pk_mul_f32 v[212:213], v[22:23], v[94:95]
	v_pk_mul_f32 v[216:217], v[14:15], v[94:95]
	v_pk_mul_f32 v[196:197], v[22:23], v[86:87]
	v_pk_mul_f32 v[204:205], v[14:15], v[86:87]
	v_pk_fma_f32 v[212:213], v[24:25], v[96:97], v[212:213]
	v_pk_fma_f32 v[216:217], v[16:17], v[96:97], v[216:217]
	v_pk_mul_f32 v[198:199], v[24:25], v[88:89]
	v_pk_mul_f32 v[206:207], v[16:17], v[88:89]
	v_pk_fma_f32 v[212:213], v[18:19], v[98:99], v[212:213]
	v_pk_fma_f32 v[216:217], v[10:11], v[98:99], v[216:217]
	v_pk_mul_f32 v[200:201], v[18:19], v[90:91]
	v_pk_mul_f32 v[208:209], v[10:11], v[90:91]
	v_pk_fma_f32 v[212:213], v[20:21], v[100:101], v[212:213]
	v_pk_fma_f32 v[216:217], v[12:13], v[100:101], v[216:217]
	v_pk_mul_f32 v[202:203], v[20:21], v[92:93]
	v_pk_mul_f32 v[210:211], v[12:13], v[92:93]
	v_add_f32_e32 v226, v222, v223
	v_add_f32_e32 v227, v224, v225
	v_add_f32_e32 v220, v212, v213
	v_add_f32_e32 v221, v216, v217
	v_pk_fma_f32 v[196:197], v[126:127], v[110:111], v[196:197] op_sel_hi:[0,1,1]
	v_pk_fma_f32 v[204:205], v[126:127], v[110:111], v[204:205] op_sel:[1,0,0] op_sel_hi:[1,1,1]
	ds_write_b64 v228, v[226:227] offset:2880
	v_add_f32_dpp v220, v220, v220 quad_perm:[1,0,3,2] row_mask:0xf bank_mask:0xf bound_ctrl:1
	v_add_f32_dpp v221, v221, v221 quad_perm:[1,0,3,2] row_mask:0xf bank_mask:0xf bound_ctrl:1
	v_pk_fma_f32 v[198:199], v[126:127], v[112:113], v[198:199] op_sel_hi:[0,1,1]
	v_pk_fma_f32 v[206:207], v[126:127], v[112:113], v[206:207] op_sel:[1,0,0] op_sel_hi:[1,1,1]
	v_add_f32_dpp v220, v220, v220 quad_perm:[2,3,0,1] row_mask:0xf bank_mask:0xf bound_ctrl:1
	v_add_f32_dpp v221, v221, v221 quad_perm:[2,3,0,1] row_mask:0xf bank_mask:0xf bound_ctrl:1
	v_pk_fma_f32 v[200:201], v[126:127], v[114:115], v[200:201] op_sel_hi:[0,1,1]
	v_pk_fma_f32 v[208:209], v[126:127], v[114:115], v[208:209] op_sel:[1,0,0] op_sel_hi:[1,1,1]
	v_add_f32_dpp v220, v220, v220 row_half_mirror row_mask:0xf bank_mask:0xf bound_ctrl:1
	v_add_f32_dpp v221, v221, v221 row_half_mirror row_mask:0xf bank_mask:0xf bound_ctrl:1
	v_pk_fma_f32 v[202:203], v[126:127], v[116:117], v[202:203] op_sel_hi:[0,1,1]
	v_pk_fma_f32 v[210:211], v[126:127], v[116:117], v[210:211] op_sel:[1,0,0] op_sel_hi:[1,1,1]
	v_pk_fma_f32 v[22:23], v[220:221], v[102:103], v[196:197] op_sel_hi:[0,1,1] neg_lo:[1,0,0] neg_hi:[1,0,0]
	v_pk_fma_f32 v[14:15], v[220:221], v[102:103], v[204:205] op_sel:[1,0,0] op_sel_hi:[1,1,1] neg_lo:[1,0,0] neg_hi:[1,0,0]
	v_pk_fma_f32 v[24:25], v[220:221], v[104:105], v[198:199] op_sel_hi:[0,1,1] neg_lo:[1,0,0] neg_hi:[1,0,0]
	v_pk_fma_f32 v[16:17], v[220:221], v[104:105], v[206:207] op_sel:[1,0,0] op_sel_hi:[1,1,1] neg_lo:[1,0,0] neg_hi:[1,0,0]
	v_pk_fma_f32 v[18:19], v[220:221], v[106:107], v[200:201] op_sel_hi:[0,1,1] neg_lo:[1,0,0] neg_hi:[1,0,0]
	v_pk_fma_f32 v[10:11], v[220:221], v[106:107], v[208:209] op_sel:[1,0,0] op_sel_hi:[1,1,1] neg_lo:[1,0,0] neg_hi:[1,0,0]
	v_pk_fma_f32 v[20:21], v[220:221], v[108:109], v[202:203] op_sel_hi:[0,1,1] neg_lo:[1,0,0] neg_hi:[1,0,0]
	v_pk_fma_f32 v[12:13], v[220:221], v[108:109], v[210:211] op_sel:[1,0,0] op_sel_hi:[1,1,1] neg_lo:[1,0,0] neg_hi:[1,0,0]
	v_pk_mul_f32 v[222:223], v[22:23], v[118:119]
	v_pk_mul_f32 v[224:225], v[14:15], v[118:119]
	v_pk_fma_f32 v[222:223], v[24:25], v[120:121], v[222:223]
	v_pk_fma_f32 v[224:225], v[16:17], v[120:121], v[224:225]
	v_pk_fma_f32 v[222:223], v[18:19], v[122:123], v[222:223]
	v_pk_fma_f32 v[224:225], v[10:11], v[122:123], v[224:225]
	v_pk_fma_f32 v[222:223], v[20:21], v[124:125], v[222:223]
	v_pk_fma_f32 v[224:225], v[12:13], v[124:125], v[224:225]
	s_waitcnt lgkmcnt(0)
; __device__ __forceinline__ void scan_rows(f32x2 (&X)[8], const ScanOps& o, const f32x4 (&b)[2], const f32x4 (&kd)[2], const f32x4 (&r)[2], const bool use_v, float& yA, float& yB) {
;     f32x2 aA = X[0] * o.kk[0].xy, aB = X[4] * o.kk[0].xy;
;     aA += X[1] * o.kk[0].zw; aB += X[5] * o.kk[0].zw;
;     aA += X[2] * o.kk[1].xy; aB += X[6] * o.kk[1].xy;
;     aA += X[3] * o.kk[1].zw; aB += X[7] * o.kk[1].zw;
;     const float saA = sum8(aA.x + aA.y), saB = sum8(aB.x + aB.y);
;     const f32x2 nA = (f32x2){-saA, -saA}, nB = (f32x2){-saB, -saB}, vA = (f32x2){o.v.x, o.v.x}, vB = (f32x2){o.v.y, o.v.y};
;     f32x2 tA, tB, accA, accB;
;     tA = X[0] * o.w[0].xy; tA += nA * b[0].xy; if (use_v) tA += vA * kd[0].xy; X[0] = tA; accA = tA * r[0].xy;
;     tB = X[4] * o.w[0].xy; tB += nB * b[0].xy; if (use_v) tB += vB * kd[0].xy; X[4] = tB; accB = tB * r[0].xy;
;     tA = X[1] * o.w[0].zw; tA += nA * b[0].zw; if (use_v) tA += vA * kd[0].zw; X[1] = tA; accA += tA * r[0].zw;
;     tB = X[5] * o.w[0].zw; tB += nB * b[0].zw; if (use_v) tB += vB * kd[0].zw; X[5] = tB; accB += tB * r[0].zw;
;     tA = X[2] * o.w[1].xy; tA += nA * b[1].xy; if (use_v) tA += vA * kd[1].xy; X[2] = tA; accA += tA * r[1].xy;
;     tB = X[6] * o.w[1].xy; tB += nB * b[1].xy; if (use_v) tB += vB * kd[1].xy; X[6] = tB; accB += tB * r[1].xy;
;     tA = X[3] * o.w[1].zw; tA += nA * b[1].zw; if (use_v) tA += vA * kd[1].zw; X[3] = tA; accA += tA * r[1].zw;
;     tB = X[7] * o.w[1].zw; tB += nB * b[1].zw; if (use_v) tB += vB * kd[1].zw; X[7] = tB; accB += tB * r[1].zw;
;     yA = sum8(accA.x + accA.y); yB = sum8(accB.x + accB.y);
; __device__ void phase_scan(int c, const bf16_t* PROJ, const float* k_k, const bf16_t* Wd, const bf16_t* Bd, const float* k_a, bf16_t* Y, bf16_t* Q, float* FS, float* sm) {
;     ...
;                 for (int i = 0; i < 16; i += 2) {
;                     float yA = 0.f, yB = 0.f;
;                     scan_ld(ob, obv, i + 1, B);
;                     if (roleP) A.v = (f32x2){0.f, 0.f};
;                     scan_step1(X, A, ob + i * 64, yA, yB);
;                     *(f32x2*)(obw + i * 16 + 2 * vp) = (f32x2){yA, yB};
;                     if (i + 2 < 16) scan_ld(ob, obv, i + 2, A);
;                     if (roleP) B.v = (f32x2){0.f, 0.f};
;                     scan_step1(X, B, ob + (i + 1) * 64, yA, yB);
;                     *(f32x2*)(obw + (i + 1) * 16 + 2 * vp) = (f32x2){yA, yB};
	ds_read_b128 v[86:89], v84 offset:2048
	ds_read_b128 v[90:93], v84 offset:2064
	ds_read_b128 v[94:97], v84 offset:6144
	ds_read_b128 v[98:101], v84 offset:6160
	ds_read_b128 v[102:105], v84 offset:10240
	ds_read_b128 v[106:109], v84 offset:10256
	ds_read_b128 v[110:113], v84 offset:14336
	ds_read_b128 v[114:117], v84 offset:14352
	ds_read_b128 v[118:121], v84 offset:18432
	ds_read_b128 v[122:125], v84 offset:18448
	ds_read_b64 v[126:127], v85 offset:22528
	v_pk_mul_f32 v[212:213], v[22:23], v[136:137]
	v_pk_mul_f32 v[216:217], v[14:15], v[136:137]
	v_pk_mul_f32 v[196:197], v[22:23], v[128:129]
	v_pk_mul_f32 v[204:205], v[14:15], v[128:129]
	v_pk_fma_f32 v[212:213], v[24:25], v[138:139], v[212:213]
	v_pk_fma_f32 v[216:217], v[16:17], v[138:139], v[216:217]
	v_pk_mul_f32 v[198:199], v[24:25], v[130:131]
	v_pk_mul_f32 v[206:207], v[16:17], v[130:131]
	v_pk_fma_f32 v[212:213], v[18:19], v[140:141], v[212:213]
	v_pk_fma_f32 v[216:217], v[10:11], v[140:141], v[216:217]
	v_pk_mul_f32 v[200:201], v[18:19], v[132:133]
	v_pk_mul_f32 v[208:209], v[10:11], v[132:133]
	v_pk_fma_f32 v[212:213], v[20:21], v[142:143], v[212:213]
	v_pk_fma_f32 v[216:217], v[12:13], v[142:143], v[216:217]
	v_pk_mul_f32 v[202:203], v[20:21], v[134:135]
	v_pk_mul_f32 v[210:211], v[12:13], v[134:135]
	v_add_f32_e32 v226, v222, v223
	v_add_f32_e32 v227, v224, v225
	v_add_f32_e32 v220, v212, v213
	v_add_f32_e32 v221, v216, v217
	v_pk_fma_f32 v[196:197], v[168:169], v[152:153], v[196:197] op_sel_hi:[0,1,1]
	v_pk_fma_f32 v[204:205], v[168:169], v[152:153], v[204:205] op_sel:[1,0,0] op_sel_hi:[1,1,1]
	ds_write_b64 v228, v[226:227] offset:3456
	v_add_f32_dpp v220, v220, v220 quad_perm:[1,0,3,2] row_mask:0xf bank_mask:0xf bound_ctrl:1
	v_add_f32_dpp v221, v221, v221 quad_perm:[1,0,3,2] row_mask:0xf bank_mask:0xf bound_ctrl:1
	v_pk_fma_f32 v[198:199], v[168:169], v[154:155], v[198:199] op_sel_hi:[0,1,1]
	v_pk_fma_f32 v[206:207], v[168:169], v[154:155], v[206:207] op_sel:[1,0,0] op_sel_hi:[1,1,1]
	v_add_f32_dpp v220, v220, v220 quad_perm:[2,3,0,1] row_mask:0xf bank_mask:0xf bound_ctrl:1
	v_add_f32_dpp v221, v221, v221 quad_perm:[2,3,0,1] row_mask:0xf bank_mask:0xf bound_ctrl:1
	v_pk_fma_f32 v[200:201], v[168:169], v[156:157], v[200:201] op_sel_hi:[0,1,1]
	v_pk_fma_f32 v[208:209], v[168:169], v[156:157], v[208:209] op_sel:[1,0,0] op_sel_hi:[1,1,1]
	v_add_f32_dpp v220, v220, v220 row_half_mirror row_mask:0xf bank_mask:0xf bound_ctrl:1
	v_add_f32_dpp v221, v221, v221 row_half_mirror row_mask:0xf bank_mask:0xf bound_ctrl:1
	v_pk_fma_f32 v[202:203], v[168:169], v[158:159], v[202:203] op_sel_hi:[0,1,1]
	v_pk_fma_f32 v[210:211], v[168:169], v[158:159], v[210:211] op_sel:[1,0,0] op_sel_hi:[1,1,1]
	v_pk_fma_f32 v[22:23], v[220:221], v[144:145], v[196:197] op_sel_hi:[0,1,1] neg_lo:[1,0,0] neg_hi:[1,0,0]
	v_pk_fma_f32 v[14:15], v[220:221], v[144:145], v[204:205] op_sel:[1,0,0] op_sel_hi:[1,1,1] neg_lo:[1,0,0] neg_hi:[1,0,0]
	v_pk_fma_f32 v[24:25], v[220:221], v[146:147], v[198:199] op_sel_hi:[0,1,1] neg_lo:[1,0,0] neg_hi:[1,0,0]
	v_pk_fma_f32 v[16:17], v[220:221], v[146:147], v[206:207] op_sel:[1,0,0] op_sel_hi:[1,1,1] neg_lo:[1,0,0] neg_hi:[1,0,0]
	v_pk_fma_f32 v[18:19], v[220:221], v[148:149], v[200:201] op_sel_hi:[0,1,1] neg_lo:[1,0,0] neg_hi:[1,0,0]
	v_pk_fma_f32 v[10:11], v[220:221], v[148:149], v[208:209] op_sel:[1,0,0] op_sel_hi:[1,1,1] neg_lo:[1,0,0] neg_hi:[1,0,0]
	v_pk_fma_f32 v[20:21], v[220:221], v[150:151], v[202:203] op_sel_hi:[0,1,1] neg_lo:[1,0,0] neg_hi:[1,0,0]
	v_pk_fma_f32 v[12:13], v[220:221], v[150:151], v[210:211] op_sel:[1,0,0] op_sel_hi:[1,1,1] neg_lo:[1,0,0] neg_hi:[1,0,0]
	v_pk_mul_f32 v[222:223], v[22:23], v[160:161]
	v_pk_mul_f32 v[224:225], v[14:15], v[160:161]
	v_pk_fma_f32 v[222:223], v[24:25], v[162:163], v[222:223]
	v_pk_fma_f32 v[224:225], v[16:17], v[162:163], v[224:225]
	v_pk_fma_f32 v[222:223], v[18:19], v[164:165], v[222:223]
	v_pk_fma_f32 v[224:225], v[10:11], v[164:165], v[224:225]
	v_pk_fma_f32 v[222:223], v[20:21], v[166:167], v[222:223]
	v_pk_fma_f32 v[224:225], v[12:13], v[166:167], v[224:225]
	s_waitcnt lgkmcnt(0)
	ds_read_b128 v[128:131], v84 offset:2304
	ds_read_b128 v[132:135], v84 offset:2320
	ds_read_b128 v[136:139], v84 offset:6400
	ds_read_b128 v[140:143], v84 offset:6416
	ds_read_b128 v[144:147], v84 offset:10496
	ds_read_b128 v[148:151], v84 offset:10512
	ds_read_b128 v[152:155], v84 offset:14592
	ds_read_b128 v[156:159], v84 offset:14608
	ds_read_b128 v[160:163], v84 offset:18688
	ds_read_b128 v[164:167], v84 offset:18704
	ds_read_b64 v[168:169], v85 offset:22784
	v_pk_mul_f32 v[212:213], v[22:23], v[94:95]
	v_pk_mul_f32 v[216:217], v[14:15], v[94:95]
	v_pk_mul_f32 v[196:197], v[22:23], v[86:87]
	v_pk_mul_f32 v[204:205], v[14:15], v[86:87]
	v_pk_fma_f32 v[212:213], v[24:25], v[96:97], v[212:213]
	v_pk_fma_f32 v[216:217], v[16:17], v[96:97], v[216:217]
	v_pk_mul_f32 v[198:199], v[24:25], v[88:89]
	v_pk_mul_f32 v[206:207], v[16:17], v[88:89]
	v_pk_fma_f32 v[212:213], v[18:19], v[98:99], v[212:213]
	v_pk_fma_f32 v[216:217], v[10:11], v[98:99], v[216:217]
	v_pk_mul_f32 v[200:201], v[18:19], v[90:91]
	v_pk_mul_f32 v[208:209], v[10:11], v[90:91]
	v_pk_fma_f32 v[212:213], v[20:21], v[100:101], v[212:213]
	v_pk_fma_f32 v[216:217], v[12:13], v[100:101], v[216:217]
	v_pk_mul_f32 v[202:203], v[20:21], v[92:93]
	v_pk_mul_f32 v[210:211], v[12:13], v[92:93]
	v_add_f32_e32 v226, v222, v223
	v_add_f32_e32 v227, v224, v225
	v_add_f32_e32 v220, v212, v213
	v_add_f32_e32 v221, v216, v217
	v_pk_fma_f32 v[196:197], v[126:127], v[110:111], v[196:197] op_sel_hi:[0,1,1]
	v_pk_fma_f32 v[204:205], v[126:127], v[110:111], v[204:205] op_sel:[1,0,0] op_sel_hi:[1,1,1]
; __device__ __forceinline__ void scan_rows(f32x2 (&X)[8], const ScanOps& o, const f32x4 (&b)[2], const f32x4 (&kd)[2], const f32x4 (&r)[2], const bool use_v, float& yA, float& yB) {
;     f32x2 aA = X[0] * o.kk[0].xy, aB = X[4] * o.kk[0].xy;
;     aA += X[1] * o.kk[0].zw; aB += X[5] * o.kk[0].zw;
;     aA += X[2] * o.kk[1].xy; aB += X[6] * o.kk[1].xy;
;     aA += X[3] * o.kk[1].zw; aB += X[7] * o.kk[1].zw;
;     const float saA = sum8(aA.x + aA.y), saB = sum8(aB.x + aB.y);
;     const f32x2 nA = (f32x2){-saA, -saA}, nB = (f32x2){-saB, -saB}, vA = (f32x2){o.v.x, o.v.x}, vB = (f32x2){o.v.y, o.v.y};
;     f32x2 tA, tB, accA, accB;
;     tA = X[0] * o.w[0].xy; tA += nA * b[0].xy; if (use_v) tA += vA * kd[0].xy; X[0] = tA; accA = tA * r[0].xy;
;     tB = X[4] * o.w[0].xy; tB += nB * b[0].xy; if (use_v) tB += vB * kd[0].xy; X[4] = tB; accB = tB * r[0].xy;
;     tA = X[1] * o.w[0].zw; tA += nA * b[0].zw; if (use_v) tA += vA * kd[0].zw; X[1] = tA; accA += tA * r[0].zw;
;     tB = X[5] * o.w[0].zw; tB += nB * b[0].zw; if (use_v) tB += vB * kd[0].zw; X[5] = tB; accB += tB * r[0].zw;
;     tA = X[2] * o.w[1].xy; tA += nA * b[1].xy; if (use_v) tA += vA * kd[1].xy; X[2] = tA; accA += tA * r[1].xy;
;     tB = X[6] * o.w[1].xy; tB += nB * b[1].xy; if (use_v) tB += vB * kd[1].xy; X[6] = tB; accB += tB * r[1].xy;
;     tA = X[3] * o.w[1].zw; tA += nA * b[1].zw; if (use_v) tA += vA * kd[1].zw; X[3] = tA; accA += tA * r[1].zw;
;     tB = X[7] * o.w[1].zw; tB += nB * b[1].zw; if (use_v) tB += vB * kd[1].zw; X[7] = tB; accB += tB * r[1].zw;
;     yA = sum8(accA.x + accA.y); yB = sum8(accB.x + accB.y);
; __device__ void phase_scan(int c, const bf16_t* PROJ, const float* k_k, const bf16_t* Wd, const bf16_t* Bd, const float* k_a, bf16_t* Y, bf16_t* Q, float* FS, float* sm) {
;     ...
;                 for (int i = 0; i < 16; i += 2) {
;                     float yA = 0.f, yB = 0.f;
;                     scan_ld(ob, obv, i + 1, B);
;                     if (roleP) A.v = (f32x2){0.f, 0.f};
;                     scan_step1(X, A, ob + i * 64, yA, yB);
;                     *(f32x2*)(obw + i * 16 + 2 * vp) = (f32x2){yA, yB};
;                     if (i + 2 < 16) scan_ld(ob, obv, i + 2, A);
;                     if (roleP) B.v = (f32x2){0.f, 0.f};
;                     scan_step1(X, B, ob + (i + 1) * 64, yA, yB);
;                     *(f32x2*)(obw + (i + 1) * 16 + 2 * vp) = (f32x2){yA, yB};
	ds_write_b64 v228, v[226:227] offset:4032
	v_add_f32_dpp v220, v220, v220 quad_perm:[1,0,3,2] row_mask:0xf bank_mask:0xf bound_ctrl:1
	v_add_f32_dpp v221, v221, v221 quad_perm:[1,0,3,2] row_mask:0xf bank_mask:0xf bound_ctrl:1
	v_pk_fma_f32 v[198:199], v[126:127], v[112:113], v[198:199] op_sel_hi:[0,1,1]
	v_pk_fma_f32 v[206:207], v[126:127], v[112:113], v[206:207] op_sel:[1,0,0] op_sel_hi:[1,1,1]
	v_add_f32_dpp v220, v220, v220 quad_perm:[2,3,0,1] row_mask:0xf bank_mask:0xf bound_ctrl:1
	v_add_f32_dpp v221, v221, v221 quad_perm:[2,3,0,1] row_mask:0xf bank_mask:0xf bound_ctrl:1
	v_pk_fma_f32 v[200:201], v[126:127], v[114:115], v[200:201] op_sel_hi:[0,1,1]
	v_pk_fma_f32 v[208:209], v[126:127], v[114:115], v[208:209] op_sel:[1,0,0] op_sel_hi:[1,1,1]
	v_add_f32_dpp v220, v220, v220 row_half_mirror row_mask:0xf bank_mask:0xf bound_ctrl:1
	v_add_f32_dpp v221, v221, v221 row_half_mirror row_mask:0xf bank_mask:0xf bound_ctrl:1
	v_pk_fma_f32 v[202:203], v[126:127], v[116:117], v[202:203] op_sel_hi:[0,1,1]
	v_pk_fma_f32 v[210:211], v[126:127], v[116:117], v[210:211] op_sel:[1,0,0] op_sel_hi:[1,1,1]
	v_pk_fma_f32 v[22:23], v[220:221], v[102:103], v[196:197] op_sel_hi:[0,1,1] neg_lo:[1,0,0] neg_hi:[1,0,0]
	v_pk_fma_f32 v[14:15], v[220:221], v[102:103], v[204:205] op_sel:[1,0,0] op_sel_hi:[1,1,1] neg_lo:[1,0,0] neg_hi:[1,0,0]
	v_pk_fma_f32 v[24:25], v[220:221], v[104:105], v[198:199] op_sel_hi:[0,1,1] neg_lo:[1,0,0] neg_hi:[1,0,0]
	v_pk_fma_f32 v[16:17], v[220:221], v[104:105], v[206:207] op_sel:[1,0,0] op_sel_hi:[1,1,1] neg_lo:[1,0,0] neg_hi:[1,0,0]
	v_pk_fma_f32 v[18:19], v[220:221], v[106:107], v[200:201] op_sel_hi:[0,1,1] neg_lo:[1,0,0] neg_hi:[1,0,0]
	v_pk_fma_f32 v[10:11], v[220:221], v[106:107], v[208:209] op_sel:[1,0,0] op_sel_hi:[1,1,1] neg_lo:[1,0,0] neg_hi:[1,0,0]
	v_pk_fma_f32 v[20:21], v[220:221], v[108:109], v[202:203] op_sel_hi:[0,1,1] neg_lo:[1,0,0] neg_hi:[1,0,0]
	v_pk_fma_f32 v[12:13], v[220:221], v[108:109], v[210:211] op_sel:[1,0,0] op_sel_hi:[1,1,1] neg_lo:[1,0,0] neg_hi:[1,0,0]
	v_pk_mul_f32 v[222:223], v[22:23], v[118:119]
	v_pk_mul_f32 v[224:225], v[14:15], v[118:119]
	v_pk_fma_f32 v[222:223], v[24:25], v[120:121], v[222:223]
	v_pk_fma_f32 v[224:225], v[16:17], v[120:121], v[224:225]
	v_pk_fma_f32 v[222:223], v[18:19], v[122:123], v[222:223]
	v_pk_fma_f32 v[224:225], v[10:11], v[122:123], v[224:225]
	v_pk_fma_f32 v[222:223], v[20:21], v[124:125], v[222:223]
	v_pk_fma_f32 v[224:225], v[12:13], v[124:125], v[224:225]
	s_waitcnt lgkmcnt(0)
	ds_read_b128 v[86:89], v84 offset:2560
	ds_read_b128 v[90:93], v84 offset:2576
	ds_read_b128 v[94:97], v84 offset:6656
	ds_read_b128 v[98:101], v84 offset:6672
	ds_read_b128 v[102:105], v84 offset:10752
	ds_read_b128 v[106:109], v84 offset:10768
	ds_read_b128 v[110:113], v84 offset:14848
	ds_read_b128 v[114:117], v84 offset:14864
	ds_read_b128 v[118:121], v84 offset:18944
	ds_read_b128 v[122:125], v84 offset:18960
	ds_read_b64 v[126:127], v85 offset:23040
	v_pk_mul_f32 v[212:213], v[22:23], v[136:137]
	v_pk_mul_f32 v[216:217], v[14:15], v[136:137]
	v_pk_mul_f32 v[196:197], v[22:23], v[128:129]
	v_pk_mul_f32 v[204:205], v[14:15], v[128:129]
	v_pk_fma_f32 v[212:213], v[24:25], v[138:139], v[212:213]
	v_pk_fma_f32 v[216:217], v[16:17], v[138:139], v[216:217]
	v_pk_mul_f32 v[198:199], v[24:25], v[130:131]
	v_pk_mul_f32 v[206:207], v[16:17], v[130:131]
	v_pk_fma_f32 v[212:213], v[18:19], v[140:141], v[212:213]
	v_pk_fma_f32 v[216:217], v[10:11], v[140:141], v[216:217]
	v_pk_mul_f32 v[200:201], v[18:19], v[132:133]
	v_pk_mul_f32 v[208:209], v[10:11], v[132:133]
	v_pk_fma_f32 v[212:213], v[20:21], v[142:143], v[212:213]
	v_pk_fma_f32 v[216:217], v[12:13], v[142:143], v[216:217]
	v_pk_mul_f32 v[202:203], v[20:21], v[134:135]
	v_pk_mul_f32 v[210:211], v[12:13], v[134:135]
	v_add_f32_e32 v226, v222, v223
	v_add_f32_e32 v227, v224, v225
	v_add_f32_e32 v220, v212, v213
	v_add_f32_e32 v221, v216, v217
	v_pk_fma_f32 v[196:197], v[168:169], v[152:153], v[196:197] op_sel_hi:[0,1,1]
	v_pk_fma_f32 v[204:205], v[168:169], v[152:153], v[204:205] op_sel:[1,0,0] op_sel_hi:[1,1,1]
	ds_write_b64 v228, v[226:227] offset:4608
	v_add_f32_dpp v220, v220, v220 quad_perm:[1,0,3,2] row_mask:0xf bank_mask:0xf bound_ctrl:1
	v_add_f32_dpp v221, v221, v221 quad_perm:[1,0,3,2] row_mask:0xf bank_mask:0xf bound_ctrl:1
	v_pk_fma_f32 v[198:199], v[168:169], v[154:155], v[198:199] op_sel_hi:[0,1,1]
	v_pk_fma_f32 v[206:207], v[168:169], v[154:155], v[206:207] op_sel:[1,0,0] op_sel_hi:[1,1,1]
	v_add_f32_dpp v220, v220, v220 quad_perm:[2,3,0,1] row_mask:0xf bank_mask:0xf bound_ctrl:1
	v_add_f32_dpp v221, v221, v221 quad_perm:[2,3,0,1] row_mask:0xf bank_mask:0xf bound_ctrl:1
	v_pk_fma_f32 v[200:201], v[168:169], v[156:157], v[200:201] op_sel_hi:[0,1,1]
	v_pk_fma_f32 v[208:209], v[168:169], v[156:157], v[208:209] op_sel:[1,0,0] op_sel_hi:[1,1,1]
	v_add_f32_dpp v220, v220, v220 row_half_mirror row_mask:0xf bank_mask:0xf bound_ctrl:1
	v_add_f32_dpp v221, v221, v221 row_half_mirror row_mask:0xf bank_mask:0xf bound_ctrl:1
	v_pk_fma_f32 v[202:203], v[168:169], v[158:159], v[202:203] op_sel_hi:[0,1,1]
	v_pk_fma_f32 v[210:211], v[168:169], v[158:159], v[210:211] op_sel:[1,0,0] op_sel_hi:[1,1,1]
	v_pk_fma_f32 v[22:23], v[220:221], v[144:145], v[196:197] op_sel_hi:[0,1,1] neg_lo:[1,0,0] neg_hi:[1,0,0]
	v_pk_fma_f32 v[14:15], v[220:221], v[144:145], v[204:205] op_sel:[1,0,0] op_sel_hi:[1,1,1] neg_lo:[1,0,0] neg_hi:[1,0,0]
	v_pk_fma_f32 v[24:25], v[220:221], v[146:147], v[198:199] op_sel_hi:[0,1,1] neg_lo:[1,0,0] neg_hi:[1,0,0]
	v_pk_fma_f32 v[16:17], v[220:221], v[146:147], v[206:207] op_sel:[1,0,0] op_sel_hi:[1,1,1] neg_lo:[1,0,0] neg_hi:[1,0,0]
	v_pk_fma_f32 v[18:19], v[220:221], v[148:149], v[200:201] op_sel_hi:[0,1,1] neg_lo:[1,0,0] neg_hi:[1,0,0]
	v_pk_fma_f32 v[10:11], v[220:221], v[148:149], v[208:209] op_sel:[1,0,0] op_sel_hi:[1,1,1] neg_lo:[1,0,0] neg_hi:[1,0,0]
	v_pk_fma_f32 v[20:21], v[220:221], v[150:151], v[202:203] op_sel_hi:[0,1,1] neg_lo:[1,0,0] neg_hi:[1,0,0]
	v_pk_fma_f32 v[12:13], v[220:221], v[150:151], v[210:211] op_sel:[1,0,0] op_sel_hi:[1,1,1] neg_lo:[1,0,0] neg_hi:[1,0,0]
	v_pk_mul_f32 v[222:223], v[22:23], v[160:161]
	v_pk_mul_f32 v[224:225], v[14:15], v[160:161]
	v_pk_fma_f32 v[222:223], v[24:25], v[162:163], v[222:223]
	v_pk_fma_f32 v[224:225], v[16:17], v[162:163], v[224:225]
	v_pk_fma_f32 v[222:223], v[18:19], v[164:165], v[222:223]
	v_pk_fma_f32 v[224:225], v[10:11], v[164:165], v[224:225]
	v_pk_fma_f32 v[222:223], v[20:21], v[166:167], v[222:223]
	v_pk_fma_f32 v[224:225], v[12:13], v[166:167], v[224:225]
	s_waitcnt lgkmcnt(0)
; __device__ __forceinline__ void scan_rows(f32x2 (&X)[8], const ScanOps& o, const f32x4 (&b)[2], const f32x4 (&kd)[2], const f32x4 (&r)[2], const bool use_v, float& yA, float& yB) {
;     f32x2 aA = X[0] * o.kk[0].xy, aB = X[4] * o.kk[0].xy;
;     aA += X[1] * o.kk[0].zw; aB += X[5] * o.kk[0].zw;
;     aA += X[2] * o.kk[1].xy; aB += X[6] * o.kk[1].xy;
;     aA += X[3] * o.kk[1].zw; aB += X[7] * o.kk[1].zw;
;     const float saA = sum8(aA.x + aA.y), saB = sum8(aB.x + aB.y);
;     const f32x2 nA = (f32x2){-saA, -saA}, nB = (f32x2){-saB, -saB}, vA = (f32x2){o.v.x, o.v.x}, vB = (f32x2){o.v.y, o.v.y};
;     f32x2 tA, tB, accA, accB;
;     tA = X[0] * o.w[0].xy; tA += nA * b[0].xy; if (use_v) tA += vA * kd[0].xy; X[0] = tA; accA = tA * r[0].xy;
;     tB = X[4] * o.w[0].xy; tB += nB * b[0].xy; if (use_v) tB += vB * kd[0].xy; X[4] = tB; accB = tB * r[0].xy;
;     tA = X[1] * o.w[0].zw; tA += nA * b[0].zw; if (use_v) tA += vA * kd[0].zw; X[1] = tA; accA += tA * r[0].zw;
;     tB = X[5] * o.w[0].zw; tB += nB * b[0].zw; if (use_v) tB += vB * kd[0].zw; X[5] = tB; accB += tB * r[0].zw;
;     tA = X[2] * o.w[1].xy; tA += nA * b[1].xy; if (use_v) tA += vA * kd[1].xy; X[2] = tA; accA += tA * r[1].xy;
;     tB = X[6] * o.w[1].xy; tB += nB * b[1].xy; if (use_v) tB += vB * kd[1].xy; X[6] = tB; accB += tB * r[1].xy;
;     tA = X[3] * o.w[1].zw; tA += nA * b[1].zw; if (use_v) tA += vA * kd[1].zw; X[3] = tA; accA += tA * r[1].zw;
;     tB = X[7] * o.w[1].zw; tB += nB * b[1].zw; if (use_v) tB += vB * kd[1].zw; X[7] = tB; accB += tB * r[1].zw;
;     yA = sum8(accA.x + accA.y); yB = sum8(accB.x + accB.y);
; __device__ void phase_scan(int c, const bf16_t* PROJ, const float* k_k, const bf16_t* Wd, const bf16_t* Bd, const float* k_a, bf16_t* Y, bf16_t* Q, float* FS, float* sm) {
;     ...
;                 for (int i = 0; i < 16; i += 2) {
;                     float yA = 0.f, yB = 0.f;
;                     scan_ld(ob, obv, i + 1, B);
;                     if (roleP) A.v = (f32x2){0.f, 0.f};
;                     scan_step1(X, A, ob + i * 64, yA, yB);
;                     *(f32x2*)(obw + i * 16 + 2 * vp) = (f32x2){yA, yB};
;                     if (i + 2 < 16) scan_ld(ob, obv, i + 2, A);
;                     if (roleP) B.v = (f32x2){0.f, 0.f};
;                     scan_step1(X, B, ob + (i + 1) * 64, yA, yB);
;                     *(f32x2*)(obw + (i + 1) * 16 + 2 * vp) = (f32x2){yA, yB};
	ds_read_b128 v[128:131], v84 offset:2816
	ds_read_b128 v[132:135], v84 offset:2832
	ds_read_b128 v[136:139], v84 offset:6912
	ds_read_b128 v[140:143], v84 offset:6928
	ds_read_b128 v[144:147], v84 offset:11008
	ds_read_b128 v[148:151], v84 offset:11024
	ds_read_b128 v[152:155], v84 offset:15104
	ds_read_b128 v[156:159], v84 offset:15120
	ds_read_b128 v[160:163], v84 offset:19200
	ds_read_b128 v[164:167], v84 offset:19216
	ds_read_b64 v[168:169], v85 offset:23296
	v_pk_mul_f32 v[212:213], v[22:23], v[94:95]
	v_pk_mul_f32 v[216:217], v[14:15], v[94:95]
	v_pk_mul_f32 v[196:197], v[22:23], v[86:87]
	v_pk_mul_f32 v[204:205], v[14:15], v[86:87]
	v_pk_fma_f32 v[212:213], v[24:25], v[96:97], v[212:213]
	v_pk_fma_f32 v[216:217], v[16:17], v[96:97], v[216:217]
	v_pk_mul_f32 v[198:199], v[24:25], v[88:89]
	v_pk_mul_f32 v[206:207], v[16:17], v[88:89]
	v_pk_fma_f32 v[212:213], v[18:19], v[98:99], v[212:213]
	v_pk_fma_f32 v[216:217], v[10:11], v[98:99], v[216:217]
	v_pk_mul_f32 v[200:201], v[18:19], v[90:91]
	v_pk_mul_f32 v[208:209], v[10:11], v[90:91]
	v_pk_fma_f32 v[212:213], v[20:21], v[100:101], v[212:213]
	v_pk_fma_f32 v[216:217], v[12:13], v[100:101], v[216:217]
	v_pk_mul_f32 v[202:203], v[20:21], v[92:93]
	v_pk_mul_f32 v[210:211], v[12:13], v[92:93]
	v_add_f32_e32 v226, v222, v223
	v_add_f32_e32 v227, v224, v225
	v_add_f32_e32 v220, v212, v213
	v_add_f32_e32 v221, v216, v217
	v_pk_fma_f32 v[196:197], v[126:127], v[110:111], v[196:197] op_sel_hi:[0,1,1]
	v_pk_fma_f32 v[204:205], v[126:127], v[110:111], v[204:205] op_sel:[1,0,0] op_sel_hi:[1,1,1]
	ds_write_b64 v228, v[226:227] offset:5184
	v_add_f32_dpp v220, v220, v220 quad_perm:[1,0,3,2] row_mask:0xf bank_mask:0xf bound_ctrl:1
	v_add_f32_dpp v221, v221, v221 quad_perm:[1,0,3,2] row_mask:0xf bank_mask:0xf bound_ctrl:1
	v_pk_fma_f32 v[198:199], v[126:127], v[112:113], v[198:199] op_sel_hi:[0,1,1]
	v_pk_fma_f32 v[206:207], v[126:127], v[112:113], v[206:207] op_sel:[1,0,0] op_sel_hi:[1,1,1]
	v_add_f32_dpp v220, v220, v220 quad_perm:[2,3,0,1] row_mask:0xf bank_mask:0xf bound_ctrl:1
	v_add_f32_dpp v221, v221, v221 quad_perm:[2,3,0,1] row_mask:0xf bank_mask:0xf bound_ctrl:1
	v_pk_fma_f32 v[200:201], v[126:127], v[114:115], v[200:201] op_sel_hi:[0,1,1]
	v_pk_fma_f32 v[208:209], v[126:127], v[114:115], v[208:209] op_sel:[1,0,0] op_sel_hi:[1,1,1]
	v_add_f32_dpp v220, v220, v220 row_half_mirror row_mask:0xf bank_mask:0xf bound_ctrl:1
	v_add_f32_dpp v221, v221, v221 row_half_mirror row_mask:0xf bank_mask:0xf bound_ctrl:1
	v_pk_fma_f32 v[202:203], v[126:127], v[116:117], v[202:203] op_sel_hi:[0,1,1]
	v_pk_fma_f32 v[210:211], v[126:127], v[116:117], v[210:211] op_sel:[1,0,0] op_sel_hi:[1,1,1]
	v_pk_fma_f32 v[22:23], v[220:221], v[102:103], v[196:197] op_sel_hi:[0,1,1] neg_lo:[1,0,0] neg_hi:[1,0,0]
	v_pk_fma_f32 v[14:15], v[220:221], v[102:103], v[204:205] op_sel:[1,0,0] op_sel_hi:[1,1,1] neg_lo:[1,0,0] neg_hi:[1,0,0]
	v_pk_fma_f32 v[24:25], v[220:221], v[104:105], v[198:199] op_sel_hi:[0,1,1] neg_lo:[1,0,0] neg_hi:[1,0,0]
	v_pk_fma_f32 v[16:17], v[220:221], v[104:105], v[206:207] op_sel:[1,0,0] op_sel_hi:[1,1,1] neg_lo:[1,0,0] neg_hi:[1,0,0]
	v_pk_fma_f32 v[18:19], v[220:221], v[106:107], v[200:201] op_sel_hi:[0,1,1] neg_lo:[1,0,0] neg_hi:[1,0,0]
	v_pk_fma_f32 v[10:11], v[220:221], v[106:107], v[208:209] op_sel:[1,0,0] op_sel_hi:[1,1,1] neg_lo:[1,0,0] neg_hi:[1,0,0]
	v_pk_fma_f32 v[20:21], v[220:221], v[108:109], v[202:203] op_sel_hi:[0,1,1] neg_lo:[1,0,0] neg_hi:[1,0,0]
	v_pk_fma_f32 v[12:13], v[220:221], v[108:109], v[210:211] op_sel:[1,0,0] op_sel_hi:[1,1,1] neg_lo:[1,0,0] neg_hi:[1,0,0]
	v_pk_mul_f32 v[222:223], v[22:23], v[118:119]
	v_pk_mul_f32 v[224:225], v[14:15], v[118:119]
	v_pk_fma_f32 v[222:223], v[24:25], v[120:121], v[222:223]
	v_pk_fma_f32 v[224:225], v[16:17], v[120:121], v[224:225]
	v_pk_fma_f32 v[222:223], v[18:19], v[122:123], v[222:223]
	v_pk_fma_f32 v[224:225], v[10:11], v[122:123], v[224:225]
	v_pk_fma_f32 v[222:223], v[20:21], v[124:125], v[222:223]
	v_pk_fma_f32 v[224:225], v[12:13], v[124:125], v[224:225]
	s_waitcnt lgkmcnt(0)
	ds_read_b128 v[86:89], v84 offset:3072
	ds_read_b128 v[90:93], v84 offset:3088
	ds_read_b128 v[94:97], v84 offset:7168
	ds_read_b128 v[98:101], v84 offset:7184
	ds_read_b128 v[102:105], v84 offset:11264
	ds_read_b128 v[106:109], v84 offset:11280
	ds_read_b128 v[110:113], v84 offset:15360
	ds_read_b128 v[114:117], v84 offset:15376
	ds_read_b128 v[118:121], v84 offset:19456
	ds_read_b128 v[122:125], v84 offset:19472
	ds_read_b64 v[126:127], v85 offset:23552
	v_pk_mul_f32 v[212:213], v[22:23], v[136:137]
	v_pk_mul_f32 v[216:217], v[14:15], v[136:137]
	v_pk_mul_f32 v[196:197], v[22:23], v[128:129]
	v_pk_mul_f32 v[204:205], v[14:15], v[128:129]
	v_pk_fma_f32 v[212:213], v[24:25], v[138:139], v[212:213]
	v_pk_fma_f32 v[216:217], v[16:17], v[138:139], v[216:217]
	v_pk_mul_f32 v[198:199], v[24:25], v[130:131]
	v_pk_mul_f32 v[206:207], v[16:17], v[130:131]
	v_pk_fma_f32 v[212:213], v[18:19], v[140:141], v[212:213]
	v_pk_fma_f32 v[216:217], v[10:11], v[140:141], v[216:217]
	v_pk_mul_f32 v[200:201], v[18:19], v[132:133]
	v_pk_mul_f32 v[208:209], v[10:11], v[132:133]
	v_pk_fma_f32 v[212:213], v[20:21], v[142:143], v[212:213]
	v_pk_fma_f32 v[216:217], v[12:13], v[142:143], v[216:217]
	v_pk_mul_f32 v[202:203], v[20:21], v[134:135]
	v_pk_mul_f32 v[210:211], v[12:13], v[134:135]
	v_add_f32_e32 v226, v222, v223
	v_add_f32_e32 v227, v224, v225
	v_add_f32_e32 v220, v212, v213
	v_add_f32_e32 v221, v216, v217
	v_pk_fma_f32 v[196:197], v[168:169], v[152:153], v[196:197] op_sel_hi:[0,1,1]
	v_pk_fma_f32 v[204:205], v[168:169], v[152:153], v[204:205] op_sel:[1,0,0] op_sel_hi:[1,1,1]
; __device__ __forceinline__ void scan_rows(f32x2 (&X)[8], const ScanOps& o, const f32x4 (&b)[2], const f32x4 (&kd)[2], const f32x4 (&r)[2], const bool use_v, float& yA, float& yB) {
;     f32x2 aA = X[0] * o.kk[0].xy, aB = X[4] * o.kk[0].xy;
;     aA += X[1] * o.kk[0].zw; aB += X[5] * o.kk[0].zw;
;     aA += X[2] * o.kk[1].xy; aB += X[6] * o.kk[1].xy;
;     aA += X[3] * o.kk[1].zw; aB += X[7] * o.kk[1].zw;
;     const float saA = sum8(aA.x + aA.y), saB = sum8(aB.x + aB.y);
;     const f32x2 nA = (f32x2){-saA, -saA}, nB = (f32x2){-saB, -saB}, vA = (f32x2){o.v.x, o.v.x}, vB = (f32x2){o.v.y, o.v.y};
;     f32x2 tA, tB, accA, accB;
;     tA = X[0] * o.w[0].xy; tA += nA * b[0].xy; if (use_v) tA += vA * kd[0].xy; X[0] = tA; accA = tA * r[0].xy;
;     tB = X[4] * o.w[0].xy; tB += nB * b[0].xy; if (use_v) tB += vB * kd[0].xy; X[4] = tB; accB = tB * r[0].xy;
;     tA = X[1] * o.w[0].zw; tA += nA * b[0].zw; if (use_v) tA += vA * kd[0].zw; X[1] = tA; accA += tA * r[0].zw;
;     tB = X[5] * o.w[0].zw; tB += nB * b[0].zw; if (use_v) tB += vB * kd[0].zw; X[5] = tB; accB += tB * r[0].zw;
;     tA = X[2] * o.w[1].xy; tA += nA * b[1].xy; if (use_v) tA += vA * kd[1].xy; X[2] = tA; accA += tA * r[1].xy;
;     tB = X[6] * o.w[1].xy; tB += nB * b[1].xy; if (use_v) tB += vB * kd[1].xy; X[6] = tB; accB += tB * r[1].xy;
;     tA = X[3] * o.w[1].zw; tA += nA * b[1].zw; if (use_v) tA += vA * kd[1].zw; X[3] = tA; accA += tA * r[1].zw;
;     tB = X[7] * o.w[1].zw; tB += nB * b[1].zw; if (use_v) tB += vB * kd[1].zw; X[7] = tB; accB += tB * r[1].zw;
;     yA = sum8(accA.x + accA.y); yB = sum8(accB.x + accB.y);
; __device__ void phase_scan(int c, const bf16_t* PROJ, const float* k_k, const bf16_t* Wd, const bf16_t* Bd, const float* k_a, bf16_t* Y, bf16_t* Q, float* FS, float* sm) {
;     ...
;                 for (int i = 0; i < 16; i += 2) {
;                     float yA = 0.f, yB = 0.f;
;                     scan_ld(ob, obv, i + 1, B);
;                     if (roleP) A.v = (f32x2){0.f, 0.f};
;                     scan_step1(X, A, ob + i * 64, yA, yB);
;                     *(f32x2*)(obw + i * 16 + 2 * vp) = (f32x2){yA, yB};
;                     if (i + 2 < 16) scan_ld(ob, obv, i + 2, A);
;                     if (roleP) B.v = (f32x2){0.f, 0.f};
;                     scan_step1(X, B, ob + (i + 1) * 64, yA, yB);
;                     *(f32x2*)(obw + (i + 1) * 16 + 2 * vp) = (f32x2){yA, yB};
	ds_write_b64 v228, v[226:227] offset:5760
	v_add_f32_dpp v220, v220, v220 quad_perm:[1,0,3,2] row_mask:0xf bank_mask:0xf bound_ctrl:1
	v_add_f32_dpp v221, v221, v221 quad_perm:[1,0,3,2] row_mask:0xf bank_mask:0xf bound_ctrl:1
	v_pk_fma_f32 v[198:199], v[168:169], v[154:155], v[198:199] op_sel_hi:[0,1,1]
	v_pk_fma_f32 v[206:207], v[168:169], v[154:155], v[206:207] op_sel:[1,0,0] op_sel_hi:[1,1,1]
	v_add_f32_dpp v220, v220, v220 quad_perm:[2,3,0,1] row_mask:0xf bank_mask:0xf bound_ctrl:1
	v_add_f32_dpp v221, v221, v221 quad_perm:[2,3,0,1] row_mask:0xf bank_mask:0xf bound_ctrl:1
	v_pk_fma_f32 v[200:201], v[168:169], v[156:157], v[200:201] op_sel_hi:[0,1,1]
	v_pk_fma_f32 v[208:209], v[168:169], v[156:157], v[208:209] op_sel:[1,0,0] op_sel_hi:[1,1,1]
	v_add_f32_dpp v220, v220, v220 row_half_mirror row_mask:0xf bank_mask:0xf bound_ctrl:1
	v_add_f32_dpp v221, v221, v221 row_half_mirror row_mask:0xf bank_mask:0xf bound_ctrl:1
	v_pk_fma_f32 v[202:203], v[168:169], v[158:159], v[202:203] op_sel_hi:[0,1,1]
	v_pk_fma_f32 v[210:211], v[168:169], v[158:159], v[210:211] op_sel:[1,0,0] op_sel_hi:[1,1,1]
	v_pk_fma_f32 v[22:23], v[220:221], v[144:145], v[196:197] op_sel_hi:[0,1,1] neg_lo:[1,0,0] neg_hi:[1,0,0]
	v_pk_fma_f32 v[14:15], v[220:221], v[144:145], v[204:205] op_sel:[1,0,0] op_sel_hi:[1,1,1] neg_lo:[1,0,0] neg_hi:[1,0,0]
	v_pk_fma_f32 v[24:25], v[220:221], v[146:147], v[198:199] op_sel_hi:[0,1,1] neg_lo:[1,0,0] neg_hi:[1,0,0]
	v_pk_fma_f32 v[16:17], v[220:221], v[146:147], v[206:207] op_sel:[1,0,0] op_sel_hi:[1,1,1] neg_lo:[1,0,0] neg_hi:[1,0,0]
	v_pk_fma_f32 v[18:19], v[220:221], v[148:149], v[200:201] op_sel_hi:[0,1,1] neg_lo:[1,0,0] neg_hi:[1,0,0]
	v_pk_fma_f32 v[10:11], v[220:221], v[148:149], v[208:209] op_sel:[1,0,0] op_sel_hi:[1,1,1] neg_lo:[1,0,0] neg_hi:[1,0,0]
	v_pk_fma_f32 v[20:21], v[220:221], v[150:151], v[202:203] op_sel_hi:[0,1,1] neg_lo:[1,0,0] neg_hi:[1,0,0]
	v_pk_fma_f32 v[12:13], v[220:221], v[150:151], v[210:211] op_sel:[1,0,0] op_sel_hi:[1,1,1] neg_lo:[1,0,0] neg_hi:[1,0,0]
	v_pk_mul_f32 v[222:223], v[22:23], v[160:161]
	v_pk_mul_f32 v[224:225], v[14:15], v[160:161]
	v_pk_fma_f32 v[222:223], v[24:25], v[162:163], v[222:223]
	v_pk_fma_f32 v[224:225], v[16:17], v[162:163], v[224:225]
	v_pk_fma_f32 v[222:223], v[18:19], v[164:165], v[222:223]
	v_pk_fma_f32 v[224:225], v[10:11], v[164:165], v[224:225]
	v_pk_fma_f32 v[222:223], v[20:21], v[166:167], v[222:223]
	v_pk_fma_f32 v[224:225], v[12:13], v[166:167], v[224:225]
	s_waitcnt lgkmcnt(0)
	ds_read_b128 v[128:131], v84 offset:3328
	ds_read_b128 v[132:135], v84 offset:3344
	ds_read_b128 v[136:139], v84 offset:7424
	ds_read_b128 v[140:143], v84 offset:7440
	ds_read_b128 v[144:147], v84 offset:11520
	ds_read_b128 v[148:151], v84 offset:11536
	ds_read_b128 v[152:155], v84 offset:15616
	ds_read_b128 v[156:159], v84 offset:15632
	ds_read_b128 v[160:163], v84 offset:19712
	ds_read_b128 v[164:167], v84 offset:19728
	ds_read_b64 v[168:169], v85 offset:23808
	v_pk_mul_f32 v[212:213], v[22:23], v[94:95]
	v_pk_mul_f32 v[216:217], v[14:15], v[94:95]
	v_pk_mul_f32 v[196:197], v[22:23], v[86:87]
	v_pk_mul_f32 v[204:205], v[14:15], v[86:87]
	v_pk_fma_f32 v[212:213], v[24:25], v[96:97], v[212:213]
	v_pk_fma_f32 v[216:217], v[16:17], v[96:97], v[216:217]
	v_pk_mul_f32 v[198:199], v[24:25], v[88:89]
	v_pk_mul_f32 v[206:207], v[16:17], v[88:89]
	v_pk_fma_f32 v[212:213], v[18:19], v[98:99], v[212:213]
	v_pk_fma_f32 v[216:217], v[10:11], v[98:99], v[216:217]
	v_pk_mul_f32 v[200:201], v[18:19], v[90:91]
	v_pk_mul_f32 v[208:209], v[10:11], v[90:91]
	v_pk_fma_f32 v[212:213], v[20:21], v[100:101], v[212:213]
	v_pk_fma_f32 v[216:217], v[12:13], v[100:101], v[216:217]
	v_pk_mul_f32 v[202:203], v[20:21], v[92:93]
	v_pk_mul_f32 v[210:211], v[12:13], v[92:93]
	v_add_f32_e32 v226, v222, v223
	v_add_f32_e32 v227, v224, v225
	v_add_f32_e32 v220, v212, v213
	v_add_f32_e32 v221, v216, v217
	v_pk_fma_f32 v[196:197], v[126:127], v[110:111], v[196:197] op_sel_hi:[0,1,1]
	v_pk_fma_f32 v[204:205], v[126:127], v[110:111], v[204:205] op_sel:[1,0,0] op_sel_hi:[1,1,1]
	ds_write_b64 v228, v[226:227] offset:6336
	v_add_f32_dpp v220, v220, v220 quad_perm:[1,0,3,2] row_mask:0xf bank_mask:0xf bound_ctrl:1
	v_add_f32_dpp v221, v221, v221 quad_perm:[1,0,3,2] row_mask:0xf bank_mask:0xf bound_ctrl:1
	v_pk_fma_f32 v[198:199], v[126:127], v[112:113], v[198:199] op_sel_hi:[0,1,1]
	v_pk_fma_f32 v[206:207], v[126:127], v[112:113], v[206:207] op_sel:[1,0,0] op_sel_hi:[1,1,1]
	v_add_f32_dpp v220, v220, v220 quad_perm:[2,3,0,1] row_mask:0xf bank_mask:0xf bound_ctrl:1
	v_add_f32_dpp v221, v221, v221 quad_perm:[2,3,0,1] row_mask:0xf bank_mask:0xf bound_ctrl:1
	v_pk_fma_f32 v[200:201], v[126:127], v[114:115], v[200:201] op_sel_hi:[0,1,1]
	v_pk_fma_f32 v[208:209], v[126:127], v[114:115], v[208:209] op_sel:[1,0,0] op_sel_hi:[1,1,1]
	v_add_f32_dpp v220, v220, v220 row_half_mirror row_mask:0xf bank_mask:0xf bound_ctrl:1
	v_add_f32_dpp v221, v221, v221 row_half_mirror row_mask:0xf bank_mask:0xf bound_ctrl:1
	v_pk_fma_f32 v[202:203], v[126:127], v[116:117], v[202:203] op_sel_hi:[0,1,1]
	v_pk_fma_f32 v[210:211], v[126:127], v[116:117], v[210:211] op_sel:[1,0,0] op_sel_hi:[1,1,1]
	v_pk_fma_f32 v[22:23], v[220:221], v[102:103], v[196:197] op_sel_hi:[0,1,1] neg_lo:[1,0,0] neg_hi:[1,0,0]
	v_pk_fma_f32 v[14:15], v[220:221], v[102:103], v[204:205] op_sel:[1,0,0] op_sel_hi:[1,1,1] neg_lo:[1,0,0] neg_hi:[1,0,0]
	v_pk_fma_f32 v[24:25], v[220:221], v[104:105], v[198:199] op_sel_hi:[0,1,1] neg_lo:[1,0,0] neg_hi:[1,0,0]
	v_pk_fma_f32 v[16:17], v[220:221], v[104:105], v[206:207] op_sel:[1,0,0] op_sel_hi:[1,1,1] neg_lo:[1,0,0] neg_hi:[1,0,0]
	v_pk_fma_f32 v[18:19], v[220:221], v[106:107], v[200:201] op_sel_hi:[0,1,1] neg_lo:[1,0,0] neg_hi:[1,0,0]
	v_pk_fma_f32 v[10:11], v[220:221], v[106:107], v[208:209] op_sel:[1,0,0] op_sel_hi:[1,1,1] neg_lo:[1,0,0] neg_hi:[1,0,0]
	v_pk_fma_f32 v[20:21], v[220:221], v[108:109], v[202:203] op_sel_hi:[0,1,1] neg_lo:[1,0,0] neg_hi:[1,0,0]
	v_pk_fma_f32 v[12:13], v[220:221], v[108:109], v[210:211] op_sel:[1,0,0] op_sel_hi:[1,1,1] neg_lo:[1,0,0] neg_hi:[1,0,0]
	v_pk_mul_f32 v[222:223], v[22:23], v[118:119]
	v_pk_mul_f32 v[224:225], v[14:15], v[118:119]
	v_pk_fma_f32 v[222:223], v[24:25], v[120:121], v[222:223]
	v_pk_fma_f32 v[224:225], v[16:17], v[120:121], v[224:225]
	v_pk_fma_f32 v[222:223], v[18:19], v[122:123], v[222:223]
	v_pk_fma_f32 v[224:225], v[10:11], v[122:123], v[224:225]
	v_pk_fma_f32 v[222:223], v[20:21], v[124:125], v[222:223]
	v_pk_fma_f32 v[224:225], v[12:13], v[124:125], v[224:225]
	s_waitcnt lgkmcnt(0)
; __device__ __forceinline__ void scan_rows(f32x2 (&X)[8], const ScanOps& o, const f32x4 (&b)[2], const f32x4 (&kd)[2], const f32x4 (&r)[2], const bool use_v, float& yA, float& yB) {
;     f32x2 aA = X[0] * o.kk[0].xy, aB = X[4] * o.kk[0].xy;
;     aA += X[1] * o.kk[0].zw; aB += X[5] * o.kk[0].zw;
;     aA += X[2] * o.kk[1].xy; aB += X[6] * o.kk[1].xy;
;     aA += X[3] * o.kk[1].zw; aB += X[7] * o.kk[1].zw;
;     const float saA = sum8(aA.x + aA.y), saB = sum8(aB.x + aB.y);
;     const f32x2 nA = (f32x2){-saA, -saA}, nB = (f32x2){-saB, -saB}, vA = (f32x2){o.v.x, o.v.x}, vB = (f32x2){o.v.y, o.v.y};
;     f32x2 tA, tB, accA, accB;
;     tA = X[0] * o.w[0].xy; tA += nA * b[0].xy; if (use_v) tA += vA * kd[0].xy; X[0] = tA; accA = tA * r[0].xy;
;     tB = X[4] * o.w[0].xy; tB += nB * b[0].xy; if (use_v) tB += vB * kd[0].xy; X[4] = tB; accB = tB * r[0].xy;
;     tA = X[1] * o.w[0].zw; tA += nA * b[0].zw; if (use_v) tA += vA * kd[0].zw; X[1] = tA; accA += tA * r[0].zw;
;     tB = X[5] * o.w[0].zw; tB += nB * b[0].zw; if (use_v) tB += vB * kd[0].zw; X[5] = tB; accB += tB * r[0].zw;
;     tA = X[2] * o.w[1].xy; tA += nA * b[1].xy; if (use_v) tA += vA * kd[1].xy; X[2] = tA; accA += tA * r[1].xy;
;     tB = X[6] * o.w[1].xy; tB += nB * b[1].xy; if (use_v) tB += vB * kd[1].xy; X[6] = tB; accB += tB * r[1].xy;
;     tA = X[3] * o.w[1].zw; tA += nA * b[1].zw; if (use_v) tA += vA * kd[1].zw; X[3] = tA; accA += tA * r[1].zw;
;     tB = X[7] * o.w[1].zw; tB += nB * b[1].zw; if (use_v) tB += vB * kd[1].zw; X[7] = tB; accB += tB * r[1].zw;
;     yA = sum8(accA.x + accA.y); yB = sum8(accB.x + accB.y);
; __device__ void phase_scan(int c, const bf16_t* PROJ, const float* k_k, const bf16_t* Wd, const bf16_t* Bd, const float* k_a, bf16_t* Y, bf16_t* Q, float* FS, float* sm) {
;     ...
;                 for (int i = 0; i < 16; i += 2) {
;                     float yA = 0.f, yB = 0.f;
;                     scan_ld(ob, obv, i + 1, B);
;                     if (roleP) A.v = (f32x2){0.f, 0.f};
;                     scan_step1(X, A, ob + i * 64, yA, yB);
;                     *(f32x2*)(obw + i * 16 + 2 * vp) = (f32x2){yA, yB};
;                     if (i + 2 < 16) scan_ld(ob, obv, i + 2, A);
;                     if (roleP) B.v = (f32x2){0.f, 0.f};
;                     scan_step1(X, B, ob + (i + 1) * 64, yA, yB);
;                     *(f32x2*)(obw + (i + 1) * 16 + 2 * vp) = (f32x2){yA, yB};
	ds_read_b128 v[86:89], v84 offset:3584
	ds_read_b128 v[90:93], v84 offset:3600
	ds_read_b128 v[94:97], v84 offset:7680
	ds_read_b128 v[98:101], v84 offset:7696
	ds_read_b128 v[102:105], v84 offset:11776
	ds_read_b128 v[106:109], v84 offset:11792
	ds_read_b128 v[110:113], v84 offset:15872
	ds_read_b128 v[114:117], v84 offset:15888
	ds_read_b128 v[118:121], v84 offset:19968
	ds_read_b128 v[122:125], v84 offset:19984
	ds_read_b64 v[126:127], v85 offset:24064
	v_pk_mul_f32 v[212:213], v[22:23], v[136:137]
	v_pk_mul_f32 v[216:217], v[14:15], v[136:137]
	v_pk_mul_f32 v[196:197], v[22:23], v[128:129]
	v_pk_mul_f32 v[204:205], v[14:15], v[128:129]
	v_pk_fma_f32 v[212:213], v[24:25], v[138:139], v[212:213]
	v_pk_fma_f32 v[216:217], v[16:17], v[138:139], v[216:217]
	v_pk_mul_f32 v[198:199], v[24:25], v[130:131]
	v_pk_mul_f32 v[206:207], v[16:17], v[130:131]
	v_pk_fma_f32 v[212:213], v[18:19], v[140:141], v[212:213]
	v_pk_fma_f32 v[216:217], v[10:11], v[140:141], v[216:217]
	v_pk_mul_f32 v[200:201], v[18:19], v[132:133]
	v_pk_mul_f32 v[208:209], v[10:11], v[132:133]
	v_pk_fma_f32 v[212:213], v[20:21], v[142:143], v[212:213]
	v_pk_fma_f32 v[216:217], v[12:13], v[142:143], v[216:217]
	v_pk_mul_f32 v[202:203], v[20:21], v[134:135]
	v_pk_mul_f32 v[210:211], v[12:13], v[134:135]
	v_add_f32_e32 v226, v222, v223
	v_add_f32_e32 v227, v224, v225
	v_add_f32_e32 v220, v212, v213
	v_add_f32_e32 v221, v216, v217
	v_pk_fma_f32 v[196:197], v[168:169], v[152:153], v[196:197] op_sel_hi:[0,1,1]
	v_pk_fma_f32 v[204:205], v[168:169], v[152:153], v[204:205] op_sel:[1,0,0] op_sel_hi:[1,1,1]
	ds_write_b64 v228, v[226:227] offset:6912
	v_add_f32_dpp v220, v220, v220 quad_perm:[1,0,3,2] row_mask:0xf bank_mask:0xf bound_ctrl:1
	v_add_f32_dpp v221, v221, v221 quad_perm:[1,0,3,2] row_mask:0xf bank_mask:0xf bound_ctrl:1
	v_pk_fma_f32 v[198:199], v[168:169], v[154:155], v[198:199] op_sel_hi:[0,1,1]
	v_pk_fma_f32 v[206:207], v[168:169], v[154:155], v[206:207] op_sel:[1,0,0] op_sel_hi:[1,1,1]
	v_add_f32_dpp v220, v220, v220 quad_perm:[2,3,0,1] row_mask:0xf bank_mask:0xf bound_ctrl:1
	v_add_f32_dpp v221, v221, v221 quad_perm:[2,3,0,1] row_mask:0xf bank_mask:0xf bound_ctrl:1
	v_pk_fma_f32 v[200:201], v[168:169], v[156:157], v[200:201] op_sel_hi:[0,1,1]
	v_pk_fma_f32 v[208:209], v[168:169], v[156:157], v[208:209] op_sel:[1,0,0] op_sel_hi:[1,1,1]
	v_add_f32_dpp v220, v220, v220 row_half_mirror row_mask:0xf bank_mask:0xf bound_ctrl:1
	v_add_f32_dpp v221, v221, v221 row_half_mirror row_mask:0xf bank_mask:0xf bound_ctrl:1
	v_pk_fma_f32 v[202:203], v[168:169], v[158:159], v[202:203] op_sel_hi:[0,1,1]
	v_pk_fma_f32 v[210:211], v[168:169], v[158:159], v[210:211] op_sel:[1,0,0] op_sel_hi:[1,1,1]
	v_pk_fma_f32 v[22:23], v[220:221], v[144:145], v[196:197] op_sel_hi:[0,1,1] neg_lo:[1,0,0] neg_hi:[1,0,0]
	v_pk_fma_f32 v[14:15], v[220:221], v[144:145], v[204:205] op_sel:[1,0,0] op_sel_hi:[1,1,1] neg_lo:[1,0,0] neg_hi:[1,0,0]
	v_pk_fma_f32 v[24:25], v[220:221], v[146:147], v[198:199] op_sel_hi:[0,1,1] neg_lo:[1,0,0] neg_hi:[1,0,0]
	v_pk_fma_f32 v[16:17], v[220:221], v[146:147], v[206:207] op_sel:[1,0,0] op_sel_hi:[1,1,1] neg_lo:[1,0,0] neg_hi:[1,0,0]
	v_pk_fma_f32 v[18:19], v[220:221], v[148:149], v[200:201] op_sel_hi:[0,1,1] neg_lo:[1,0,0] neg_hi:[1,0,0]
	v_pk_fma_f32 v[10:11], v[220:221], v[148:149], v[208:209] op_sel:[1,0,0] op_sel_hi:[1,1,1] neg_lo:[1,0,0] neg_hi:[1,0,0]
	v_pk_fma_f32 v[20:21], v[220:221], v[150:151], v[202:203] op_sel_hi:[0,1,1] neg_lo:[1,0,0] neg_hi:[1,0,0]
	v_pk_fma_f32 v[12:13], v[220:221], v[150:151], v[210:211] op_sel:[1,0,0] op_sel_hi:[1,1,1] neg_lo:[1,0,0] neg_hi:[1,0,0]
	v_pk_mul_f32 v[222:223], v[22:23], v[160:161]
	v_pk_mul_f32 v[224:225], v[14:15], v[160:161]
	v_pk_fma_f32 v[222:223], v[24:25], v[162:163], v[222:223]
	v_pk_fma_f32 v[224:225], v[16:17], v[162:163], v[224:225]
	v_pk_fma_f32 v[222:223], v[18:19], v[164:165], v[222:223]
	v_pk_fma_f32 v[224:225], v[10:11], v[164:165], v[224:225]
	v_pk_fma_f32 v[222:223], v[20:21], v[166:167], v[222:223]
	v_pk_fma_f32 v[224:225], v[12:13], v[166:167], v[224:225]
	s_waitcnt lgkmcnt(0)
	ds_read_b128 v[128:131], v84 offset:3840
	ds_read_b128 v[132:135], v84 offset:3856
	ds_read_b128 v[136:139], v84 offset:7936
	ds_read_b128 v[140:143], v84 offset:7952
	ds_read_b128 v[144:147], v84 offset:12032
	ds_read_b128 v[148:151], v84 offset:12048
	ds_read_b128 v[152:155], v84 offset:16128
	ds_read_b128 v[156:159], v84 offset:16144
	ds_read_b128 v[160:163], v84 offset:20224
	ds_read_b128 v[164:167], v84 offset:20240
	ds_read_b64 v[168:169], v85 offset:24320
	v_pk_mul_f32 v[212:213], v[22:23], v[94:95]
	v_pk_mul_f32 v[216:217], v[14:15], v[94:95]
	v_pk_mul_f32 v[196:197], v[22:23], v[86:87]
	v_pk_mul_f32 v[204:205], v[14:15], v[86:87]
	v_pk_fma_f32 v[212:213], v[24:25], v[96:97], v[212:213]
	v_pk_fma_f32 v[216:217], v[16:17], v[96:97], v[216:217]
	v_pk_mul_f32 v[198:199], v[24:25], v[88:89]
	v_pk_mul_f32 v[206:207], v[16:17], v[88:89]
	v_pk_fma_f32 v[212:213], v[18:19], v[98:99], v[212:213]
	v_pk_fma_f32 v[216:217], v[10:11], v[98:99], v[216:217]
	v_pk_mul_f32 v[200:201], v[18:19], v[90:91]
	v_pk_mul_f32 v[208:209], v[10:11], v[90:91]
	v_pk_fma_f32 v[212:213], v[20:21], v[100:101], v[212:213]
	v_pk_fma_f32 v[216:217], v[12:13], v[100:101], v[216:217]
	v_pk_mul_f32 v[202:203], v[20:21], v[92:93]
	v_pk_mul_f32 v[210:211], v[12:13], v[92:93]
	v_add_f32_e32 v226, v222, v223
	v_add_f32_e32 v227, v224, v225
	v_add_f32_e32 v220, v212, v213
	v_add_f32_e32 v221, v216, v217
	v_pk_fma_f32 v[196:197], v[126:127], v[110:111], v[196:197] op_sel_hi:[0,1,1]
	v_pk_fma_f32 v[204:205], v[126:127], v[110:111], v[204:205] op_sel:[1,0,0] op_sel_hi:[1,1,1]
; __device__ __forceinline__ void scan_rows(f32x2 (&X)[8], const ScanOps& o, const f32x4 (&b)[2], const f32x4 (&kd)[2], const f32x4 (&r)[2], const bool use_v, float& yA, float& yB) {
;     f32x2 aA = X[0] * o.kk[0].xy, aB = X[4] * o.kk[0].xy;
;     aA += X[1] * o.kk[0].zw; aB += X[5] * o.kk[0].zw;
;     aA += X[2] * o.kk[1].xy; aB += X[6] * o.kk[1].xy;
;     aA += X[3] * o.kk[1].zw; aB += X[7] * o.kk[1].zw;
;     const float saA = sum8(aA.x + aA.y), saB = sum8(aB.x + aB.y);
;     const f32x2 nA = (f32x2){-saA, -saA}, nB = (f32x2){-saB, -saB}, vA = (f32x2){o.v.x, o.v.x}, vB = (f32x2){o.v.y, o.v.y};
;     f32x2 tA, tB, accA, accB;
;     tA = X[0] * o.w[0].xy; tA += nA * b[0].xy; if (use_v) tA += vA * kd[0].xy; X[0] = tA; accA = tA * r[0].xy;
;     tB = X[4] * o.w[0].xy; tB += nB * b[0].xy; if (use_v) tB += vB * kd[0].xy; X[4] = tB; accB = tB * r[0].xy;
;     tA = X[1] * o.w[0].zw; tA += nA * b[0].zw; if (use_v) tA += vA * kd[0].zw; X[1] = tA; accA += tA * r[0].zw;
;     tB = X[5] * o.w[0].zw; tB += nB * b[0].zw; if (use_v) tB += vB * kd[0].zw; X[5] = tB; accB += tB * r[0].zw;
;     tA = X[2] * o.w[1].xy; tA += nA * b[1].xy; if (use_v) tA += vA * kd[1].xy; X[2] = tA; accA += tA * r[1].xy;
;     tB = X[6] * o.w[1].xy; tB += nB * b[1].xy; if (use_v) tB += vB * kd[1].xy; X[6] = tB; accB += tB * r[1].xy;
;     tA = X[3] * o.w[1].zw; tA += nA * b[1].zw; if (use_v) tA += vA * kd[1].zw; X[3] = tA; accA += tA * r[1].zw;
;     tB = X[7] * o.w[1].zw; tB += nB * b[1].zw; if (use_v) tB += vB * kd[1].zw; X[7] = tB; accB += tB * r[1].zw;
;     yA = sum8(accA.x + accA.y); yB = sum8(accB.x + accB.y);
; __device__ void phase_scan(int c, const bf16_t* PROJ, const float* k_k, const bf16_t* Wd, const bf16_t* Bd, const float* k_a, bf16_t* Y, bf16_t* Q, float* FS, float* sm) {
;     ...
;                 for (int i = 0; i < 16; i += 2) {
;                     float yA = 0.f, yB = 0.f;
;                     scan_ld(ob, obv, i + 1, B);
;                     if (roleP) A.v = (f32x2){0.f, 0.f};
;                     scan_step1(X, A, ob + i * 64, yA, yB);
;                     *(f32x2*)(obw + i * 16 + 2 * vp) = (f32x2){yA, yB};
;                     if (i + 2 < 16) scan_ld(ob, obv, i + 2, A);
;                     if (roleP) B.v = (f32x2){0.f, 0.f};
;                     scan_step1(X, B, ob + (i + 1) * 64, yA, yB);
;                     *(f32x2*)(obw + (i + 1) * 16 + 2 * vp) = (f32x2){yA, yB};
	ds_write_b64 v228, v[226:227] offset:7488
	v_add_f32_dpp v220, v220, v220 quad_perm:[1,0,3,2] row_mask:0xf bank_mask:0xf bound_ctrl:1
	v_add_f32_dpp v221, v221, v221 quad_perm:[1,0,3,2] row_mask:0xf bank_mask:0xf bound_ctrl:1
	v_pk_fma_f32 v[198:199], v[126:127], v[112:113], v[198:199] op_sel_hi:[0,1,1]
	v_pk_fma_f32 v[206:207], v[126:127], v[112:113], v[206:207] op_sel:[1,0,0] op_sel_hi:[1,1,1]
	v_add_f32_dpp v220, v220, v220 quad_perm:[2,3,0,1] row_mask:0xf bank_mask:0xf bound_ctrl:1
	v_add_f32_dpp v221, v221, v221 quad_perm:[2,3,0,1] row_mask:0xf bank_mask:0xf bound_ctrl:1
	v_pk_fma_f32 v[200:201], v[126:127], v[114:115], v[200:201] op_sel_hi:[0,1,1]
	v_pk_fma_f32 v[208:209], v[126:127], v[114:115], v[208:209] op_sel:[1,0,0] op_sel_hi:[1,1,1]
	v_add_f32_dpp v220, v220, v220 row_half_mirror row_mask:0xf bank_mask:0xf bound_ctrl:1
	v_add_f32_dpp v221, v221, v221 row_half_mirror row_mask:0xf bank_mask:0xf bound_ctrl:1
	v_pk_fma_f32 v[202:203], v[126:127], v[116:117], v[202:203] op_sel_hi:[0,1,1]
	v_pk_fma_f32 v[210:211], v[126:127], v[116:117], v[210:211] op_sel:[1,0,0] op_sel_hi:[1,1,1]
	v_pk_fma_f32 v[22:23], v[220:221], v[102:103], v[196:197] op_sel_hi:[0,1,1] neg_lo:[1,0,0] neg_hi:[1,0,0]
	v_pk_fma_f32 v[14:15], v[220:221], v[102:103], v[204:205] op_sel:[1,0,0] op_sel_hi:[1,1,1] neg_lo:[1,0,0] neg_hi:[1,0,0]
	v_pk_fma_f32 v[24:25], v[220:221], v[104:105], v[198:199] op_sel_hi:[0,1,1] neg_lo:[1,0,0] neg_hi:[1,0,0]
	v_pk_fma_f32 v[16:17], v[220:221], v[104:105], v[206:207] op_sel:[1,0,0] op_sel_hi:[1,1,1] neg_lo:[1,0,0] neg_hi:[1,0,0]
	v_pk_fma_f32 v[18:19], v[220:221], v[106:107], v[200:201] op_sel_hi:[0,1,1] neg_lo:[1,0,0] neg_hi:[1,0,0]
	v_pk_fma_f32 v[10:11], v[220:221], v[106:107], v[208:209] op_sel:[1,0,0] op_sel_hi:[1,1,1] neg_lo:[1,0,0] neg_hi:[1,0,0]
	v_pk_fma_f32 v[20:21], v[220:221], v[108:109], v[202:203] op_sel_hi:[0,1,1] neg_lo:[1,0,0] neg_hi:[1,0,0]
	v_pk_fma_f32 v[12:13], v[220:221], v[108:109], v[210:211] op_sel:[1,0,0] op_sel_hi:[1,1,1] neg_lo:[1,0,0] neg_hi:[1,0,0]
	v_pk_mul_f32 v[222:223], v[22:23], v[118:119]
	v_pk_mul_f32 v[224:225], v[14:15], v[118:119]
	v_pk_fma_f32 v[222:223], v[24:25], v[120:121], v[222:223]
	v_pk_fma_f32 v[224:225], v[16:17], v[120:121], v[224:225]
	v_pk_fma_f32 v[222:223], v[18:19], v[122:123], v[222:223]
	v_pk_fma_f32 v[224:225], v[10:11], v[122:123], v[224:225]
	v_pk_fma_f32 v[222:223], v[20:21], v[124:125], v[222:223]
	v_pk_fma_f32 v[224:225], v[12:13], v[124:125], v[224:225]
	s_waitcnt lgkmcnt(0)
	v_pk_mul_f32 v[212:213], v[22:23], v[136:137]
	v_pk_mul_f32 v[216:217], v[14:15], v[136:137]
	v_pk_mul_f32 v[196:197], v[22:23], v[128:129]
	v_pk_mul_f32 v[204:205], v[14:15], v[128:129]
	v_pk_fma_f32 v[212:213], v[24:25], v[138:139], v[212:213]
	v_pk_fma_f32 v[216:217], v[16:17], v[138:139], v[216:217]
	v_pk_mul_f32 v[198:199], v[24:25], v[130:131]
	v_pk_mul_f32 v[206:207], v[16:17], v[130:131]
	v_pk_fma_f32 v[212:213], v[18:19], v[140:141], v[212:213]
	v_pk_fma_f32 v[216:217], v[10:11], v[140:141], v[216:217]
	v_pk_mul_f32 v[200:201], v[18:19], v[132:133]
	v_pk_mul_f32 v[208:209], v[10:11], v[132:133]
	v_pk_fma_f32 v[212:213], v[20:21], v[142:143], v[212:213]
	v_pk_fma_f32 v[216:217], v[12:13], v[142:143], v[216:217]
	v_pk_mul_f32 v[202:203], v[20:21], v[134:135]
	v_pk_mul_f32 v[210:211], v[12:13], v[134:135]
	v_add_f32_e32 v226, v222, v223
	v_add_f32_e32 v227, v224, v225
	v_add_f32_e32 v220, v212, v213
	v_add_f32_e32 v221, v216, v217
	v_pk_fma_f32 v[196:197], v[168:169], v[152:153], v[196:197] op_sel_hi:[0,1,1]
	v_pk_fma_f32 v[204:205], v[168:169], v[152:153], v[204:205] op_sel:[1,0,0] op_sel_hi:[1,1,1]
	ds_write_b64 v228, v[226:227] offset:8064
	v_add_f32_dpp v220, v220, v220 quad_perm:[1,0,3,2] row_mask:0xf bank_mask:0xf bound_ctrl:1
	v_add_f32_dpp v221, v221, v221 quad_perm:[1,0,3,2] row_mask:0xf bank_mask:0xf bound_ctrl:1
	v_pk_fma_f32 v[198:199], v[168:169], v[154:155], v[198:199] op_sel_hi:[0,1,1]
	v_pk_fma_f32 v[206:207], v[168:169], v[154:155], v[206:207] op_sel:[1,0,0] op_sel_hi:[1,1,1]
	v_add_f32_dpp v220, v220, v220 quad_perm:[2,3,0,1] row_mask:0xf bank_mask:0xf bound_ctrl:1
	v_add_f32_dpp v221, v221, v221 quad_perm:[2,3,0,1] row_mask:0xf bank_mask:0xf bound_ctrl:1
	v_pk_fma_f32 v[200:201], v[168:169], v[156:157], v[200:201] op_sel_hi:[0,1,1]
	v_pk_fma_f32 v[208:209], v[168:169], v[156:157], v[208:209] op_sel:[1,0,0] op_sel_hi:[1,1,1]
	v_add_f32_dpp v220, v220, v220 row_half_mirror row_mask:0xf bank_mask:0xf bound_ctrl:1
	v_add_f32_dpp v221, v221, v221 row_half_mirror row_mask:0xf bank_mask:0xf bound_ctrl:1
	v_pk_fma_f32 v[202:203], v[168:169], v[158:159], v[202:203] op_sel_hi:[0,1,1]
	v_pk_fma_f32 v[210:211], v[168:169], v[158:159], v[210:211] op_sel:[1,0,0] op_sel_hi:[1,1,1]
	v_pk_fma_f32 v[22:23], v[220:221], v[144:145], v[196:197] op_sel_hi:[0,1,1] neg_lo:[1,0,0] neg_hi:[1,0,0]
	v_pk_fma_f32 v[14:15], v[220:221], v[144:145], v[204:205] op_sel:[1,0,0] op_sel_hi:[1,1,1] neg_lo:[1,0,0] neg_hi:[1,0,0]
	v_pk_fma_f32 v[24:25], v[220:221], v[146:147], v[198:199] op_sel_hi:[0,1,1] neg_lo:[1,0,0] neg_hi:[1,0,0]
	v_pk_fma_f32 v[16:17], v[220:221], v[146:147], v[206:207] op_sel:[1,0,0] op_sel_hi:[1,1,1] neg_lo:[1,0,0] neg_hi:[1,0,0]
	v_pk_fma_f32 v[18:19], v[220:221], v[148:149], v[200:201] op_sel_hi:[0,1,1] neg_lo:[1,0,0] neg_hi:[1,0,0]
	v_pk_fma_f32 v[10:11], v[220:221], v[148:149], v[208:209] op_sel:[1,0,0] op_sel_hi:[1,1,1] neg_lo:[1,0,0] neg_hi:[1,0,0]
	v_pk_fma_f32 v[20:21], v[220:221], v[150:151], v[202:203] op_sel_hi:[0,1,1] neg_lo:[1,0,0] neg_hi:[1,0,0]
	v_pk_fma_f32 v[12:13], v[220:221], v[150:151], v[210:211] op_sel:[1,0,0] op_sel_hi:[1,1,1] neg_lo:[1,0,0] neg_hi:[1,0,0]
	v_pk_mul_f32 v[222:223], v[22:23], v[160:161]
	v_pk_mul_f32 v[224:225], v[14:15], v[160:161]
	v_pk_fma_f32 v[222:223], v[24:25], v[162:163], v[222:223]
	v_pk_fma_f32 v[224:225], v[16:17], v[162:163], v[224:225]
	v_pk_fma_f32 v[222:223], v[18:19], v[164:165], v[222:223]
	v_pk_fma_f32 v[224:225], v[10:11], v[164:165], v[224:225]
	v_pk_fma_f32 v[222:223], v[20:21], v[166:167], v[222:223]
	v_pk_fma_f32 v[224:225], v[12:13], v[166:167], v[224:225]
	v_add_f32_e32 v226, v222, v223
	v_add_f32_e32 v227, v224, v225
	ds_write_b64 v228, v[226:227] offset:8640
	s_branch .Lscan_body_end
; __device__ __forceinline__ void scan_rows(f32x2 (&X)[8], const ScanOps& o, const f32x4 (&b)[2], const f32x4 (&kd)[2], const f32x4 (&r)[2], const bool use_v, float& yA, float& yB) {
;     f32x2 aA = X[0] * o.kk[0].xy, aB = X[4] * o.kk[0].xy;
;     aA += X[1] * o.kk[0].zw; aB += X[5] * o.kk[0].zw;
;     aA += X[2] * o.kk[1].xy; aB += X[6] * o.kk[1].xy;
;     aA += X[3] * o.kk[1].zw; aB += X[7] * o.kk[1].zw;
;     const float saA = sum8(aA.x + aA.y), saB = sum8(aB.x + aB.y);
;     const f32x2 nA = (f32x2){-saA, -saA}, nB = (f32x2){-saB, -saB}, vA = (f32x2){o.v.x, o.v.x}, vB = (f32x2){o.v.y, o.v.y};
;     f32x2 tA, tB, accA, accB;
;     tA = X[0] * o.w[0].xy; tA += nA * b[0].xy; if (use_v) tA += vA * kd[0].xy; X[0] = tA; accA = tA * r[0].xy;
;     tB = X[4] * o.w[0].xy; tB += nB * b[0].xy; if (use_v) tB += vB * kd[0].xy; X[4] = tB; accB = tB * r[0].xy;
;     tA = X[1] * o.w[0].zw; tA += nA * b[0].zw; if (use_v) tA += vA * kd[0].zw; X[1] = tA; accA += tA * r[0].zw;
;     tB = X[5] * o.w[0].zw; tB += nB * b[0].zw; if (use_v) tB += vB * kd[0].zw; X[5] = tB; accB += tB * r[0].zw;
;     tA = X[2] * o.w[1].xy; tA += nA * b[1].xy; if (use_v) tA += vA * kd[1].xy; X[2] = tA; accA += tA * r[1].xy;
;     tB = X[6] * o.w[1].xy; tB += nB * b[1].xy; if (use_v) tB += vB * kd[1].xy; X[6] = tB; accB += tB * r[1].xy;
;     tA = X[3] * o.w[1].zw; tA += nA * b[1].zw; if (use_v) tA += vA * kd[1].zw; X[3] = tA; accA += tA * r[1].zw;
;     tB = X[7] * o.w[1].zw; tB += nB * b[1].zw; if (use_v) tB += vB * kd[1].zw; X[7] = tB; accB += tB * r[1].zw;
;     yA = sum8(accA.x + accA.y); yB = sum8(accB.x + accB.y);
; __device__ void phase_scan(int c, const bf16_t* PROJ, const float* k_k, const bf16_t* Wd, const bf16_t* Bd, const float* k_a, bf16_t* Y, bf16_t* Q, float* FS, float* sm) {
;     ...
;                 for (int i = 0; i < 16; i += 2) {
;                     float yA = 0.f, yB = 0.f;
;                     scan_ld(ob, obv, i + 1, B);
;                     if (roleP) A.v = (f32x2){0.f, 0.f};
;                     scan_step1(X, A, ob + i * 64, yA, yB);
;                     *(f32x2*)(obw + i * 16 + 2 * vp) = (f32x2){yA, yB};
;                     if (i + 2 < 16) scan_ld(ob, obv, i + 2, A);
;                     if (roleP) B.v = (f32x2){0.f, 0.f};
;                     scan_step1(X, B, ob + (i + 1) * 64, yA, yB);
;                     *(f32x2*)(obw + (i + 1) * 16 + 2 * vp) = (f32x2){yA, yB};
.Lscan_p_body:
	ds_read_b128 v[86:89], v84 offset:0
	ds_read_b128 v[90:93], v84 offset:16
	ds_read_b128 v[94:97], v84 offset:4096
	ds_read_b128 v[98:101], v84 offset:4112
	ds_read_b128 v[102:105], v84 offset:8192
	ds_read_b128 v[106:109], v84 offset:8208
	ds_read_b128 v[118:121], v84 offset:16384
	ds_read_b128 v[122:125], v84 offset:16400
	s_waitcnt lgkmcnt(0)
	ds_read_b128 v[128:131], v84 offset:256
	ds_read_b128 v[132:135], v84 offset:272
	ds_read_b128 v[136:139], v84 offset:4352
	ds_read_b128 v[140:143], v84 offset:4368
	ds_read_b128 v[144:147], v84 offset:8448
	ds_read_b128 v[148:151], v84 offset:8464
	ds_read_b128 v[160:163], v84 offset:16640
	ds_read_b128 v[164:167], v84 offset:16656
	v_pk_mul_f32 v[212:213], v[22:23], v[94:95]
	v_pk_mul_f32 v[216:217], v[14:15], v[94:95]
	v_pk_mul_f32 v[196:197], v[22:23], v[86:87]
	v_pk_mul_f32 v[204:205], v[14:15], v[86:87]
	v_pk_fma_f32 v[212:213], v[24:25], v[96:97], v[212:213]
	v_pk_fma_f32 v[216:217], v[16:17], v[96:97], v[216:217]
	v_pk_mul_f32 v[198:199], v[24:25], v[88:89]
	v_pk_mul_f32 v[206:207], v[16:17], v[88:89]
	v_pk_fma_f32 v[212:213], v[18:19], v[98:99], v[212:213]
	v_pk_fma_f32 v[216:217], v[10:11], v[98:99], v[216:217]
	v_pk_fma_f32 v[212:213], v[20:21], v[100:101], v[212:213]
	v_pk_fma_f32 v[216:217], v[12:13], v[100:101], v[216:217]
	v_add_f32_e32 v220, v212, v213
	v_add_f32_e32 v221, v216, v217
	v_pk_mul_f32 v[200:201], v[18:19], v[90:91]
	v_pk_mul_f32 v[208:209], v[10:11], v[90:91]
	v_add_f32_dpp v220, v220, v220 quad_perm:[1,0,3,2] row_mask:0xf bank_mask:0xf bound_ctrl:1
	v_add_f32_dpp v221, v221, v221 quad_perm:[1,0,3,2] row_mask:0xf bank_mask:0xf bound_ctrl:1
	v_pk_mul_f32 v[202:203], v[20:21], v[92:93]
	v_pk_mul_f32 v[210:211], v[12:13], v[92:93]
	v_add_f32_dpp v220, v220, v220 quad_perm:[2,3,0,1] row_mask:0xf bank_mask:0xf bound_ctrl:1
	v_add_f32_dpp v221, v221, v221 quad_perm:[2,3,0,1] row_mask:0xf bank_mask:0xf bound_ctrl:1
	s_nop 0
	v_add_f32_dpp v220, v220, v220 row_half_mirror row_mask:0xf bank_mask:0xf bound_ctrl:1
	v_add_f32_dpp v221, v221, v221 row_half_mirror row_mask:0xf bank_mask:0xf bound_ctrl:1
	s_nop 0
	v_pk_fma_f32 v[22:23], v[220:221], v[102:103], v[196:197] op_sel_hi:[0,1,1] neg_lo:[1,0,0] neg_hi:[1,0,0]
	v_pk_fma_f32 v[14:15], v[220:221], v[102:103], v[204:205] op_sel:[1,0,0] op_sel_hi:[1,1,1] neg_lo:[1,0,0] neg_hi:[1,0,0]
	v_pk_fma_f32 v[24:25], v[220:221], v[104:105], v[198:199] op_sel_hi:[0,1,1] neg_lo:[1,0,0] neg_hi:[1,0,0]
	v_pk_fma_f32 v[16:17], v[220:221], v[104:105], v[206:207] op_sel:[1,0,0] op_sel_hi:[1,1,1] neg_lo:[1,0,0] neg_hi:[1,0,0]
	v_pk_fma_f32 v[18:19], v[220:221], v[106:107], v[200:201] op_sel_hi:[0,1,1] neg_lo:[1,0,0] neg_hi:[1,0,0]
	v_pk_fma_f32 v[10:11], v[220:221], v[106:107], v[208:209] op_sel:[1,0,0] op_sel_hi:[1,1,1] neg_lo:[1,0,0] neg_hi:[1,0,0]
	v_pk_fma_f32 v[20:21], v[220:221], v[108:109], v[202:203] op_sel_hi:[0,1,1] neg_lo:[1,0,0] neg_hi:[1,0,0]
	v_pk_fma_f32 v[12:13], v[220:221], v[108:109], v[210:211] op_sel:[1,0,0] op_sel_hi:[1,1,1] neg_lo:[1,0,0] neg_hi:[1,0,0]
	v_pk_mul_f32 v[222:223], v[22:23], v[118:119]
	v_pk_mul_f32 v[224:225], v[14:15], v[118:119]
	v_pk_fma_f32 v[222:223], v[24:25], v[120:121], v[222:223]
	v_pk_fma_f32 v[224:225], v[16:17], v[120:121], v[224:225]
	v_pk_fma_f32 v[222:223], v[18:19], v[122:123], v[222:223]
	v_pk_fma_f32 v[224:225], v[10:11], v[122:123], v[224:225]
	v_pk_fma_f32 v[222:223], v[20:21], v[124:125], v[222:223]
	v_pk_fma_f32 v[224:225], v[12:13], v[124:125], v[224:225]
	s_waitcnt lgkmcnt(0)
	ds_read_b128 v[86:89], v84 offset:512
	ds_read_b128 v[90:93], v84 offset:528
	ds_read_b128 v[94:97], v84 offset:4608
	ds_read_b128 v[98:101], v84 offset:4624
	ds_read_b128 v[102:105], v84 offset:8704
	ds_read_b128 v[106:109], v84 offset:8720
	ds_read_b128 v[118:121], v84 offset:16896
	ds_read_b128 v[122:125], v84 offset:16912
	v_pk_mul_f32 v[212:213], v[22:23], v[136:137]
	v_pk_mul_f32 v[216:217], v[14:15], v[136:137]
	v_pk_mul_f32 v[196:197], v[22:23], v[128:129]
	v_pk_mul_f32 v[204:205], v[14:15], v[128:129]
	v_pk_fma_f32 v[212:213], v[24:25], v[138:139], v[212:213]
	v_pk_fma_f32 v[216:217], v[16:17], v[138:139], v[216:217]
	v_pk_mul_f32 v[198:199], v[24:25], v[130:131]
	v_pk_mul_f32 v[206:207], v[16:17], v[130:131]
	v_pk_fma_f32 v[212:213], v[18:19], v[140:141], v[212:213]
	v_pk_fma_f32 v[216:217], v[10:11], v[140:141], v[216:217]
	v_pk_fma_f32 v[212:213], v[20:21], v[142:143], v[212:213]
	v_pk_fma_f32 v[216:217], v[12:13], v[142:143], v[216:217]
	v_add_f32_e32 v226, v222, v223
	v_add_f32_e32 v227, v224, v225
	v_add_f32_e32 v220, v212, v213
	v_add_f32_e32 v221, v216, v217
	v_pk_mul_f32 v[200:201], v[18:19], v[132:133]
	v_pk_mul_f32 v[208:209], v[10:11], v[132:133]
	ds_write_b64 v228, v[226:227]
	v_add_f32_dpp v220, v220, v220 quad_perm:[1,0,3,2] row_mask:0xf bank_mask:0xf bound_ctrl:1
	v_add_f32_dpp v221, v221, v221 quad_perm:[1,0,3,2] row_mask:0xf bank_mask:0xf bound_ctrl:1
	v_pk_mul_f32 v[202:203], v[20:21], v[134:135]
	v_pk_mul_f32 v[210:211], v[12:13], v[134:135]
	v_add_f32_dpp v220, v220, v220 quad_perm:[2,3,0,1] row_mask:0xf bank_mask:0xf bound_ctrl:1
	v_add_f32_dpp v221, v221, v221 quad_perm:[2,3,0,1] row_mask:0xf bank_mask:0xf bound_ctrl:1
	s_nop 0
	v_add_f32_dpp v220, v220, v220 row_half_mirror row_mask:0xf bank_mask:0xf bound_ctrl:1
	v_add_f32_dpp v221, v221, v221 row_half_mirror row_mask:0xf bank_mask:0xf bound_ctrl:1
	s_nop 0
	v_pk_fma_f32 v[22:23], v[220:221], v[144:145], v[196:197] op_sel_hi:[0,1,1] neg_lo:[1,0,0] neg_hi:[1,0,0]
	v_pk_fma_f32 v[14:15], v[220:221], v[144:145], v[204:205] op_sel:[1,0,0] op_sel_hi:[1,1,1] neg_lo:[1,0,0] neg_hi:[1,0,0]
	v_pk_fma_f32 v[24:25], v[220:221], v[146:147], v[198:199] op_sel_hi:[0,1,1] neg_lo:[1,0,0] neg_hi:[1,0,0]
	v_pk_fma_f32 v[16:17], v[220:221], v[146:147], v[206:207] op_sel:[1,0,0] op_sel_hi:[1,1,1] neg_lo:[1,0,0] neg_hi:[1,0,0]
	v_pk_fma_f32 v[18:19], v[220:221], v[148:149], v[200:201] op_sel_hi:[0,1,1] neg_lo:[1,0,0] neg_hi:[1,0,0]
	v_pk_fma_f32 v[10:11], v[220:221], v[148:149], v[208:209] op_sel:[1,0,0] op_sel_hi:[1,1,1] neg_lo:[1,0,0] neg_hi:[1,0,0]
	v_pk_fma_f32 v[20:21], v[220:221], v[150:151], v[202:203] op_sel_hi:[0,1,1] neg_lo:[1,0,0] neg_hi:[1,0,0]
	v_pk_fma_f32 v[12:13], v[220:221], v[150:151], v[210:211] op_sel:[1,0,0] op_sel_hi:[1,1,1] neg_lo:[1,0,0] neg_hi:[1,0,0]
	v_pk_mul_f32 v[222:223], v[22:23], v[160:161]
	v_pk_mul_f32 v[224:225], v[14:15], v[160:161]
	v_pk_fma_f32 v[222:223], v[24:25], v[162:163], v[222:223]
	v_pk_fma_f32 v[224:225], v[16:17], v[162:163], v[224:225]
	v_pk_fma_f32 v[222:223], v[18:19], v[164:165], v[222:223]
	v_pk_fma_f32 v[224:225], v[10:11], v[164:165], v[224:225]
	v_pk_fma_f32 v[222:223], v[20:21], v[166:167], v[222:223]
	v_pk_fma_f32 v[224:225], v[12:13], v[166:167], v[224:225]
	s_waitcnt lgkmcnt(0)
; __device__ __forceinline__ void scan_rows(f32x2 (&X)[8], const ScanOps& o, const f32x4 (&b)[2], const f32x4 (&kd)[2], const f32x4 (&r)[2], const bool use_v, float& yA, float& yB) {
;     f32x2 aA = X[0] * o.kk[0].xy, aB = X[4] * o.kk[0].xy;
;     aA += X[1] * o.kk[0].zw; aB += X[5] * o.kk[0].zw;
;     aA += X[2] * o.kk[1].xy; aB += X[6] * o.kk[1].xy;
;     aA += X[3] * o.kk[1].zw; aB += X[7] * o.kk[1].zw;
;     const float saA = sum8(aA.x + aA.y), saB = sum8(aB.x + aB.y);
;     const f32x2 nA = (f32x2){-saA, -saA}, nB = (f32x2){-saB, -saB}, vA = (f32x2){o.v.x, o.v.x}, vB = (f32x2){o.v.y, o.v.y};
;     f32x2 tA, tB, accA, accB;
;     tA = X[0] * o.w[0].xy; tA += nA * b[0].xy; if (use_v) tA += vA * kd[0].xy; X[0] = tA; accA = tA * r[0].xy;
;     tB = X[4] * o.w[0].xy; tB += nB * b[0].xy; if (use_v) tB += vB * kd[0].xy; X[4] = tB; accB = tB * r[0].xy;
;     tA = X[1] * o.w[0].zw; tA += nA * b[0].zw; if (use_v) tA += vA * kd[0].zw; X[1] = tA; accA += tA * r[0].zw;
;     tB = X[5] * o.w[0].zw; tB += nB * b[0].zw; if (use_v) tB += vB * kd[0].zw; X[5] = tB; accB += tB * r[0].zw;
;     tA = X[2] * o.w[1].xy; tA += nA * b[1].xy; if (use_v) tA += vA * kd[1].xy; X[2] = tA; accA += tA * r[1].xy;
;     tB = X[6] * o.w[1].xy; tB += nB * b[1].xy; if (use_v) tB += vB * kd[1].xy; X[6] = tB; accB += tB * r[1].xy;
;     tA = X[3] * o.w[1].zw; tA += nA * b[1].zw; if (use_v) tA += vA * kd[1].zw; X[3] = tA; accA += tA * r[1].zw;
;     tB = X[7] * o.w[1].zw; tB += nB * b[1].zw; if (use_v) tB += vB * kd[1].zw; X[7] = tB; accB += tB * r[1].zw;
;     yA = sum8(accA.x + accA.y); yB = sum8(accB.x + accB.y);
; __device__ void phase_scan(int c, const bf16_t* PROJ, const float* k_k, const bf16_t* Wd, const bf16_t* Bd, const float* k_a, bf16_t* Y, bf16_t* Q, float* FS, float* sm) {
;     ...
;                 for (int i = 0; i < 16; i += 2) {
;                     float yA = 0.f, yB = 0.f;
;                     scan_ld(ob, obv, i + 1, B);
;                     if (roleP) A.v = (f32x2){0.f, 0.f};
;                     scan_step1(X, A, ob + i * 64, yA, yB);
;                     *(f32x2*)(obw + i * 16 + 2 * vp) = (f32x2){yA, yB};
;                     if (i + 2 < 16) scan_ld(ob, obv, i + 2, A);
;                     if (roleP) B.v = (f32x2){0.f, 0.f};
;                     scan_step1(X, B, ob + (i + 1) * 64, yA, yB);
;                     *(f32x2*)(obw + (i + 1) * 16 + 2 * vp) = (f32x2){yA, yB};
	ds_read_b128 v[128:131], v84 offset:768
	ds_read_b128 v[132:135], v84 offset:784
	ds_read_b128 v[136:139], v84 offset:4864
	ds_read_b128 v[140:143], v84 offset:4880
	ds_read_b128 v[144:147], v84 offset:8960
	ds_read_b128 v[148:151], v84 offset:8976
	ds_read_b128 v[160:163], v84 offset:17152
	ds_read_b128 v[164:167], v84 offset:17168
	v_pk_mul_f32 v[212:213], v[22:23], v[94:95]
	v_pk_mul_f32 v[216:217], v[14:15], v[94:95]
	v_pk_mul_f32 v[196:197], v[22:23], v[86:87]
	v_pk_mul_f32 v[204:205], v[14:15], v[86:87]
	v_pk_fma_f32 v[212:213], v[24:25], v[96:97], v[212:213]
	v_pk_fma_f32 v[216:217], v[16:17], v[96:97], v[216:217]
	v_pk_mul_f32 v[198:199], v[24:25], v[88:89]
	v_pk_mul_f32 v[206:207], v[16:17], v[88:89]
	v_pk_fma_f32 v[212:213], v[18:19], v[98:99], v[212:213]
	v_pk_fma_f32 v[216:217], v[10:11], v[98:99], v[216:217]
	v_pk_fma_f32 v[212:213], v[20:21], v[100:101], v[212:213]
	v_pk_fma_f32 v[216:217], v[12:13], v[100:101], v[216:217]
	v_add_f32_e32 v226, v222, v223
	v_add_f32_e32 v227, v224, v225
	v_add_f32_e32 v220, v212, v213
	v_add_f32_e32 v221, v216, v217
	v_pk_mul_f32 v[200:201], v[18:19], v[90:91]
	v_pk_mul_f32 v[208:209], v[10:11], v[90:91]
	ds_write_b64 v228, v[226:227] offset:576
	v_add_f32_dpp v220, v220, v220 quad_perm:[1,0,3,2] row_mask:0xf bank_mask:0xf bound_ctrl:1
	v_add_f32_dpp v221, v221, v221 quad_perm:[1,0,3,2] row_mask:0xf bank_mask:0xf bound_ctrl:1
	v_pk_mul_f32 v[202:203], v[20:21], v[92:93]
	v_pk_mul_f32 v[210:211], v[12:13], v[92:93]
	v_add_f32_dpp v220, v220, v220 quad_perm:[2,3,0,1] row_mask:0xf bank_mask:0xf bound_ctrl:1
	v_add_f32_dpp v221, v221, v221 quad_perm:[2,3,0,1] row_mask:0xf bank_mask:0xf bound_ctrl:1
	s_nop 0
	v_add_f32_dpp v220, v220, v220 row_half_mirror row_mask:0xf bank_mask:0xf bound_ctrl:1
	v_add_f32_dpp v221, v221, v221 row_half_mirror row_mask:0xf bank_mask:0xf bound_ctrl:1
	s_nop 0
	v_pk_fma_f32 v[22:23], v[220:221], v[102:103], v[196:197] op_sel_hi:[0,1,1] neg_lo:[1,0,0] neg_hi:[1,0,0]
	v_pk_fma_f32 v[14:15], v[220:221], v[102:103], v[204:205] op_sel:[1,0,0] op_sel_hi:[1,1,1] neg_lo:[1,0,0] neg_hi:[1,0,0]
	v_pk_fma_f32 v[24:25], v[220:221], v[104:105], v[198:199] op_sel_hi:[0,1,1] neg_lo:[1,0,0] neg_hi:[1,0,0]
	v_pk_fma_f32 v[16:17], v[220:221], v[104:105], v[206:207] op_sel:[1,0,0] op_sel_hi:[1,1,1] neg_lo:[1,0,0] neg_hi:[1,0,0]
	v_pk_fma_f32 v[18:19], v[220:221], v[106:107], v[200:201] op_sel_hi:[0,1,1] neg_lo:[1,0,0] neg_hi:[1,0,0]
	v_pk_fma_f32 v[10:11], v[220:221], v[106:107], v[208:209] op_sel:[1,0,0] op_sel_hi:[1,1,1] neg_lo:[1,0,0] neg_hi:[1,0,0]
	v_pk_fma_f32 v[20:21], v[220:221], v[108:109], v[202:203] op_sel_hi:[0,1,1] neg_lo:[1,0,0] neg_hi:[1,0,0]
	v_pk_fma_f32 v[12:13], v[220:221], v[108:109], v[210:211] op_sel:[1,0,0] op_sel_hi:[1,1,1] neg_lo:[1,0,0] neg_hi:[1,0,0]
	v_pk_mul_f32 v[222:223], v[22:23], v[118:119]
	v_pk_mul_f32 v[224:225], v[14:15], v[118:119]
	v_pk_fma_f32 v[222:223], v[24:25], v[120:121], v[222:223]
	v_pk_fma_f32 v[224:225], v[16:17], v[120:121], v[224:225]
	v_pk_fma_f32 v[222:223], v[18:19], v[122:123], v[222:223]
	v_pk_fma_f32 v[224:225], v[10:11], v[122:123], v[224:225]
	v_pk_fma_f32 v[222:223], v[20:21], v[124:125], v[222:223]
	v_pk_fma_f32 v[224:225], v[12:13], v[124:125], v[224:225]
	s_waitcnt lgkmcnt(0)
	ds_read_b128 v[86:89], v84 offset:1024
	ds_read_b128 v[90:93], v84 offset:1040
	ds_read_b128 v[94:97], v84 offset:5120
	ds_read_b128 v[98:101], v84 offset:5136
	ds_read_b128 v[102:105], v84 offset:9216
	ds_read_b128 v[106:109], v84 offset:9232
	ds_read_b128 v[118:121], v84 offset:17408
	ds_read_b128 v[122:125], v84 offset:17424
	v_pk_mul_f32 v[212:213], v[22:23], v[136:137]
	v_pk_mul_f32 v[216:217], v[14:15], v[136:137]
	v_pk_mul_f32 v[196:197], v[22:23], v[128:129]
	v_pk_mul_f32 v[204:205], v[14:15], v[128:129]
	v_pk_fma_f32 v[212:213], v[24:25], v[138:139], v[212:213]
	v_pk_fma_f32 v[216:217], v[16:17], v[138:139], v[216:217]
	v_pk_mul_f32 v[198:199], v[24:25], v[130:131]
	v_pk_mul_f32 v[206:207], v[16:17], v[130:131]
	v_pk_fma_f32 v[212:213], v[18:19], v[140:141], v[212:213]
	v_pk_fma_f32 v[216:217], v[10:11], v[140:141], v[216:217]
	v_pk_fma_f32 v[212:213], v[20:21], v[142:143], v[212:213]
	v_pk_fma_f32 v[216:217], v[12:13], v[142:143], v[216:217]
	v_add_f32_e32 v226, v222, v223
	v_add_f32_e32 v227, v224, v225
	v_add_f32_e32 v220, v212, v213
	v_add_f32_e32 v221, v216, v217
	v_pk_mul_f32 v[200:201], v[18:19], v[132:133]
	v_pk_mul_f32 v[208:209], v[10:11], v[132:133]
	ds_write_b64 v228, v[226:227] offset:1152
	v_add_f32_dpp v220, v220, v220 quad_perm:[1,0,3,2] row_mask:0xf bank_mask:0xf bound_ctrl:1
	v_add_f32_dpp v221, v221, v221 quad_perm:[1,0,3,2] row_mask:0xf bank_mask:0xf bound_ctrl:1
	v_pk_mul_f32 v[202:203], v[20:21], v[134:135]
	v_pk_mul_f32 v[210:211], v[12:13], v[134:135]
	v_add_f32_dpp v220, v220, v220 quad_perm:[2,3,0,1] row_mask:0xf bank_mask:0xf bound_ctrl:1
	v_add_f32_dpp v221, v221, v221 quad_perm:[2,3,0,1] row_mask:0xf bank_mask:0xf bound_ctrl:1
	s_nop 0
	v_add_f32_dpp v220, v220, v220 row_half_mirror row_mask:0xf bank_mask:0xf bound_ctrl:1
	v_add_f32_dpp v221, v221, v221 row_half_mirror row_mask:0xf bank_mask:0xf bound_ctrl:1
	s_nop 0
	v_pk_fma_f32 v[22:23], v[220:221], v[144:145], v[196:197] op_sel_hi:[0,1,1] neg_lo:[1,0,0] neg_hi:[1,0,0]
	v_pk_fma_f32 v[14:15], v[220:221], v[144:145], v[204:205] op_sel:[1,0,0] op_sel_hi:[1,1,1] neg_lo:[1,0,0] neg_hi:[1,0,0]
	v_pk_fma_f32 v[24:25], v[220:221], v[146:147], v[198:199] op_sel_hi:[0,1,1] neg_lo:[1,0,0] neg_hi:[1,0,0]
	v_pk_fma_f32 v[16:17], v[220:221], v[146:147], v[206:207] op_sel:[1,0,0] op_sel_hi:[1,1,1] neg_lo:[1,0,0] neg_hi:[1,0,0]
	v_pk_fma_f32 v[18:19], v[220:221], v[148:149], v[200:201] op_sel_hi:[0,1,1] neg_lo:[1,0,0] neg_hi:[1,0,0]
	v_pk_fma_f32 v[10:11], v[220:221], v[148:149], v[208:209] op_sel:[1,0,0] op_sel_hi:[1,1,1] neg_lo:[1,0,0] neg_hi:[1,0,0]
	v_pk_fma_f32 v[20:21], v[220:221], v[150:151], v[202:203] op_sel_hi:[0,1,1] neg_lo:[1,0,0] neg_hi:[1,0,0]
	v_pk_fma_f32 v[12:13], v[220:221], v[150:151], v[210:211] op_sel:[1,0,0] op_sel_hi:[1,1,1] neg_lo:[1,0,0] neg_hi:[1,0,0]
	v_pk_mul_f32 v[222:223], v[22:23], v[160:161]
	v_pk_mul_f32 v[224:225], v[14:15], v[160:161]
	v_pk_fma_f32 v[222:223], v[24:25], v[162:163], v[222:223]
	v_pk_fma_f32 v[224:225], v[16:17], v[162:163], v[224:225]
	v_pk_fma_f32 v[222:223], v[18:19], v[164:165], v[222:223]
	v_pk_fma_f32 v[224:225], v[10:11], v[164:165], v[224:225]
	v_pk_fma_f32 v[222:223], v[20:21], v[166:167], v[222:223]
	v_pk_fma_f32 v[224:225], v[12:13], v[166:167], v[224:225]
	s_waitcnt lgkmcnt(0)
; __device__ __forceinline__ void scan_rows(f32x2 (&X)[8], const ScanOps& o, const f32x4 (&b)[2], const f32x4 (&kd)[2], const f32x4 (&r)[2], const bool use_v, float& yA, float& yB) {
;     f32x2 aA = X[0] * o.kk[0].xy, aB = X[4] * o.kk[0].xy;
;     aA += X[1] * o.kk[0].zw; aB += X[5] * o.kk[0].zw;
;     aA += X[2] * o.kk[1].xy; aB += X[6] * o.kk[1].xy;
;     aA += X[3] * o.kk[1].zw; aB += X[7] * o.kk[1].zw;
;     const float saA = sum8(aA.x + aA.y), saB = sum8(aB.x + aB.y);
;     const f32x2 nA = (f32x2){-saA, -saA}, nB = (f32x2){-saB, -saB}, vA = (f32x2){o.v.x, o.v.x}, vB = (f32x2){o.v.y, o.v.y};
;     f32x2 tA, tB, accA, accB;
;     tA = X[0] * o.w[0].xy; tA += nA * b[0].xy; if (use_v) tA += vA * kd[0].xy; X[0] = tA; accA = tA * r[0].xy;
;     tB = X[4] * o.w[0].xy; tB += nB * b[0].xy; if (use_v) tB += vB * kd[0].xy; X[4] = tB; accB = tB * r[0].xy;
;     tA = X[1] * o.w[0].zw; tA += nA * b[0].zw; if (use_v) tA += vA * kd[0].zw; X[1] = tA; accA += tA * r[0].zw;
;     tB = X[5] * o.w[0].zw; tB += nB * b[0].zw; if (use_v) tB += vB * kd[0].zw; X[5] = tB; accB += tB * r[0].zw;
;     tA = X[2] * o.w[1].xy; tA += nA * b[1].xy; if (use_v) tA += vA * kd[1].xy; X[2] = tA; accA += tA * r[1].xy;
;     tB = X[6] * o.w[1].xy; tB += nB * b[1].xy; if (use_v) tB += vB * kd[1].xy; X[6] = tB; accB += tB * r[1].xy;
;     tA = X[3] * o.w[1].zw; tA += nA * b[1].zw; if (use_v) tA += vA * kd[1].zw; X[3] = tA; accA += tA * r[1].zw;
;     tB = X[7] * o.w[1].zw; tB += nB * b[1].zw; if (use_v) tB += vB * kd[1].zw; X[7] = tB; accB += tB * r[1].zw;
;     yA = sum8(accA.x + accA.y); yB = sum8(accB.x + accB.y);
; __device__ void phase_scan(int c, const bf16_t* PROJ, const float* k_k, const bf16_t* Wd, const bf16_t* Bd, const float* k_a, bf16_t* Y, bf16_t* Q, float* FS, float* sm) {
;     ...
;                 for (int i = 0; i < 16; i += 2) {
;                     float yA = 0.f, yB = 0.f;
;                     scan_ld(ob, obv, i + 1, B);
;                     if (roleP) A.v = (f32x2){0.f, 0.f};
;                     scan_step1(X, A, ob + i * 64, yA, yB);
;                     *(f32x2*)(obw + i * 16 + 2 * vp) = (f32x2){yA, yB};
;                     if (i + 2 < 16) scan_ld(ob, obv, i + 2, A);
;                     if (roleP) B.v = (f32x2){0.f, 0.f};
;                     scan_step1(X, B, ob + (i + 1) * 64, yA, yB);
;                     *(f32x2*)(obw + (i + 1) * 16 + 2 * vp) = (f32x2){yA, yB};
	ds_read_b128 v[128:131], v84 offset:1280
	ds_read_b128 v[132:135], v84 offset:1296
	ds_read_b128 v[136:139], v84 offset:5376
	ds_read_b128 v[140:143], v84 offset:5392
	ds_read_b128 v[144:147], v84 offset:9472
	ds_read_b128 v[148:151], v84 offset:9488
	ds_read_b128 v[160:163], v84 offset:17664
	ds_read_b128 v[164:167], v84 offset:17680
	v_pk_mul_f32 v[212:213], v[22:23], v[94:95]
	v_pk_mul_f32 v[216:217], v[14:15], v[94:95]
	v_pk_mul_f32 v[196:197], v[22:23], v[86:87]
	v_pk_mul_f32 v[204:205], v[14:15], v[86:87]
	v_pk_fma_f32 v[212:213], v[24:25], v[96:97], v[212:213]
	v_pk_fma_f32 v[216:217], v[16:17], v[96:97], v[216:217]
	v_pk_mul_f32 v[198:199], v[24:25], v[88:89]
	v_pk_mul_f32 v[206:207], v[16:17], v[88:89]
	v_pk_fma_f32 v[212:213], v[18:19], v[98:99], v[212:213]
	v_pk_fma_f32 v[216:217], v[10:11], v[98:99], v[216:217]
	v_pk_fma_f32 v[212:213], v[20:21], v[100:101], v[212:213]
	v_pk_fma_f32 v[216:217], v[12:13], v[100:101], v[216:217]
	v_add_f32_e32 v226, v222, v223
	v_add_f32_e32 v227, v224, v225
	v_add_f32_e32 v220, v212, v213
	v_add_f32_e32 v221, v216, v217
	v_pk_mul_f32 v[200:201], v[18:19], v[90:91]
	v_pk_mul_f32 v[208:209], v[10:11], v[90:91]
	ds_write_b64 v228, v[226:227] offset:1728
	v_add_f32_dpp v220, v220, v220 quad_perm:[1,0,3,2] row_mask:0xf bank_mask:0xf bound_ctrl:1
	v_add_f32_dpp v221, v221, v221 quad_perm:[1,0,3,2] row_mask:0xf bank_mask:0xf bound_ctrl:1
	v_pk_mul_f32 v[202:203], v[20:21], v[92:93]
	v_pk_mul_f32 v[210:211], v[12:13], v[92:93]
	v_add_f32_dpp v220, v220, v220 quad_perm:[2,3,0,1] row_mask:0xf bank_mask:0xf bound_ctrl:1
	v_add_f32_dpp v221, v221, v221 quad_perm:[2,3,0,1] row_mask:0xf bank_mask:0xf bound_ctrl:1
	s_nop 0
	v_add_f32_dpp v220, v220, v220 row_half_mirror row_mask:0xf bank_mask:0xf bound_ctrl:1
	v_add_f32_dpp v221, v221, v221 row_half_mirror row_mask:0xf bank_mask:0xf bound_ctrl:1
	s_nop 0
	v_pk_fma_f32 v[22:23], v[220:221], v[102:103], v[196:197] op_sel_hi:[0,1,1] neg_lo:[1,0,0] neg_hi:[1,0,0]
	v_pk_fma_f32 v[14:15], v[220:221], v[102:103], v[204:205] op_sel:[1,0,0] op_sel_hi:[1,1,1] neg_lo:[1,0,0] neg_hi:[1,0,0]
	v_pk_fma_f32 v[24:25], v[220:221], v[104:105], v[198:199] op_sel_hi:[0,1,1] neg_lo:[1,0,0] neg_hi:[1,0,0]
	v_pk_fma_f32 v[16:17], v[220:221], v[104:105], v[206:207] op_sel:[1,0,0] op_sel_hi:[1,1,1] neg_lo:[1,0,0] neg_hi:[1,0,0]
	v_pk_fma_f32 v[18:19], v[220:221], v[106:107], v[200:201] op_sel_hi:[0,1,1] neg_lo:[1,0,0] neg_hi:[1,0,0]
	v_pk_fma_f32 v[10:11], v[220:221], v[106:107], v[208:209] op_sel:[1,0,0] op_sel_hi:[1,1,1] neg_lo:[1,0,0] neg_hi:[1,0,0]
	v_pk_fma_f32 v[20:21], v[220:221], v[108:109], v[202:203] op_sel_hi:[0,1,1] neg_lo:[1,0,0] neg_hi:[1,0,0]
	v_pk_fma_f32 v[12:13], v[220:221], v[108:109], v[210:211] op_sel:[1,0,0] op_sel_hi:[1,1,1] neg_lo:[1,0,0] neg_hi:[1,0,0]
	v_pk_mul_f32 v[222:223], v[22:23], v[118:119]
	v_pk_mul_f32 v[224:225], v[14:15], v[118:119]
	v_pk_fma_f32 v[222:223], v[24:25], v[120:121], v[222:223]
	v_pk_fma_f32 v[224:225], v[16:17], v[120:121], v[224:225]
	v_pk_fma_f32 v[222:223], v[18:19], v[122:123], v[222:223]
	v_pk_fma_f32 v[224:225], v[10:11], v[122:123], v[224:225]
	v_pk_fma_f32 v[222:223], v[20:21], v[124:125], v[222:223]
	v_pk_fma_f32 v[224:225], v[12:13], v[124:125], v[224:225]
	s_waitcnt lgkmcnt(0)
	ds_read_b128 v[86:89], v84 offset:1536
	ds_read_b128 v[90:93], v84 offset:1552
	ds_read_b128 v[94:97], v84 offset:5632
	ds_read_b128 v[98:101], v84 offset:5648
	ds_read_b128 v[102:105], v84 offset:9728
	ds_read_b128 v[106:109], v84 offset:9744
	ds_read_b128 v[118:121], v84 offset:17920
	ds_read_b128 v[122:125], v84 offset:17936
	v_pk_mul_f32 v[212:213], v[22:23], v[136:137]
	v_pk_mul_f32 v[216:217], v[14:15], v[136:137]
	v_pk_mul_f32 v[196:197], v[22:23], v[128:129]
	v_pk_mul_f32 v[204:205], v[14:15], v[128:129]
	v_pk_fma_f32 v[212:213], v[24:25], v[138:139], v[212:213]
	v_pk_fma_f32 v[216:217], v[16:17], v[138:139], v[216:217]
	v_pk_mul_f32 v[198:199], v[24:25], v[130:131]
	v_pk_mul_f32 v[206:207], v[16:17], v[130:131]
	v_pk_fma_f32 v[212:213], v[18:19], v[140:141], v[212:213]
	v_pk_fma_f32 v[216:217], v[10:11], v[140:141], v[216:217]
	v_pk_fma_f32 v[212:213], v[20:21], v[142:143], v[212:213]
	v_pk_fma_f32 v[216:217], v[12:13], v[142:143], v[216:217]
	v_add_f32_e32 v226, v222, v223
	v_add_f32_e32 v227, v224, v225
	v_add_f32_e32 v220, v212, v213
	v_add_f32_e32 v221, v216, v217
	v_pk_mul_f32 v[200:201], v[18:19], v[132:133]
	v_pk_mul_f32 v[208:209], v[10:11], v[132:133]
	ds_write_b64 v228, v[226:227] offset:2304
	v_add_f32_dpp v220, v220, v220 quad_perm:[1,0,3,2] row_mask:0xf bank_mask:0xf bound_ctrl:1
	v_add_f32_dpp v221, v221, v221 quad_perm:[1,0,3,2] row_mask:0xf bank_mask:0xf bound_ctrl:1
	v_pk_mul_f32 v[202:203], v[20:21], v[134:135]
	v_pk_mul_f32 v[210:211], v[12:13], v[134:135]
	v_add_f32_dpp v220, v220, v220 quad_perm:[2,3,0,1] row_mask:0xf bank_mask:0xf bound_ctrl:1
	v_add_f32_dpp v221, v221, v221 quad_perm:[2,3,0,1] row_mask:0xf bank_mask:0xf bound_ctrl:1
	s_nop 0
	v_add_f32_dpp v220, v220, v220 row_half_mirror row_mask:0xf bank_mask:0xf bound_ctrl:1
	v_add_f32_dpp v221, v221, v221 row_half_mirror row_mask:0xf bank_mask:0xf bound_ctrl:1
	s_nop 0
	v_pk_fma_f32 v[22:23], v[220:221], v[144:145], v[196:197] op_sel_hi:[0,1,1] neg_lo:[1,0,0] neg_hi:[1,0,0]
	v_pk_fma_f32 v[14:15], v[220:221], v[144:145], v[204:205] op_sel:[1,0,0] op_sel_hi:[1,1,1] neg_lo:[1,0,0] neg_hi:[1,0,0]
	v_pk_fma_f32 v[24:25], v[220:221], v[146:147], v[198:199] op_sel_hi:[0,1,1] neg_lo:[1,0,0] neg_hi:[1,0,0]
	v_pk_fma_f32 v[16:17], v[220:221], v[146:147], v[206:207] op_sel:[1,0,0] op_sel_hi:[1,1,1] neg_lo:[1,0,0] neg_hi:[1,0,0]
	v_pk_fma_f32 v[18:19], v[220:221], v[148:149], v[200:201] op_sel_hi:[0,1,1] neg_lo:[1,0,0] neg_hi:[1,0,0]
	v_pk_fma_f32 v[10:11], v[220:221], v[148:149], v[208:209] op_sel:[1,0,0] op_sel_hi:[1,1,1] neg_lo:[1,0,0] neg_hi:[1,0,0]
	v_pk_fma_f32 v[20:21], v[220:221], v[150:151], v[202:203] op_sel_hi:[0,1,1] neg_lo:[1,0,0] neg_hi:[1,0,0]
	v_pk_fma_f32 v[12:13], v[220:221], v[150:151], v[210:211] op_sel:[1,0,0] op_sel_hi:[1,1,1] neg_lo:[1,0,0] neg_hi:[1,0,0]
	v_pk_mul_f32 v[222:223], v[22:23], v[160:161]
	v_pk_mul_f32 v[224:225], v[14:15], v[160:161]
	v_pk_fma_f32 v[222:223], v[24:25], v[162:163], v[222:223]
	v_pk_fma_f32 v[224:225], v[16:17], v[162:163], v[224:225]
	v_pk_fma_f32 v[222:223], v[18:19], v[164:165], v[222:223]
	v_pk_fma_f32 v[224:225], v[10:11], v[164:165], v[224:225]
	v_pk_fma_f32 v[222:223], v[20:21], v[166:167], v[222:223]
	v_pk_fma_f32 v[224:225], v[12:13], v[166:167], v[224:225]
	s_waitcnt lgkmcnt(0)
; __device__ __forceinline__ void scan_rows(f32x2 (&X)[8], const ScanOps& o, const f32x4 (&b)[2], const f32x4 (&kd)[2], const f32x4 (&r)[2], const bool use_v, float& yA, float& yB) {
;     f32x2 aA = X[0] * o.kk[0].xy, aB = X[4] * o.kk[0].xy;
;     aA += X[1] * o.kk[0].zw; aB += X[5] * o.kk[0].zw;
;     aA += X[2] * o.kk[1].xy; aB += X[6] * o.kk[1].xy;
;     aA += X[3] * o.kk[1].zw; aB += X[7] * o.kk[1].zw;
;     const float saA = sum8(aA.x + aA.y), saB = sum8(aB.x + aB.y);
;     const f32x2 nA = (f32x2){-saA, -saA}, nB = (f32x2){-saB, -saB}, vA = (f32x2){o.v.x, o.v.x}, vB = (f32x2){o.v.y, o.v.y};
;     f32x2 tA, tB, accA, accB;
;     tA = X[0] * o.w[0].xy; tA += nA * b[0].xy; if (use_v) tA += vA * kd[0].xy; X[0] = tA; accA = tA * r[0].xy;
;     tB = X[4] * o.w[0].xy; tB += nB * b[0].xy; if (use_v) tB += vB * kd[0].xy; X[4] = tB; accB = tB * r[0].xy;
;     tA = X[1] * o.w[0].zw; tA += nA * b[0].zw; if (use_v) tA += vA * kd[0].zw; X[1] = tA; accA += tA * r[0].zw;
;     tB = X[5] * o.w[0].zw; tB += nB * b[0].zw; if (use_v) tB += vB * kd[0].zw; X[5] = tB; accB += tB * r[0].zw;
;     tA = X[2] * o.w[1].xy; tA += nA * b[1].xy; if (use_v) tA += vA * kd[1].xy; X[2] = tA; accA += tA * r[1].xy;
;     tB = X[6] * o.w[1].xy; tB += nB * b[1].xy; if (use_v) tB += vB * kd[1].xy; X[6] = tB; accB += tB * r[1].xy;
;     tA = X[3] * o.w[1].zw; tA += nA * b[1].zw; if (use_v) tA += vA * kd[1].zw; X[3] = tA; accA += tA * r[1].zw;
;     tB = X[7] * o.w[1].zw; tB += nB * b[1].zw; if (use_v) tB += vB * kd[1].zw; X[7] = tB; accB += tB * r[1].zw;
;     yA = sum8(accA.x + accA.y); yB = sum8(accB.x + accB.y);
; __device__ void phase_scan(int c, const bf16_t* PROJ, const float* k_k, const bf16_t* Wd, const bf16_t* Bd, const float* k_a, bf16_t* Y, bf16_t* Q, float* FS, float* sm) {
;     ...
;                 for (int i = 0; i < 16; i += 2) {
;                     float yA = 0.f, yB = 0.f;
;                     scan_ld(ob, obv, i + 1, B);
;                     if (roleP) A.v = (f32x2){0.f, 0.f};
;                     scan_step1(X, A, ob + i * 64, yA, yB);
;                     *(f32x2*)(obw + i * 16 + 2 * vp) = (f32x2){yA, yB};
;                     if (i + 2 < 16) scan_ld(ob, obv, i + 2, A);
;                     if (roleP) B.v = (f32x2){0.f, 0.f};
;                     scan_step1(X, B, ob + (i + 1) * 64, yA, yB);
;                     *(f32x2*)(obw + (i + 1) * 16 + 2 * vp) = (f32x2){yA, yB};
	ds_read_b128 v[128:131], v84 offset:1792
	ds_read_b128 v[132:135], v84 offset:1808
	ds_read_b128 v[136:139], v84 offset:5888
	ds_read_b128 v[140:143], v84 offset:5904
	ds_read_b128 v[144:147], v84 offset:9984
	ds_read_b128 v[148:151], v84 offset:10000
	ds_read_b128 v[160:163], v84 offset:18176
	ds_read_b128 v[164:167], v84 offset:18192
	v_pk_mul_f32 v[212:213], v[22:23], v[94:95]
	v_pk_mul_f32 v[216:217], v[14:15], v[94:95]
	v_pk_mul_f32 v[196:197], v[22:23], v[86:87]
	v_pk_mul_f32 v[204:205], v[14:15], v[86:87]
	v_pk_fma_f32 v[212:213], v[24:25], v[96:97], v[212:213]
	v_pk_fma_f32 v[216:217], v[16:17], v[96:97], v[216:217]
	v_pk_mul_f32 v[198:199], v[24:25], v[88:89]
	v_pk_mul_f32 v[206:207], v[16:17], v[88:89]
	v_pk_fma_f32 v[212:213], v[18:19], v[98:99], v[212:213]
	v_pk_fma_f32 v[216:217], v[10:11], v[98:99], v[216:217]
	v_pk_fma_f32 v[212:213], v[20:21], v[100:101], v[212:213]
	v_pk_fma_f32 v[216:217], v[12:13], v[100:101], v[216:217]
	v_add_f32_e32 v226, v222, v223
	v_add_f32_e32 v227, v224, v225
	v_add_f32_e32 v220, v212, v213
	v_add_f32_e32 v221, v216, v217
	v_pk_mul_f32 v[200:201], v[18:19], v[90:91]
	v_pk_mul_f32 v[208:209], v[10:11], v[90:91]
	ds_write_b64 v228, v[226:227] offset:2880
	v_add_f32_dpp v220, v220, v220 quad_perm:[1,0,3,2] row_mask:0xf bank_mask:0xf bound_ctrl:1
	v_add_f32_dpp v221, v221, v221 quad_perm:[1,0,3,2] row_mask:0xf bank_mask:0xf bound_ctrl:1
	v_pk_mul_f32 v[202:203], v[20:21], v[92:93]
	v_pk_mul_f32 v[210:211], v[12:13], v[92:93]
	v_add_f32_dpp v220, v220, v220 quad_perm:[2,3,0,1] row_mask:0xf bank_mask:0xf bound_ctrl:1
	v_add_f32_dpp v221, v221, v221 quad_perm:[2,3,0,1] row_mask:0xf bank_mask:0xf bound_ctrl:1
	s_nop 0
	v_add_f32_dpp v220, v220, v220 row_half_mirror row_mask:0xf bank_mask:0xf bound_ctrl:1
	v_add_f32_dpp v221, v221, v221 row_half_mirror row_mask:0xf bank_mask:0xf bound_ctrl:1
	s_nop 0
	v_pk_fma_f32 v[22:23], v[220:221], v[102:103], v[196:197] op_sel_hi:[0,1,1] neg_lo:[1,0,0] neg_hi:[1,0,0]
	v_pk_fma_f32 v[14:15], v[220:221], v[102:103], v[204:205] op_sel:[1,0,0] op_sel_hi:[1,1,1] neg_lo:[1,0,0] neg_hi:[1,0,0]
	v_pk_fma_f32 v[24:25], v[220:221], v[104:105], v[198:199] op_sel_hi:[0,1,1] neg_lo:[1,0,0] neg_hi:[1,0,0]
	v_pk_fma_f32 v[16:17], v[220:221], v[104:105], v[206:207] op_sel:[1,0,0] op_sel_hi:[1,1,1] neg_lo:[1,0,0] neg_hi:[1,0,0]
	v_pk_fma_f32 v[18:19], v[220:221], v[106:107], v[200:201] op_sel_hi:[0,1,1] neg_lo:[1,0,0] neg_hi:[1,0,0]
	v_pk_fma_f32 v[10:11], v[220:221], v[106:107], v[208:209] op_sel:[1,0,0] op_sel_hi:[1,1,1] neg_lo:[1,0,0] neg_hi:[1,0,0]
	v_pk_fma_f32 v[20:21], v[220:221], v[108:109], v[202:203] op_sel_hi:[0,1,1] neg_lo:[1,0,0] neg_hi:[1,0,0]
	v_pk_fma_f32 v[12:13], v[220:221], v[108:109], v[210:211] op_sel:[1,0,0] op_sel_hi:[1,1,1] neg_lo:[1,0,0] neg_hi:[1,0,0]
	v_pk_mul_f32 v[222:223], v[22:23], v[118:119]
	v_pk_mul_f32 v[224:225], v[14:15], v[118:119]
	v_pk_fma_f32 v[222:223], v[24:25], v[120:121], v[222:223]
	v_pk_fma_f32 v[224:225], v[16:17], v[120:121], v[224:225]
	v_pk_fma_f32 v[222:223], v[18:19], v[122:123], v[222:223]
	v_pk_fma_f32 v[224:225], v[10:11], v[122:123], v[224:225]
	v_pk_fma_f32 v[222:223], v[20:21], v[124:125], v[222:223]
	v_pk_fma_f32 v[224:225], v[12:13], v[124:125], v[224:225]
	s_waitcnt lgkmcnt(0)
	ds_read_b128 v[86:89], v84 offset:2048
	ds_read_b128 v[90:93], v84 offset:2064
	ds_read_b128 v[94:97], v84 offset:6144
	ds_read_b128 v[98:101], v84 offset:6160
	ds_read_b128 v[102:105], v84 offset:10240
	ds_read_b128 v[106:109], v84 offset:10256
	ds_read_b128 v[118:121], v84 offset:18432
	ds_read_b128 v[122:125], v84 offset:18448
	v_pk_mul_f32 v[212:213], v[22:23], v[136:137]
	v_pk_mul_f32 v[216:217], v[14:15], v[136:137]
	v_pk_mul_f32 v[196:197], v[22:23], v[128:129]
	v_pk_mul_f32 v[204:205], v[14:15], v[128:129]
	v_pk_fma_f32 v[212:213], v[24:25], v[138:139], v[212:213]
	v_pk_fma_f32 v[216:217], v[16:17], v[138:139], v[216:217]
	v_pk_mul_f32 v[198:199], v[24:25], v[130:131]
	v_pk_mul_f32 v[206:207], v[16:17], v[130:131]
	v_pk_fma_f32 v[212:213], v[18:19], v[140:141], v[212:213]
	v_pk_fma_f32 v[216:217], v[10:11], v[140:141], v[216:217]
	v_pk_fma_f32 v[212:213], v[20:21], v[142:143], v[212:213]
	v_pk_fma_f32 v[216:217], v[12:13], v[142:143], v[216:217]
	v_add_f32_e32 v226, v222, v223
	v_add_f32_e32 v227, v224, v225
	v_add_f32_e32 v220, v212, v213
	v_add_f32_e32 v221, v216, v217
	v_pk_mul_f32 v[200:201], v[18:19], v[132:133]
	v_pk_mul_f32 v[208:209], v[10:11], v[132:133]
	ds_write_b64 v228, v[226:227] offset:3456
	v_add_f32_dpp v220, v220, v220 quad_perm:[1,0,3,2] row_mask:0xf bank_mask:0xf bound_ctrl:1
	v_add_f32_dpp v221, v221, v221 quad_perm:[1,0,3,2] row_mask:0xf bank_mask:0xf bound_ctrl:1
	v_pk_mul_f32 v[202:203], v[20:21], v[134:135]
	v_pk_mul_f32 v[210:211], v[12:13], v[134:135]
	v_add_f32_dpp v220, v220, v220 quad_perm:[2,3,0,1] row_mask:0xf bank_mask:0xf bound_ctrl:1
	v_add_f32_dpp v221, v221, v221 quad_perm:[2,3,0,1] row_mask:0xf bank_mask:0xf bound_ctrl:1
	s_nop 0
	v_add_f32_dpp v220, v220, v220 row_half_mirror row_mask:0xf bank_mask:0xf bound_ctrl:1
	v_add_f32_dpp v221, v221, v221 row_half_mirror row_mask:0xf bank_mask:0xf bound_ctrl:1
	s_nop 0
	v_pk_fma_f32 v[22:23], v[220:221], v[144:145], v[196:197] op_sel_hi:[0,1,1] neg_lo:[1,0,0] neg_hi:[1,0,0]
	v_pk_fma_f32 v[14:15], v[220:221], v[144:145], v[204:205] op_sel:[1,0,0] op_sel_hi:[1,1,1] neg_lo:[1,0,0] neg_hi:[1,0,0]
	v_pk_fma_f32 v[24:25], v[220:221], v[146:147], v[198:199] op_sel_hi:[0,1,1] neg_lo:[1,0,0] neg_hi:[1,0,0]
	v_pk_fma_f32 v[16:17], v[220:221], v[146:147], v[206:207] op_sel:[1,0,0] op_sel_hi:[1,1,1] neg_lo:[1,0,0] neg_hi:[1,0,0]
	v_pk_fma_f32 v[18:19], v[220:221], v[148:149], v[200:201] op_sel_hi:[0,1,1] neg_lo:[1,0,0] neg_hi:[1,0,0]
	v_pk_fma_f32 v[10:11], v[220:221], v[148:149], v[208:209] op_sel:[1,0,0] op_sel_hi:[1,1,1] neg_lo:[1,0,0] neg_hi:[1,0,0]
	v_pk_fma_f32 v[20:21], v[220:221], v[150:151], v[202:203] op_sel_hi:[0,1,1] neg_lo:[1,0,0] neg_hi:[1,0,0]
	v_pk_fma_f32 v[12:13], v[220:221], v[150:151], v[210:211] op_sel:[1,0,0] op_sel_hi:[1,1,1] neg_lo:[1,0,0] neg_hi:[1,0,0]
	v_pk_mul_f32 v[222:223], v[22:23], v[160:161]
	v_pk_mul_f32 v[224:225], v[14:15], v[160:161]
	v_pk_fma_f32 v[222:223], v[24:25], v[162:163], v[222:223]
	v_pk_fma_f32 v[224:225], v[16:17], v[162:163], v[224:225]
	v_pk_fma_f32 v[222:223], v[18:19], v[164:165], v[222:223]
	v_pk_fma_f32 v[224:225], v[10:11], v[164:165], v[224:225]
	v_pk_fma_f32 v[222:223], v[20:21], v[166:167], v[222:223]
	v_pk_fma_f32 v[224:225], v[12:13], v[166:167], v[224:225]
	s_waitcnt lgkmcnt(0)
; __device__ __forceinline__ void scan_rows(f32x2 (&X)[8], const ScanOps& o, const f32x4 (&b)[2], const f32x4 (&kd)[2], const f32x4 (&r)[2], const bool use_v, float& yA, float& yB) {
;     f32x2 aA = X[0] * o.kk[0].xy, aB = X[4] * o.kk[0].xy;
;     aA += X[1] * o.kk[0].zw; aB += X[5] * o.kk[0].zw;
;     aA += X[2] * o.kk[1].xy; aB += X[6] * o.kk[1].xy;
;     aA += X[3] * o.kk[1].zw; aB += X[7] * o.kk[1].zw;
;     const float saA = sum8(aA.x + aA.y), saB = sum8(aB.x + aB.y);
;     const f32x2 nA = (f32x2){-saA, -saA}, nB = (f32x2){-saB, -saB}, vA = (f32x2){o.v.x, o.v.x}, vB = (f32x2){o.v.y, o.v.y};
;     f32x2 tA, tB, accA, accB;
;     tA = X[0] * o.w[0].xy; tA += nA * b[0].xy; if (use_v) tA += vA * kd[0].xy; X[0] = tA; accA = tA * r[0].xy;
;     tB = X[4] * o.w[0].xy; tB += nB * b[0].xy; if (use_v) tB += vB * kd[0].xy; X[4] = tB; accB = tB * r[0].xy;
;     tA = X[1] * o.w[0].zw; tA += nA * b[0].zw; if (use_v) tA += vA * kd[0].zw; X[1] = tA; accA += tA * r[0].zw;
;     tB = X[5] * o.w[0].zw; tB += nB * b[0].zw; if (use_v) tB += vB * kd[0].zw; X[5] = tB; accB += tB * r[0].zw;
;     tA = X[2] * o.w[1].xy; tA += nA * b[1].xy; if (use_v) tA += vA * kd[1].xy; X[2] = tA; accA += tA * r[1].xy;
;     tB = X[6] * o.w[1].xy; tB += nB * b[1].xy; if (use_v) tB += vB * kd[1].xy; X[6] = tB; accB += tB * r[1].xy;
;     tA = X[3] * o.w[1].zw; tA += nA * b[1].zw; if (use_v) tA += vA * kd[1].zw; X[3] = tA; accA += tA * r[1].zw;
;     tB = X[7] * o.w[1].zw; tB += nB * b[1].zw; if (use_v) tB += vB * kd[1].zw; X[7] = tB; accB += tB * r[1].zw;
;     yA = sum8(accA.x + accA.y); yB = sum8(accB.x + accB.y);
; __device__ void phase_scan(int c, const bf16_t* PROJ, const float* k_k, const bf16_t* Wd, const bf16_t* Bd, const float* k_a, bf16_t* Y, bf16_t* Q, float* FS, float* sm) {
;     ...
;                 for (int i = 0; i < 16; i += 2) {
;                     float yA = 0.f, yB = 0.f;
;                     scan_ld(ob, obv, i + 1, B);
;                     if (roleP) A.v = (f32x2){0.f, 0.f};
;                     scan_step1(X, A, ob + i * 64, yA, yB);
;                     *(f32x2*)(obw + i * 16 + 2 * vp) = (f32x2){yA, yB};
;                     if (i + 2 < 16) scan_ld(ob, obv, i + 2, A);
;                     if (roleP) B.v = (f32x2){0.f, 0.f};
;                     scan_step1(X, B, ob + (i + 1) * 64, yA, yB);
;                     *(f32x2*)(obw + (i + 1) * 16 + 2 * vp) = (f32x2){yA, yB};
	ds_read_b128 v[128:131], v84 offset:2304
	ds_read_b128 v[132:135], v84 offset:2320
	ds_read_b128 v[136:139], v84 offset:6400
	ds_read_b128 v[140:143], v84 offset:6416
	ds_read_b128 v[144:147], v84 offset:10496
	ds_read_b128 v[148:151], v84 offset:10512
	ds_read_b128 v[160:163], v84 offset:18688
	ds_read_b128 v[164:167], v84 offset:18704
	v_pk_mul_f32 v[212:213], v[22:23], v[94:95]
	v_pk_mul_f32 v[216:217], v[14:15], v[94:95]
	v_pk_mul_f32 v[196:197], v[22:23], v[86:87]
	v_pk_mul_f32 v[204:205], v[14:15], v[86:87]
	v_pk_fma_f32 v[212:213], v[24:25], v[96:97], v[212:213]
	v_pk_fma_f32 v[216:217], v[16:17], v[96:97], v[216:217]
	v_pk_mul_f32 v[198:199], v[24:25], v[88:89]
	v_pk_mul_f32 v[206:207], v[16:17], v[88:89]
	v_pk_fma_f32 v[212:213], v[18:19], v[98:99], v[212:213]
	v_pk_fma_f32 v[216:217], v[10:11], v[98:99], v[216:217]
	v_pk_fma_f32 v[212:213], v[20:21], v[100:101], v[212:213]
	v_pk_fma_f32 v[216:217], v[12:13], v[100:101], v[216:217]
	v_add_f32_e32 v226, v222, v223
	v_add_f32_e32 v227, v224, v225
	v_add_f32_e32 v220, v212, v213
	v_add_f32_e32 v221, v216, v217
	v_pk_mul_f32 v[200:201], v[18:19], v[90:91]
	v_pk_mul_f32 v[208:209], v[10:11], v[90:91]
	ds_write_b64 v228, v[226:227] offset:4032
	v_add_f32_dpp v220, v220, v220 quad_perm:[1,0,3,2] row_mask:0xf bank_mask:0xf bound_ctrl:1
	v_add_f32_dpp v221, v221, v221 quad_perm:[1,0,3,2] row_mask:0xf bank_mask:0xf bound_ctrl:1
	v_pk_mul_f32 v[202:203], v[20:21], v[92:93]
	v_pk_mul_f32 v[210:211], v[12:13], v[92:93]
	v_add_f32_dpp v220, v220, v220 quad_perm:[2,3,0,1] row_mask:0xf bank_mask:0xf bound_ctrl:1
	v_add_f32_dpp v221, v221, v221 quad_perm:[2,3,0,1] row_mask:0xf bank_mask:0xf bound_ctrl:1
	s_nop 0
	v_add_f32_dpp v220, v220, v220 row_half_mirror row_mask:0xf bank_mask:0xf bound_ctrl:1
	v_add_f32_dpp v221, v221, v221 row_half_mirror row_mask:0xf bank_mask:0xf bound_ctrl:1
	s_nop 0
	v_pk_fma_f32 v[22:23], v[220:221], v[102:103], v[196:197] op_sel_hi:[0,1,1] neg_lo:[1,0,0] neg_hi:[1,0,0]
	v_pk_fma_f32 v[14:15], v[220:221], v[102:103], v[204:205] op_sel:[1,0,0] op_sel_hi:[1,1,1] neg_lo:[1,0,0] neg_hi:[1,0,0]
	v_pk_fma_f32 v[24:25], v[220:221], v[104:105], v[198:199] op_sel_hi:[0,1,1] neg_lo:[1,0,0] neg_hi:[1,0,0]
	v_pk_fma_f32 v[16:17], v[220:221], v[104:105], v[206:207] op_sel:[1,0,0] op_sel_hi:[1,1,1] neg_lo:[1,0,0] neg_hi:[1,0,0]
	v_pk_fma_f32 v[18:19], v[220:221], v[106:107], v[200:201] op_sel_hi:[0,1,1] neg_lo:[1,0,0] neg_hi:[1,0,0]
	v_pk_fma_f32 v[10:11], v[220:221], v[106:107], v[208:209] op_sel:[1,0,0] op_sel_hi:[1,1,1] neg_lo:[1,0,0] neg_hi:[1,0,0]
	v_pk_fma_f32 v[20:21], v[220:221], v[108:109], v[202:203] op_sel_hi:[0,1,1] neg_lo:[1,0,0] neg_hi:[1,0,0]
	v_pk_fma_f32 v[12:13], v[220:221], v[108:109], v[210:211] op_sel:[1,0,0] op_sel_hi:[1,1,1] neg_lo:[1,0,0] neg_hi:[1,0,0]
	v_pk_mul_f32 v[222:223], v[22:23], v[118:119]
	v_pk_mul_f32 v[224:225], v[14:15], v[118:119]
	v_pk_fma_f32 v[222:223], v[24:25], v[120:121], v[222:223]
	v_pk_fma_f32 v[224:225], v[16:17], v[120:121], v[224:225]
	v_pk_fma_f32 v[222:223], v[18:19], v[122:123], v[222:223]
	v_pk_fma_f32 v[224:225], v[10:11], v[122:123], v[224:225]
	v_pk_fma_f32 v[222:223], v[20:21], v[124:125], v[222:223]
	v_pk_fma_f32 v[224:225], v[12:13], v[124:125], v[224:225]
	s_waitcnt lgkmcnt(0)
	ds_read_b128 v[86:89], v84 offset:2560
	ds_read_b128 v[90:93], v84 offset:2576
	ds_read_b128 v[94:97], v84 offset:6656
	ds_read_b128 v[98:101], v84 offset:6672
	ds_read_b128 v[102:105], v84 offset:10752
	ds_read_b128 v[106:109], v84 offset:10768
	ds_read_b128 v[118:121], v84 offset:18944
	ds_read_b128 v[122:125], v84 offset:18960
	v_pk_mul_f32 v[212:213], v[22:23], v[136:137]
	v_pk_mul_f32 v[216:217], v[14:15], v[136:137]
	v_pk_mul_f32 v[196:197], v[22:23], v[128:129]
	v_pk_mul_f32 v[204:205], v[14:15], v[128:129]
	v_pk_fma_f32 v[212:213], v[24:25], v[138:139], v[212:213]
	v_pk_fma_f32 v[216:217], v[16:17], v[138:139], v[216:217]
	v_pk_mul_f32 v[198:199], v[24:25], v[130:131]
	v_pk_mul_f32 v[206:207], v[16:17], v[130:131]
	v_pk_fma_f32 v[212:213], v[18:19], v[140:141], v[212:213]
	v_pk_fma_f32 v[216:217], v[10:11], v[140:141], v[216:217]
	v_pk_fma_f32 v[212:213], v[20:21], v[142:143], v[212:213]
	v_pk_fma_f32 v[216:217], v[12:13], v[142:143], v[216:217]
	v_add_f32_e32 v226, v222, v223
	v_add_f32_e32 v227, v224, v225
	v_add_f32_e32 v220, v212, v213
	v_add_f32_e32 v221, v216, v217
	v_pk_mul_f32 v[200:201], v[18:19], v[132:133]
	v_pk_mul_f32 v[208:209], v[10:11], v[132:133]
	ds_write_b64 v228, v[226:227] offset:4608
	v_add_f32_dpp v220, v220, v220 quad_perm:[1,0,3,2] row_mask:0xf bank_mask:0xf bound_ctrl:1
	v_add_f32_dpp v221, v221, v221 quad_perm:[1,0,3,2] row_mask:0xf bank_mask:0xf bound_ctrl:1
	v_pk_mul_f32 v[202:203], v[20:21], v[134:135]
	v_pk_mul_f32 v[210:211], v[12:13], v[134:135]
	v_add_f32_dpp v220, v220, v220 quad_perm:[2,3,0,1] row_mask:0xf bank_mask:0xf bound_ctrl:1
	v_add_f32_dpp v221, v221, v221 quad_perm:[2,3,0,1] row_mask:0xf bank_mask:0xf bound_ctrl:1
	s_nop 0
	v_add_f32_dpp v220, v220, v220 row_half_mirror row_mask:0xf bank_mask:0xf bound_ctrl:1
	v_add_f32_dpp v221, v221, v221 row_half_mirror row_mask:0xf bank_mask:0xf bound_ctrl:1
	s_nop 0
	v_pk_fma_f32 v[22:23], v[220:221], v[144:145], v[196:197] op_sel_hi:[0,1,1] neg_lo:[1,0,0] neg_hi:[1,0,0]
	v_pk_fma_f32 v[14:15], v[220:221], v[144:145], v[204:205] op_sel:[1,0,0] op_sel_hi:[1,1,1] neg_lo:[1,0,0] neg_hi:[1,0,0]
	v_pk_fma_f32 v[24:25], v[220:221], v[146:147], v[198:199] op_sel_hi:[0,1,1] neg_lo:[1,0,0] neg_hi:[1,0,0]
	v_pk_fma_f32 v[16:17], v[220:221], v[146:147], v[206:207] op_sel:[1,0,0] op_sel_hi:[1,1,1] neg_lo:[1,0,0] neg_hi:[1,0,0]
	v_pk_fma_f32 v[18:19], v[220:221], v[148:149], v[200:201] op_sel_hi:[0,1,1] neg_lo:[1,0,0] neg_hi:[1,0,0]
	v_pk_fma_f32 v[10:11], v[220:221], v[148:149], v[208:209] op_sel:[1,0,0] op_sel_hi:[1,1,1] neg_lo:[1,0,0] neg_hi:[1,0,0]
	v_pk_fma_f32 v[20:21], v[220:221], v[150:151], v[202:203] op_sel_hi:[0,1,1] neg_lo:[1,0,0] neg_hi:[1,0,0]
	v_pk_fma_f32 v[12:13], v[220:221], v[150:151], v[210:211] op_sel:[1,0,0] op_sel_hi:[1,1,1] neg_lo:[1,0,0] neg_hi:[1,0,0]
	v_pk_mul_f32 v[222:223], v[22:23], v[160:161]
	v_pk_mul_f32 v[224:225], v[14:15], v[160:161]
	v_pk_fma_f32 v[222:223], v[24:25], v[162:163], v[222:223]
	v_pk_fma_f32 v[224:225], v[16:17], v[162:163], v[224:225]
	v_pk_fma_f32 v[222:223], v[18:19], v[164:165], v[222:223]
	v_pk_fma_f32 v[224:225], v[10:11], v[164:165], v[224:225]
	v_pk_fma_f32 v[222:223], v[20:21], v[166:167], v[222:223]
	v_pk_fma_f32 v[224:225], v[12:13], v[166:167], v[224:225]
	s_waitcnt lgkmcnt(0)
; __device__ __forceinline__ void scan_rows(f32x2 (&X)[8], const ScanOps& o, const f32x4 (&b)[2], const f32x4 (&kd)[2], const f32x4 (&r)[2], const bool use_v, float& yA, float& yB) {
;     f32x2 aA = X[0] * o.kk[0].xy, aB = X[4] * o.kk[0].xy;
;     aA += X[1] * o.kk[0].zw; aB += X[5] * o.kk[0].zw;
;     aA += X[2] * o.kk[1].xy; aB += X[6] * o.kk[1].xy;
;     aA += X[3] * o.kk[1].zw; aB += X[7] * o.kk[1].zw;
;     const float saA = sum8(aA.x + aA.y), saB = sum8(aB.x + aB.y);
;     const f32x2 nA = (f32x2){-saA, -saA}, nB = (f32x2){-saB, -saB}, vA = (f32x2){o.v.x, o.v.x}, vB = (f32x2){o.v.y, o.v.y};
;     f32x2 tA, tB, accA, accB;
;     tA = X[0] * o.w[0].xy; tA += nA * b[0].xy; if (use_v) tA += vA * kd[0].xy; X[0] = tA; accA = tA * r[0].xy;
;     tB = X[4] * o.w[0].xy; tB += nB * b[0].xy; if (use_v) tB += vB * kd[0].xy; X[4] = tB; accB = tB * r[0].xy;
;     tA = X[1] * o.w[0].zw; tA += nA * b[0].zw; if (use_v) tA += vA * kd[0].zw; X[1] = tA; accA += tA * r[0].zw;
;     tB = X[5] * o.w[0].zw; tB += nB * b[0].zw; if (use_v) tB += vB * kd[0].zw; X[5] = tB; accB += tB * r[0].zw;
;     tA = X[2] * o.w[1].xy; tA += nA * b[1].xy; if (use_v) tA += vA * kd[1].xy; X[2] = tA; accA += tA * r[1].xy;
;     tB = X[6] * o.w[1].xy; tB += nB * b[1].xy; if (use_v) tB += vB * kd[1].xy; X[6] = tB; accB += tB * r[1].xy;
;     tA = X[3] * o.w[1].zw; tA += nA * b[1].zw; if (use_v) tA += vA * kd[1].zw; X[3] = tA; accA += tA * r[1].zw;
;     tB = X[7] * o.w[1].zw; tB += nB * b[1].zw; if (use_v) tB += vB * kd[1].zw; X[7] = tB; accB += tB * r[1].zw;
;     yA = sum8(accA.x + accA.y); yB = sum8(accB.x + accB.y);
; __device__ void phase_scan(int c, const bf16_t* PROJ, const float* k_k, const bf16_t* Wd, const bf16_t* Bd, const float* k_a, bf16_t* Y, bf16_t* Q, float* FS, float* sm) {
;     ...
;                 for (int i = 0; i < 16; i += 2) {
;                     float yA = 0.f, yB = 0.f;
;                     scan_ld(ob, obv, i + 1, B);
;                     if (roleP) A.v = (f32x2){0.f, 0.f};
;                     scan_step1(X, A, ob + i * 64, yA, yB);
;                     *(f32x2*)(obw + i * 16 + 2 * vp) = (f32x2){yA, yB};
;                     if (i + 2 < 16) scan_ld(ob, obv, i + 2, A);
;                     if (roleP) B.v = (f32x2){0.f, 0.f};
;                     scan_step1(X, B, ob + (i + 1) * 64, yA, yB);
;                     *(f32x2*)(obw + (i + 1) * 16 + 2 * vp) = (f32x2){yA, yB};
	ds_read_b128 v[128:131], v84 offset:2816
	ds_read_b128 v[132:135], v84 offset:2832
	ds_read_b128 v[136:139], v84 offset:6912
	ds_read_b128 v[140:143], v84 offset:6928
	ds_read_b128 v[144:147], v84 offset:11008
	ds_read_b128 v[148:151], v84 offset:11024
	ds_read_b128 v[160:163], v84 offset:19200
	ds_read_b128 v[164:167], v84 offset:19216
	v_pk_mul_f32 v[212:213], v[22:23], v[94:95]
	v_pk_mul_f32 v[216:217], v[14:15], v[94:95]
	v_pk_mul_f32 v[196:197], v[22:23], v[86:87]
	v_pk_mul_f32 v[204:205], v[14:15], v[86:87]
	v_pk_fma_f32 v[212:213], v[24:25], v[96:97], v[212:213]
	v_pk_fma_f32 v[216:217], v[16:17], v[96:97], v[216:217]
	v_pk_mul_f32 v[198:199], v[24:25], v[88:89]
	v_pk_mul_f32 v[206:207], v[16:17], v[88:89]
	v_pk_fma_f32 v[212:213], v[18:19], v[98:99], v[212:213]
	v_pk_fma_f32 v[216:217], v[10:11], v[98:99], v[216:217]
	v_pk_fma_f32 v[212:213], v[20:21], v[100:101], v[212:213]
	v_pk_fma_f32 v[216:217], v[12:13], v[100:101], v[216:217]
	v_add_f32_e32 v226, v222, v223
	v_add_f32_e32 v227, v224, v225
	v_add_f32_e32 v220, v212, v213
	v_add_f32_e32 v221, v216, v217
	v_pk_mul_f32 v[200:201], v[18:19], v[90:91]
	v_pk_mul_f32 v[208:209], v[10:11], v[90:91]
	ds_write_b64 v228, v[226:227] offset:5184
	v_add_f32_dpp v220, v220, v220 quad_perm:[1,0,3,2] row_mask:0xf bank_mask:0xf bound_ctrl:1
	v_add_f32_dpp v221, v221, v221 quad_perm:[1,0,3,2] row_mask:0xf bank_mask:0xf bound_ctrl:1
	v_pk_mul_f32 v[202:203], v[20:21], v[92:93]
	v_pk_mul_f32 v[210:211], v[12:13], v[92:93]
	v_add_f32_dpp v220, v220, v220 quad_perm:[2,3,0,1] row_mask:0xf bank_mask:0xf bound_ctrl:1
	v_add_f32_dpp v221, v221, v221 quad_perm:[2,3,0,1] row_mask:0xf bank_mask:0xf bound_ctrl:1
	s_nop 0
	v_add_f32_dpp v220, v220, v220 row_half_mirror row_mask:0xf bank_mask:0xf bound_ctrl:1
	v_add_f32_dpp v221, v221, v221 row_half_mirror row_mask:0xf bank_mask:0xf bound_ctrl:1
	s_nop 0
	v_pk_fma_f32 v[22:23], v[220:221], v[102:103], v[196:197] op_sel_hi:[0,1,1] neg_lo:[1,0,0] neg_hi:[1,0,0]
	v_pk_fma_f32 v[14:15], v[220:221], v[102:103], v[204:205] op_sel:[1,0,0] op_sel_hi:[1,1,1] neg_lo:[1,0,0] neg_hi:[1,0,0]
	v_pk_fma_f32 v[24:25], v[220:221], v[104:105], v[198:199] op_sel_hi:[0,1,1] neg_lo:[1,0,0] neg_hi:[1,0,0]
	v_pk_fma_f32 v[16:17], v[220:221], v[104:105], v[206:207] op_sel:[1,0,0] op_sel_hi:[1,1,1] neg_lo:[1,0,0] neg_hi:[1,0,0]
	v_pk_fma_f32 v[18:19], v[220:221], v[106:107], v[200:201] op_sel_hi:[0,1,1] neg_lo:[1,0,0] neg_hi:[1,0,0]
	v_pk_fma_f32 v[10:11], v[220:221], v[106:107], v[208:209] op_sel:[1,0,0] op_sel_hi:[1,1,1] neg_lo:[1,0,0] neg_hi:[1,0,0]
	v_pk_fma_f32 v[20:21], v[220:221], v[108:109], v[202:203] op_sel_hi:[0,1,1] neg_lo:[1,0,0] neg_hi:[1,0,0]
	v_pk_fma_f32 v[12:13], v[220:221], v[108:109], v[210:211] op_sel:[1,0,0] op_sel_hi:[1,1,1] neg_lo:[1,0,0] neg_hi:[1,0,0]
	v_pk_mul_f32 v[222:223], v[22:23], v[118:119]
	v_pk_mul_f32 v[224:225], v[14:15], v[118:119]
	v_pk_fma_f32 v[222:223], v[24:25], v[120:121], v[222:223]
	v_pk_fma_f32 v[224:225], v[16:17], v[120:121], v[224:225]
	v_pk_fma_f32 v[222:223], v[18:19], v[122:123], v[222:223]
	v_pk_fma_f32 v[224:225], v[10:11], v[122:123], v[224:225]
	v_pk_fma_f32 v[222:223], v[20:21], v[124:125], v[222:223]
	v_pk_fma_f32 v[224:225], v[12:13], v[124:125], v[224:225]
	s_waitcnt lgkmcnt(0)
	ds_read_b128 v[86:89], v84 offset:3072
	ds_read_b128 v[90:93], v84 offset:3088
	ds_read_b128 v[94:97], v84 offset:7168
	ds_read_b128 v[98:101], v84 offset:7184
	ds_read_b128 v[102:105], v84 offset:11264
	ds_read_b128 v[106:109], v84 offset:11280
	ds_read_b128 v[118:121], v84 offset:19456
	ds_read_b128 v[122:125], v84 offset:19472
	v_pk_mul_f32 v[212:213], v[22:23], v[136:137]
	v_pk_mul_f32 v[216:217], v[14:15], v[136:137]
	v_pk_mul_f32 v[196:197], v[22:23], v[128:129]
	v_pk_mul_f32 v[204:205], v[14:15], v[128:129]
	v_pk_fma_f32 v[212:213], v[24:25], v[138:139], v[212:213]
	v_pk_fma_f32 v[216:217], v[16:17], v[138:139], v[216:217]
	v_pk_mul_f32 v[198:199], v[24:25], v[130:131]
	v_pk_mul_f32 v[206:207], v[16:17], v[130:131]
	v_pk_fma_f32 v[212:213], v[18:19], v[140:141], v[212:213]
	v_pk_fma_f32 v[216:217], v[10:11], v[140:141], v[216:217]
	v_pk_fma_f32 v[212:213], v[20:21], v[142:143], v[212:213]
	v_pk_fma_f32 v[216:217], v[12:13], v[142:143], v[216:217]
	v_add_f32_e32 v226, v222, v223
	v_add_f32_e32 v227, v224, v225
	v_add_f32_e32 v220, v212, v213
	v_add_f32_e32 v221, v216, v217
	v_pk_mul_f32 v[200:201], v[18:19], v[132:133]
	v_pk_mul_f32 v[208:209], v[10:11], v[132:133]
	ds_write_b64 v228, v[226:227] offset:5760
	v_add_f32_dpp v220, v220, v220 quad_perm:[1,0,3,2] row_mask:0xf bank_mask:0xf bound_ctrl:1
	v_add_f32_dpp v221, v221, v221 quad_perm:[1,0,3,2] row_mask:0xf bank_mask:0xf bound_ctrl:1
	v_pk_mul_f32 v[202:203], v[20:21], v[134:135]
	v_pk_mul_f32 v[210:211], v[12:13], v[134:135]
	v_add_f32_dpp v220, v220, v220 quad_perm:[2,3,0,1] row_mask:0xf bank_mask:0xf bound_ctrl:1
	v_add_f32_dpp v221, v221, v221 quad_perm:[2,3,0,1] row_mask:0xf bank_mask:0xf bound_ctrl:1
	s_nop 0
	v_add_f32_dpp v220, v220, v220 row_half_mirror row_mask:0xf bank_mask:0xf bound_ctrl:1
	v_add_f32_dpp v221, v221, v221 row_half_mirror row_mask:0xf bank_mask:0xf bound_ctrl:1
	s_nop 0
	v_pk_fma_f32 v[22:23], v[220:221], v[144:145], v[196:197] op_sel_hi:[0,1,1] neg_lo:[1,0,0] neg_hi:[1,0,0]
	v_pk_fma_f32 v[14:15], v[220:221], v[144:145], v[204:205] op_sel:[1,0,0] op_sel_hi:[1,1,1] neg_lo:[1,0,0] neg_hi:[1,0,0]
	v_pk_fma_f32 v[24:25], v[220:221], v[146:147], v[198:199] op_sel_hi:[0,1,1] neg_lo:[1,0,0] neg_hi:[1,0,0]
	v_pk_fma_f32 v[16:17], v[220:221], v[146:147], v[206:207] op_sel:[1,0,0] op_sel_hi:[1,1,1] neg_lo:[1,0,0] neg_hi:[1,0,0]
	v_pk_fma_f32 v[18:19], v[220:221], v[148:149], v[200:201] op_sel_hi:[0,1,1] neg_lo:[1,0,0] neg_hi:[1,0,0]
	v_pk_fma_f32 v[10:11], v[220:221], v[148:149], v[208:209] op_sel:[1,0,0] op_sel_hi:[1,1,1] neg_lo:[1,0,0] neg_hi:[1,0,0]
	v_pk_fma_f32 v[20:21], v[220:221], v[150:151], v[202:203] op_sel_hi:[0,1,1] neg_lo:[1,0,0] neg_hi:[1,0,0]
	v_pk_fma_f32 v[12:13], v[220:221], v[150:151], v[210:211] op_sel:[1,0,0] op_sel_hi:[1,1,1] neg_lo:[1,0,0] neg_hi:[1,0,0]
	v_pk_mul_f32 v[222:223], v[22:23], v[160:161]
	v_pk_mul_f32 v[224:225], v[14:15], v[160:161]
	v_pk_fma_f32 v[222:223], v[24:25], v[162:163], v[222:223]
	v_pk_fma_f32 v[224:225], v[16:17], v[162:163], v[224:225]
	v_pk_fma_f32 v[222:223], v[18:19], v[164:165], v[222:223]
	v_pk_fma_f32 v[224:225], v[10:11], v[164:165], v[224:225]
	v_pk_fma_f32 v[222:223], v[20:21], v[166:167], v[222:223]
	v_pk_fma_f32 v[224:225], v[12:13], v[166:167], v[224:225]
	s_waitcnt lgkmcnt(0)
; __device__ __forceinline__ void scan_rows(f32x2 (&X)[8], const ScanOps& o, const f32x4 (&b)[2], const f32x4 (&kd)[2], const f32x4 (&r)[2], const bool use_v, float& yA, float& yB) {
;     f32x2 aA = X[0] * o.kk[0].xy, aB = X[4] * o.kk[0].xy;
;     aA += X[1] * o.kk[0].zw; aB += X[5] * o.kk[0].zw;
;     aA += X[2] * o.kk[1].xy; aB += X[6] * o.kk[1].xy;
;     aA += X[3] * o.kk[1].zw; aB += X[7] * o.kk[1].zw;
;     const float saA = sum8(aA.x + aA.y), saB = sum8(aB.x + aB.y);
;     const f32x2 nA = (f32x2){-saA, -saA}, nB = (f32x2){-saB, -saB}, vA = (f32x2){o.v.x, o.v.x}, vB = (f32x2){o.v.y, o.v.y};
;     f32x2 tA, tB, accA, accB;
;     tA = X[0] * o.w[0].xy; tA += nA * b[0].xy; if (use_v) tA += vA * kd[0].xy; X[0] = tA; accA = tA * r[0].xy;
;     tB = X[4] * o.w[0].xy; tB += nB * b[0].xy; if (use_v) tB += vB * kd[0].xy; X[4] = tB; accB = tB * r[0].xy;
;     tA = X[1] * o.w[0].zw; tA += nA * b[0].zw; if (use_v) tA += vA * kd[0].zw; X[1] = tA; accA += tA * r[0].zw;
;     tB = X[5] * o.w[0].zw; tB += nB * b[0].zw; if (use_v) tB += vB * kd[0].zw; X[5] = tB; accB += tB * r[0].zw;
;     tA = X[2] * o.w[1].xy; tA += nA * b[1].xy; if (use_v) tA += vA * kd[1].xy; X[2] = tA; accA += tA * r[1].xy;
;     tB = X[6] * o.w[1].xy; tB += nB * b[1].xy; if (use_v) tB += vB * kd[1].xy; X[6] = tB; accB += tB * r[1].xy;
;     tA = X[3] * o.w[1].zw; tA += nA * b[1].zw; if (use_v) tA += vA * kd[1].zw; X[3] = tA; accA += tA * r[1].zw;
;     tB = X[7] * o.w[1].zw; tB += nB * b[1].zw; if (use_v) tB += vB * kd[1].zw; X[7] = tB; accB += tB * r[1].zw;
;     yA = sum8(accA.x + accA.y); yB = sum8(accB.x + accB.y);
; __device__ void phase_scan(int c, const bf16_t* PROJ, const float* k_k, const bf16_t* Wd, const bf16_t* Bd, const float* k_a, bf16_t* Y, bf16_t* Q, float* FS, float* sm) {
;     ...
;                 for (int i = 0; i < 16; i += 2) {
;                     float yA = 0.f, yB = 0.f;
;                     scan_ld(ob, obv, i + 1, B);
;                     if (roleP) A.v = (f32x2){0.f, 0.f};
;                     scan_step1(X, A, ob + i * 64, yA, yB);
;                     *(f32x2*)(obw + i * 16 + 2 * vp) = (f32x2){yA, yB};
;                     if (i + 2 < 16) scan_ld(ob, obv, i + 2, A);
;                     if (roleP) B.v = (f32x2){0.f, 0.f};
;                     scan_step1(X, B, ob + (i + 1) * 64, yA, yB);
;                     *(f32x2*)(obw + (i + 1) * 16 + 2 * vp) = (f32x2){yA, yB};
	ds_read_b128 v[128:131], v84 offset:3328
	ds_read_b128 v[132:135], v84 offset:3344
	ds_read_b128 v[136:139], v84 offset:7424
	ds_read_b128 v[140:143], v84 offset:7440
	ds_read_b128 v[144:147], v84 offset:11520
	ds_read_b128 v[148:151], v84 offset:11536
	ds_read_b128 v[160:163], v84 offset:19712
	ds_read_b128 v[164:167], v84 offset:19728
	v_pk_mul_f32 v[212:213], v[22:23], v[94:95]
	v_pk_mul_f32 v[216:217], v[14:15], v[94:95]
	v_pk_mul_f32 v[196:197], v[22:23], v[86:87]
	v_pk_mul_f32 v[204:205], v[14:15], v[86:87]
	v_pk_fma_f32 v[212:213], v[24:25], v[96:97], v[212:213]
	v_pk_fma_f32 v[216:217], v[16:17], v[96:97], v[216:217]
	v_pk_mul_f32 v[198:199], v[24:25], v[88:89]
	v_pk_mul_f32 v[206:207], v[16:17], v[88:89]
	v_pk_fma_f32 v[212:213], v[18:19], v[98:99], v[212:213]
	v_pk_fma_f32 v[216:217], v[10:11], v[98:99], v[216:217]
	v_pk_fma_f32 v[212:213], v[20:21], v[100:101], v[212:213]
	v_pk_fma_f32 v[216:217], v[12:13], v[100:101], v[216:217]
	v_add_f32_e32 v226, v222, v223
	v_add_f32_e32 v227, v224, v225
	v_add_f32_e32 v220, v212, v213
	v_add_f32_e32 v221, v216, v217
	v_pk_mul_f32 v[200:201], v[18:19], v[90:91]
	v_pk_mul_f32 v[208:209], v[10:11], v[90:91]
	ds_write_b64 v228, v[226:227] offset:6336
	v_add_f32_dpp v220, v220, v220 quad_perm:[1,0,3,2] row_mask:0xf bank_mask:0xf bound_ctrl:1
	v_add_f32_dpp v221, v221, v221 quad_perm:[1,0,3,2] row_mask:0xf bank_mask:0xf bound_ctrl:1
	v_pk_mul_f32 v[202:203], v[20:21], v[92:93]
	v_pk_mul_f32 v[210:211], v[12:13], v[92:93]
	v_add_f32_dpp v220, v220, v220 quad_perm:[2,3,0,1] row_mask:0xf bank_mask:0xf bound_ctrl:1
	v_add_f32_dpp v221, v221, v221 quad_perm:[2,3,0,1] row_mask:0xf bank_mask:0xf bound_ctrl:1
	s_nop 0
	v_add_f32_dpp v220, v220, v220 row_half_mirror row_mask:0xf bank_mask:0xf bound_ctrl:1
	v_add_f32_dpp v221, v221, v221 row_half_mirror row_mask:0xf bank_mask:0xf bound_ctrl:1
	s_nop 0
	v_pk_fma_f32 v[22:23], v[220:221], v[102:103], v[196:197] op_sel_hi:[0,1,1] neg_lo:[1,0,0] neg_hi:[1,0,0]
	v_pk_fma_f32 v[14:15], v[220:221], v[102:103], v[204:205] op_sel:[1,0,0] op_sel_hi:[1,1,1] neg_lo:[1,0,0] neg_hi:[1,0,0]
	v_pk_fma_f32 v[24:25], v[220:221], v[104:105], v[198:199] op_sel_hi:[0,1,1] neg_lo:[1,0,0] neg_hi:[1,0,0]
	v_pk_fma_f32 v[16:17], v[220:221], v[104:105], v[206:207] op_sel:[1,0,0] op_sel_hi:[1,1,1] neg_lo:[1,0,0] neg_hi:[1,0,0]
	v_pk_fma_f32 v[18:19], v[220:221], v[106:107], v[200:201] op_sel_hi:[0,1,1] neg_lo:[1,0,0] neg_hi:[1,0,0]
	v_pk_fma_f32 v[10:11], v[220:221], v[106:107], v[208:209] op_sel:[1,0,0] op_sel_hi:[1,1,1] neg_lo:[1,0,0] neg_hi:[1,0,0]
	v_pk_fma_f32 v[20:21], v[220:221], v[108:109], v[202:203] op_sel_hi:[0,1,1] neg_lo:[1,0,0] neg_hi:[1,0,0]
	v_pk_fma_f32 v[12:13], v[220:221], v[108:109], v[210:211] op_sel:[1,0,0] op_sel_hi:[1,1,1] neg_lo:[1,0,0] neg_hi:[1,0,0]
	v_pk_mul_f32 v[222:223], v[22:23], v[118:119]
	v_pk_mul_f32 v[224:225], v[14:15], v[118:119]
	v_pk_fma_f32 v[222:223], v[24:25], v[120:121], v[222:223]
	v_pk_fma_f32 v[224:225], v[16:17], v[120:121], v[224:225]
	v_pk_fma_f32 v[222:223], v[18:19], v[122:123], v[222:223]
	v_pk_fma_f32 v[224:225], v[10:11], v[122:123], v[224:225]
	v_pk_fma_f32 v[222:223], v[20:21], v[124:125], v[222:223]
	v_pk_fma_f32 v[224:225], v[12:13], v[124:125], v[224:225]
	s_waitcnt lgkmcnt(0)
	ds_read_b128 v[86:89], v84 offset:3584
	ds_read_b128 v[90:93], v84 offset:3600
	ds_read_b128 v[94:97], v84 offset:7680
	ds_read_b128 v[98:101], v84 offset:7696
	ds_read_b128 v[102:105], v84 offset:11776
	ds_read_b128 v[106:109], v84 offset:11792
	ds_read_b128 v[118:121], v84 offset:19968
	ds_read_b128 v[122:125], v84 offset:19984
	v_pk_mul_f32 v[212:213], v[22:23], v[136:137]
	v_pk_mul_f32 v[216:217], v[14:15], v[136:137]
	v_pk_mul_f32 v[196:197], v[22:23], v[128:129]
	v_pk_mul_f32 v[204:205], v[14:15], v[128:129]
	v_pk_fma_f32 v[212:213], v[24:25], v[138:139], v[212:213]
	v_pk_fma_f32 v[216:217], v[16:17], v[138:139], v[216:217]
	v_pk_mul_f32 v[198:199], v[24:25], v[130:131]
	v_pk_mul_f32 v[206:207], v[16:17], v[130:131]
	v_pk_fma_f32 v[212:213], v[18:19], v[140:141], v[212:213]
	v_pk_fma_f32 v[216:217], v[10:11], v[140:141], v[216:217]
	v_pk_fma_f32 v[212:213], v[20:21], v[142:143], v[212:213]
	v_pk_fma_f32 v[216:217], v[12:13], v[142:143], v[216:217]
	v_add_f32_e32 v226, v222, v223
	v_add_f32_e32 v227, v224, v225
	v_add_f32_e32 v220, v212, v213
	v_add_f32_e32 v221, v216, v217
	v_pk_mul_f32 v[200:201], v[18:19], v[132:133]
	v_pk_mul_f32 v[208:209], v[10:11], v[132:133]
	ds_write_b64 v228, v[226:227] offset:6912
	v_add_f32_dpp v220, v220, v220 quad_perm:[1,0,3,2] row_mask:0xf bank_mask:0xf bound_ctrl:1
	v_add_f32_dpp v221, v221, v221 quad_perm:[1,0,3,2] row_mask:0xf bank_mask:0xf bound_ctrl:1
	v_pk_mul_f32 v[202:203], v[20:21], v[134:135]
	v_pk_mul_f32 v[210:211], v[12:13], v[134:135]
	v_add_f32_dpp v220, v220, v220 quad_perm:[2,3,0,1] row_mask:0xf bank_mask:0xf bound_ctrl:1
	v_add_f32_dpp v221, v221, v221 quad_perm:[2,3,0,1] row_mask:0xf bank_mask:0xf bound_ctrl:1
	s_nop 0
	v_add_f32_dpp v220, v220, v220 row_half_mirror row_mask:0xf bank_mask:0xf bound_ctrl:1
	v_add_f32_dpp v221, v221, v221 row_half_mirror row_mask:0xf bank_mask:0xf bound_ctrl:1
	s_nop 0
	v_pk_fma_f32 v[22:23], v[220:221], v[144:145], v[196:197] op_sel_hi:[0,1,1] neg_lo:[1,0,0] neg_hi:[1,0,0]
	v_pk_fma_f32 v[14:15], v[220:221], v[144:145], v[204:205] op_sel:[1,0,0] op_sel_hi:[1,1,1] neg_lo:[1,0,0] neg_hi:[1,0,0]
	v_pk_fma_f32 v[24:25], v[220:221], v[146:147], v[198:199] op_sel_hi:[0,1,1] neg_lo:[1,0,0] neg_hi:[1,0,0]
	v_pk_fma_f32 v[16:17], v[220:221], v[146:147], v[206:207] op_sel:[1,0,0] op_sel_hi:[1,1,1] neg_lo:[1,0,0] neg_hi:[1,0,0]
	v_pk_fma_f32 v[18:19], v[220:221], v[148:149], v[200:201] op_sel_hi:[0,1,1] neg_lo:[1,0,0] neg_hi:[1,0,0]
	v_pk_fma_f32 v[10:11], v[220:221], v[148:149], v[208:209] op_sel:[1,0,0] op_sel_hi:[1,1,1] neg_lo:[1,0,0] neg_hi:[1,0,0]
	v_pk_fma_f32 v[20:21], v[220:221], v[150:151], v[202:203] op_sel_hi:[0,1,1] neg_lo:[1,0,0] neg_hi:[1,0,0]
	v_pk_fma_f32 v[12:13], v[220:221], v[150:151], v[210:211] op_sel:[1,0,0] op_sel_hi:[1,1,1] neg_lo:[1,0,0] neg_hi:[1,0,0]
	v_pk_mul_f32 v[222:223], v[22:23], v[160:161]
	v_pk_mul_f32 v[224:225], v[14:15], v[160:161]
	v_pk_fma_f32 v[222:223], v[24:25], v[162:163], v[222:223]
	v_pk_fma_f32 v[224:225], v[16:17], v[162:163], v[224:225]
	v_pk_fma_f32 v[222:223], v[18:19], v[164:165], v[222:223]
	v_pk_fma_f32 v[224:225], v[10:11], v[164:165], v[224:225]
	v_pk_fma_f32 v[222:223], v[20:21], v[166:167], v[222:223]
	v_pk_fma_f32 v[224:225], v[12:13], v[166:167], v[224:225]
	s_waitcnt lgkmcnt(0)
; __device__ __forceinline__ void scan_rows(f32x2 (&X)[8], const ScanOps& o, const f32x4 (&b)[2], const f32x4 (&kd)[2], const f32x4 (&r)[2], const bool use_v, float& yA, float& yB) {
;     f32x2 aA = X[0] * o.kk[0].xy, aB = X[4] * o.kk[0].xy;
;     aA += X[1] * o.kk[0].zw; aB += X[5] * o.kk[0].zw;
;     aA += X[2] * o.kk[1].xy; aB += X[6] * o.kk[1].xy;
;     aA += X[3] * o.kk[1].zw; aB += X[7] * o.kk[1].zw;
;     const float saA = sum8(aA.x + aA.y), saB = sum8(aB.x + aB.y);
;     const f32x2 nA = (f32x2){-saA, -saA}, nB = (f32x2){-saB, -saB}, vA = (f32x2){o.v.x, o.v.x}, vB = (f32x2){o.v.y, o.v.y};
;     f32x2 tA, tB, accA, accB;
;     tA = X[0] * o.w[0].xy; tA += nA * b[0].xy; if (use_v) tA += vA * kd[0].xy; X[0] = tA; accA = tA * r[0].xy;
;     tB = X[4] * o.w[0].xy; tB += nB * b[0].xy; if (use_v) tB += vB * kd[0].xy; X[4] = tB; accB = tB * r[0].xy;
;     tA = X[1] * o.w[0].zw; tA += nA * b[0].zw; if (use_v) tA += vA * kd[0].zw; X[1] = tA; accA += tA * r[0].zw;
;     tB = X[5] * o.w[0].zw; tB += nB * b[0].zw; if (use_v) tB += vB * kd[0].zw; X[5] = tB; accB += tB * r[0].zw;
;     tA = X[2] * o.w[1].xy; tA += nA * b[1].xy; if (use_v) tA += vA * kd[1].xy; X[2] = tA; accA += tA * r[1].xy;
;     tB = X[6] * o.w[1].xy; tB += nB * b[1].xy; if (use_v) tB += vB * kd[1].xy; X[6] = tB; accB += tB * r[1].xy;
;     tA = X[3] * o.w[1].zw; tA += nA * b[1].zw; if (use_v) tA += vA * kd[1].zw; X[3] = tA; accA += tA * r[1].zw;
;     tB = X[7] * o.w[1].zw; tB += nB * b[1].zw; if (use_v) tB += vB * kd[1].zw; X[7] = tB; accB += tB * r[1].zw;
;     yA = sum8(accA.x + accA.y); yB = sum8(accB.x + accB.y);
; __device__ void phase_scan(int c, const bf16_t* PROJ, const float* k_k, const bf16_t* Wd, const bf16_t* Bd, const float* k_a, bf16_t* Y, bf16_t* Q, float* FS, float* sm) {
;     ...
;                 for (int i = 0; i < 16; i += 2) {
;                     float yA = 0.f, yB = 0.f;
;                     scan_ld(ob, obv, i + 1, B);
;                     if (roleP) A.v = (f32x2){0.f, 0.f};
;                     scan_step1(X, A, ob + i * 64, yA, yB);
;                     *(f32x2*)(obw + i * 16 + 2 * vp) = (f32x2){yA, yB};
;                     if (i + 2 < 16) scan_ld(ob, obv, i + 2, A);
;                     if (roleP) B.v = (f32x2){0.f, 0.f};
;                     scan_step1(X, B, ob + (i + 1) * 64, yA, yB);
;                     *(f32x2*)(obw + (i + 1) * 16 + 2 * vp) = (f32x2){yA, yB};
	ds_read_b128 v[128:131], v84 offset:3840
	ds_read_b128 v[132:135], v84 offset:3856
	ds_read_b128 v[136:139], v84 offset:7936
	ds_read_b128 v[140:143], v84 offset:7952
	ds_read_b128 v[144:147], v84 offset:12032
	ds_read_b128 v[148:151], v84 offset:12048
	ds_read_b128 v[160:163], v84 offset:20224
	ds_read_b128 v[164:167], v84 offset:20240
	v_pk_mul_f32 v[212:213], v[22:23], v[94:95]
	v_pk_mul_f32 v[216:217], v[14:15], v[94:95]
	v_pk_mul_f32 v[196:197], v[22:23], v[86:87]
	v_pk_mul_f32 v[204:205], v[14:15], v[86:87]
	v_pk_fma_f32 v[212:213], v[24:25], v[96:97], v[212:213]
	v_pk_fma_f32 v[216:217], v[16:17], v[96:97], v[216:217]
	v_pk_mul_f32 v[198:199], v[24:25], v[88:89]
	v_pk_mul_f32 v[206:207], v[16:17], v[88:89]
	v_pk_fma_f32 v[212:213], v[18:19], v[98:99], v[212:213]
	v_pk_fma_f32 v[216:217], v[10:11], v[98:99], v[216:217]
	v_pk_fma_f32 v[212:213], v[20:21], v[100:101], v[212:213]
	v_pk_fma_f32 v[216:217], v[12:13], v[100:101], v[216:217]
	v_add_f32_e32 v226, v222, v223
	v_add_f32_e32 v227, v224, v225
	v_add_f32_e32 v220, v212, v213
	v_add_f32_e32 v221, v216, v217
	v_pk_mul_f32 v[200:201], v[18:19], v[90:91]
	v_pk_mul_f32 v[208:209], v[10:11], v[90:91]
	ds_write_b64 v228, v[226:227] offset:7488
	v_add_f32_dpp v220, v220, v220 quad_perm:[1,0,3,2] row_mask:0xf bank_mask:0xf bound_ctrl:1
	v_add_f32_dpp v221, v221, v221 quad_perm:[1,0,3,2] row_mask:0xf bank_mask:0xf bound_ctrl:1
	v_pk_mul_f32 v[202:203], v[20:21], v[92:93]
	v_pk_mul_f32 v[210:211], v[12:13], v[92:93]
	v_add_f32_dpp v220, v220, v220 quad_perm:[2,3,0,1] row_mask:0xf bank_mask:0xf bound_ctrl:1
	v_add_f32_dpp v221, v221, v221 quad_perm:[2,3,0,1] row_mask:0xf bank_mask:0xf bound_ctrl:1
	s_nop 0
	v_add_f32_dpp v220, v220, v220 row_half_mirror row_mask:0xf bank_mask:0xf bound_ctrl:1
	v_add_f32_dpp v221, v221, v221 row_half_mirror row_mask:0xf bank_mask:0xf bound_ctrl:1
	s_nop 0
	v_pk_fma_f32 v[22:23], v[220:221], v[102:103], v[196:197] op_sel_hi:[0,1,1] neg_lo:[1,0,0] neg_hi:[1,0,0]
	v_pk_fma_f32 v[14:15], v[220:221], v[102:103], v[204:205] op_sel:[1,0,0] op_sel_hi:[1,1,1] neg_lo:[1,0,0] neg_hi:[1,0,0]
	v_pk_fma_f32 v[24:25], v[220:221], v[104:105], v[198:199] op_sel_hi:[0,1,1] neg_lo:[1,0,0] neg_hi:[1,0,0]
	v_pk_fma_f32 v[16:17], v[220:221], v[104:105], v[206:207] op_sel:[1,0,0] op_sel_hi:[1,1,1] neg_lo:[1,0,0] neg_hi:[1,0,0]
	v_pk_fma_f32 v[18:19], v[220:221], v[106:107], v[200:201] op_sel_hi:[0,1,1] neg_lo:[1,0,0] neg_hi:[1,0,0]
	v_pk_fma_f32 v[10:11], v[220:221], v[106:107], v[208:209] op_sel:[1,0,0] op_sel_hi:[1,1,1] neg_lo:[1,0,0] neg_hi:[1,0,0]
	v_pk_fma_f32 v[20:21], v[220:221], v[108:109], v[202:203] op_sel_hi:[0,1,1] neg_lo:[1,0,0] neg_hi:[1,0,0]
	v_pk_fma_f32 v[12:13], v[220:221], v[108:109], v[210:211] op_sel:[1,0,0] op_sel_hi:[1,1,1] neg_lo:[1,0,0] neg_hi:[1,0,0]
	v_pk_mul_f32 v[222:223], v[22:23], v[118:119]
	v_pk_mul_f32 v[224:225], v[14:15], v[118:119]
	v_pk_fma_f32 v[222:223], v[24:25], v[120:121], v[222:223]
	v_pk_fma_f32 v[224:225], v[16:17], v[120:121], v[224:225]
	v_pk_fma_f32 v[222:223], v[18:19], v[122:123], v[222:223]
	v_pk_fma_f32 v[224:225], v[10:11], v[122:123], v[224:225]
	v_pk_fma_f32 v[222:223], v[20:21], v[124:125], v[222:223]
	v_pk_fma_f32 v[224:225], v[12:13], v[124:125], v[224:225]
	s_waitcnt lgkmcnt(0)
	v_pk_mul_f32 v[212:213], v[22:23], v[136:137]
	v_pk_mul_f32 v[216:217], v[14:15], v[136:137]
	v_pk_mul_f32 v[196:197], v[22:23], v[128:129]
	v_pk_mul_f32 v[204:205], v[14:15], v[128:129]
	v_pk_fma_f32 v[212:213], v[24:25], v[138:139], v[212:213]
	v_pk_fma_f32 v[216:217], v[16:17], v[138:139], v[216:217]
	v_pk_mul_f32 v[198:199], v[24:25], v[130:131]
	v_pk_mul_f32 v[206:207], v[16:17], v[130:131]
	v_pk_fma_f32 v[212:213], v[18:19], v[140:141], v[212:213]
	v_pk_fma_f32 v[216:217], v[10:11], v[140:141], v[216:217]
	v_pk_fma_f32 v[212:213], v[20:21], v[142:143], v[212:213]
	v_pk_fma_f32 v[216:217], v[12:13], v[142:143], v[216:217]
	v_add_f32_e32 v226, v222, v223
	v_add_f32_e32 v227, v224, v225
	v_add_f32_e32 v220, v212, v213
	v_add_f32_e32 v221, v216, v217
	v_pk_mul_f32 v[200:201], v[18:19], v[132:133]
	v_pk_mul_f32 v[208:209], v[10:11], v[132:133]
	ds_write_b64 v228, v[226:227] offset:8064
	v_add_f32_dpp v220, v220, v220 quad_perm:[1,0,3,2] row_mask:0xf bank_mask:0xf bound_ctrl:1
	v_add_f32_dpp v221, v221, v221 quad_perm:[1,0,3,2] row_mask:0xf bank_mask:0xf bound_ctrl:1
	v_pk_mul_f32 v[202:203], v[20:21], v[134:135]
	v_pk_mul_f32 v[210:211], v[12:13], v[134:135]
	v_add_f32_dpp v220, v220, v220 quad_perm:[2,3,0,1] row_mask:0xf bank_mask:0xf bound_ctrl:1
	v_add_f32_dpp v221, v221, v221 quad_perm:[2,3,0,1] row_mask:0xf bank_mask:0xf bound_ctrl:1
	s_nop 0
	v_add_f32_dpp v220, v220, v220 row_half_mirror row_mask:0xf bank_mask:0xf bound_ctrl:1
	v_add_f32_dpp v221, v221, v221 row_half_mirror row_mask:0xf bank_mask:0xf bound_ctrl:1
	s_nop 0
	v_pk_fma_f32 v[22:23], v[220:221], v[144:145], v[196:197] op_sel_hi:[0,1,1] neg_lo:[1,0,0] neg_hi:[1,0,0]
	v_pk_fma_f32 v[14:15], v[220:221], v[144:145], v[204:205] op_sel:[1,0,0] op_sel_hi:[1,1,1] neg_lo:[1,0,0] neg_hi:[1,0,0]
	v_pk_fma_f32 v[24:25], v[220:221], v[146:147], v[198:199] op_sel_hi:[0,1,1] neg_lo:[1,0,0] neg_hi:[1,0,0]
	v_pk_fma_f32 v[16:17], v[220:221], v[146:147], v[206:207] op_sel:[1,0,0] op_sel_hi:[1,1,1] neg_lo:[1,0,0] neg_hi:[1,0,0]
	v_pk_fma_f32 v[18:19], v[220:221], v[148:149], v[200:201] op_sel_hi:[0,1,1] neg_lo:[1,0,0] neg_hi:[1,0,0]
	v_pk_fma_f32 v[10:11], v[220:221], v[148:149], v[208:209] op_sel:[1,0,0] op_sel_hi:[1,1,1] neg_lo:[1,0,0] neg_hi:[1,0,0]
	v_pk_fma_f32 v[20:21], v[220:221], v[150:151], v[202:203] op_sel_hi:[0,1,1] neg_lo:[1,0,0] neg_hi:[1,0,0]
	v_pk_fma_f32 v[12:13], v[220:221], v[150:151], v[210:211] op_sel:[1,0,0] op_sel_hi:[1,1,1] neg_lo:[1,0,0] neg_hi:[1,0,0]
	v_pk_mul_f32 v[222:223], v[22:23], v[160:161]
	v_pk_mul_f32 v[224:225], v[14:15], v[160:161]
	v_pk_fma_f32 v[222:223], v[24:25], v[162:163], v[222:223]
	v_pk_fma_f32 v[224:225], v[16:17], v[162:163], v[224:225]
	v_pk_fma_f32 v[222:223], v[18:19], v[164:165], v[222:223]
	v_pk_fma_f32 v[224:225], v[10:11], v[164:165], v[224:225]
	v_pk_fma_f32 v[222:223], v[20:21], v[166:167], v[222:223]
	v_pk_fma_f32 v[224:225], v[12:13], v[166:167], v[224:225]
	v_add_f32_e32 v226, v222, v223
	v_add_f32_e32 v227, v224, v225
	ds_write_b64 v228, v[226:227] offset:8640
; __device__ __forceinline__ unsigned pack2(float lo, float hi) { return (unsigned)f2bf(lo) | ((unsigned)f2bf(hi) << 16); }
; __device__ __forceinline__ float sum8(float x) { x += dpp_xor1(x); x += dpp_xor2(x); x += dpp_hmirror(x); return x; }
; __device__ __forceinline__ void scan_rows(f32x2 (&X)[8], const ScanOps& o, const f32x4 (&b)[2], const f32x4 (&kd)[2], const f32x4 (&r)[2], const bool use_v, float& yA, float& yB) {
;     ...
;     yA = sum8(accA.x + accA.y); yB = sum8(accB.x + accB.y);
; __device__ void phase_scan(int c, const bf16_t* PROJ, const float* k_k, const bf16_t* Wd, const bf16_t* Bd, const float* k_a, bf16_t* Y, bf16_t* Q, float* FS, float* sm) {
;     ...
;                 __builtin_amdgcn_wave_barrier(); asm volatile("s_waitcnt lgkmcnt(0)" ::: "memory");
;                 { const int st = lane >> 2, v4 = (lane & 3) * 4;
;                   const int g = g0 + ci * 16 + st; const int t = dir ? (L - 1 - g) : g;
;                   const size_t o = ((size_t)dir * TCH + (size_t)seq * L + t) * 512 + h * 64 + wq * 16 + v4;
;                   const f32x4 yv = *(const f32x4*)(obw + st * 16 + v4);
;                   uint2 pk; pk.x = pack2(yv[0], yv[1]); pk.y = pack2(yv[2], yv[3]); *(uint2*)(gout + o) = pk; }
.Lscan_body_end:
	s_waitcnt lgkmcnt(0)
	v_add_u32_e32 v84, s40, v82
	v_cndmask_b32_e64 v88, v83, v84, s[10:11]
	ds_read_b128 v[196:199], v229
	ds_read_b128 v[200:203], v229 offset:64
	ds_read_b128 v[204:207], v229 offset:128
	ds_read_b128 v[208:211], v229 offset:192
	ds_read_b128 v[212:215], v229 offset:256
	ds_read_b128 v[216:219], v229 offset:320
	ds_read_b128 v[220:223], v229 offset:384
	ds_read_b128 v[224:227], v229 offset:448
	v_ashrrev_i32_e32 v89, 31, v88
	v_lshl_add_u64 v[88:89], v[60:61], 0, v[88:89]
	v_lshlrev_b64 v[88:89], 10, v[88:89]
	v_lshl_add_u64 v[88:89], v[62:63], 0, v[88:89]
	s_waitcnt lgkmcnt(0)
	v_pk_add_f32 v[196:197], v[196:197], v[200:201]
	v_pk_add_f32 v[204:205], v[204:205], v[208:209]
	v_pk_add_f32 v[212:213], v[212:213], v[216:217]
	v_pk_add_f32 v[220:221], v[220:221], v[224:225]
	v_pk_add_f32 v[198:199], v[198:199], v[202:203]
	v_pk_add_f32 v[206:207], v[206:207], v[210:211]
	v_pk_add_f32 v[214:215], v[214:215], v[218:219]
	v_pk_add_f32 v[222:223], v[222:223], v[226:227]
	v_pk_add_f32 v[196:197], v[196:197], v[204:205]
	v_pk_add_f32 v[212:213], v[212:213], v[220:221]
	v_pk_add_f32 v[198:199], v[198:199], v[206:207]
	v_pk_add_f32 v[214:215], v[214:215], v[222:223]
	v_pk_add_f32 v[84:85], v[196:197], v[212:213]
	v_pk_add_f32 v[86:87], v[198:199], v[214:215]
	s_nop 0
	v_and_b32_sdwa v90, v86, v185 dst_sel:DWORD dst_unused:UNUSED_PAD src0_sel:WORD_1 src1_sel:DWORD
	v_and_b32_sdwa v91, v84, v185 dst_sel:DWORD dst_unused:UNUSED_PAD src0_sel:WORD_1 src1_sel:DWORD
	v_add3_u32 v84, v84, v91, s46
	v_add3_u32 v86, v86, v90, s46
	v_and_b32_sdwa v90, v87, v185 dst_sel:DWORD dst_unused:UNUSED_PAD src0_sel:WORD_1 src1_sel:DWORD
	v_and_b32_sdwa v91, v85, v185 dst_sel:DWORD dst_unused:UNUSED_PAD src0_sel:WORD_1 src1_sel:DWORD
	v_add3_u32 v87, v87, v90, s46
	v_add3_u32 v85, v85, v91, s46
	v_and_b32_e32 v87, 0xffff0000, v87
	v_and_b32_e32 v90, 0xffff0000, v85
	v_or_b32_sdwa v85, v87, v86 dst_sel:DWORD dst_unused:UNUSED_PAD src0_sel:DWORD src1_sel:WORD_1
	v_or_b32_sdwa v84, v90, v84 dst_sel:DWORD dst_unused:UNUSED_PAD src0_sel:DWORD src1_sel:WORD_1
	global_store_dwordx2 v[88:89], v[84:85], off
	s_branch .LBB0_71

; #define PG8_STAGE(bufoff, gbase, voff) do { _Pragma("unroll") for (int _i = 0; _i < 2; ++_i) \
;         __builtin_amdgcn_global_load_lds((const unsigned*)((const char*)(gbase) + (voff)[_i]), (LAS unsigned*)(lds + (bufoff) + ldsw + _i * 8192), 16, 0, 0); } while (0)
; #define PG8_LDA(dst, b, h) do { _Pragma("unroll") for (int m = 0; m < 4; ++m) _Pragma("unroll") for (int k = 0; k < 2; ++k) dst[m][k] = *(const LAS bf16x8*)(lds + PG8_SA(b, h) + aoff + m * 2048 + k * 1024); } while (0)
; #define PG8_LDB(dst, b, h) do { _Pragma("unroll") for (int n = 0; n < 2; ++n) _Pragma("unroll") for (int k = 0; k < 2; ++k) dst[n][k] = *(const LAS bf16x8*)(lds + PG8_SB(b, h) + boff + n * 2048 + k * 1024); } while (0)
; #define PG8_MMA(ai, bj, At, Bt) do { __builtin_amdgcn_s_setprio(1); _Pragma("unroll") for (int m = 0; m < 4; ++m) _Pragma("unroll") for (int n = 0; n < 2; ++n) _Pragma("unroll") for (int k = 0; k < 2; ++k) \
;         acc[ai][bj][m][n] = __builtin_amdgcn_mfma_f32_16x16x32_bf16(Bt[n][k], At[m][k], acc[ai][bj][m][n], 0, 0, 0); __builtin_amdgcn_s_setprio(0); } while (0)
; #define PG8_WAIT_L(n) asm volatile("s_waitcnt lgkmcnt(" #n ")" ::: "memory")
; #define PG8_BAR __builtin_amdgcn_s_barrier()
; #define PG8_SCHED __builtin_amdgcn_sched_barrier(0)
; template <class Epi>
; __device__ __forceinline__ void gemm_phase(LAS unsigned char* lds, const Gemm g, const Epi& E) {
;     ...
;         for (int t = 0; t < nt; t += 2) {
;             const bool last = (t == nt - 2);
;             const char* a1 = cA + (size_t)(t + 1) * kstep;
;             const char* a2 = last ? nA : cA + (size_t)(t + 2) * kstep; const char* b2 = last ? nB : cB + (size_t)(t + 2) * kstep;
;             const char* a3 = a2 + kstep; const char* b3 = b2 + kstep;
;             PG8_LDB(B0, 0, 0); PG8_SCHED; PG8_LDA(At, 0, 0); PG8_STAGE(PG8_SA(1, 1), a1 + hstepA, voffA);
;             PG8_WAIT_L(8); PG8_BAR; PG8_WAIT_L(0); PG8_MMA(0, 0, At, B0); PG8_BAR; PG8_SCHED;
;             PG8_LDB(B1, 0, 1); PG8_STAGE(PG8_SB(0, 0), b2, voffB);
;             PG8_BAR; PG8_WAIT_L(0); PG8_MMA(0, 1, At, B1); PG8_BAR;
;             PG8_LDA(At, 0, 1); PG8_STAGE(PG8_SA(0, 0), a2, voffA);
;             PG8_BAR; PG8_WAIT_L(0); PG8_MMA(1, 0, At, B0); PG8_BAR; PG8_SCHED;
.LBB0_277:
	s_add_u32 s17, s0, 0x100
	s_addc_u32 s18, s1, 0
	s_add_u32 s0, s14, 0x80
	s_addc_u32 s1, s15, 0
	s_mov_b32 s12, 0
.LBB0_278:
	s_add_i32 s19, s12, 2
	s_add_u32 s14, s0, 0x80
	s_addc_u32 s13, s1, 0
	s_add_i32 s20, 0, 0x10000
	v_add_u32_e32 v0, s20, v197
	ds_read_b128 v[132:135], v0
	ds_read_b128 v[136:139], v0 offset:1024
	ds_read_b128 v[140:143], v0 offset:2048
	ds_read_b128 v[144:147], v0 offset:3072
	s_cmp_eq_u32 s85, s12
	s_cselect_b32 s12, s22, s14
	s_cselect_b32 s13, s23, s13
	s_cselect_b32 s15, s5, s18
	s_cselect_b32 s14, s4, s17
	v_lshl_add_u64 v[2:3], s[0:1], 0, v[174:175]
	s_add_i32 m0, s8, 0xc000
	ds_read_b128 v[148:151], v205
	ds_read_b128 v[152:155], v205 offset:1024
	ds_read_b128 v[156:159], v205 offset:2048
	ds_read_b128 v[160:163], v205 offset:3072
	ds_read_b128 v[176:179], v205 offset:4096
	ds_read_b128 v[206:209], v205 offset:5120
	ds_read_b128 v[210:213], v205 offset:6144
	ds_read_b128 v[214:217], v205 offset:7168
	global_load_lds_dwordx4 v[2:3], off
	v_lshl_add_u64 v[2:3], s[0:1], 0, v[172:173]
	s_add_i32 m0, s8, 0xe000
	s_nop 0
	global_load_lds_dwordx4 v[2:3], off
	s_waitcnt lgkmcnt(8)
	s_barrier
	s_waitcnt lgkmcnt(0)
	s_setprio 1
	s_waitcnt lgkmcnt(0)
	v_mfma_f32_16x16x32_bf16 v[48:51], v[132:135], v[148:151], v[48:51]
	v_mfma_f32_16x16x32_bf16 v[52:55], v[140:143], v[148:151], v[52:55]
	v_mfma_f32_16x16x32_bf16 v[56:59], v[132:135], v[156:159], v[56:59]
	v_mfma_f32_16x16x32_bf16 v[60:63], v[140:143], v[156:159], v[60:63]
	v_mfma_f32_16x16x32_bf16 v[64:67], v[132:135], v[176:179], v[64:67]
	v_mfma_f32_16x16x32_bf16 v[68:71], v[140:143], v[176:179], v[68:71]
	v_mfma_f32_16x16x32_bf16 v[72:75], v[132:135], v[210:213], v[72:75]
	v_mfma_f32_16x16x32_bf16 v[76:79], v[140:143], v[210:213], v[76:79]
	v_mfma_f32_16x16x32_bf16 v[48:51], v[136:139], v[152:155], v[48:51]
	v_mfma_f32_16x16x32_bf16 v[52:55], v[144:147], v[152:155], v[52:55]
	v_mfma_f32_16x16x32_bf16 v[56:59], v[136:139], v[160:163], v[56:59]
	v_mfma_f32_16x16x32_bf16 v[60:63], v[144:147], v[160:163], v[60:63]
	v_mfma_f32_16x16x32_bf16 v[64:67], v[136:139], v[206:209], v[64:67]
	v_mfma_f32_16x16x32_bf16 v[68:71], v[144:147], v[206:209], v[68:71]
	v_mfma_f32_16x16x32_bf16 v[72:75], v[136:139], v[214:217], v[72:75]
	v_mfma_f32_16x16x32_bf16 v[76:79], v[144:147], v[214:217], v[76:79]
	s_setprio 0
	s_barrier
	s_add_i32 s21, 0, 0x14000
	s_add_i32 s20, s20, s7
	v_add_u32_e32 v0, s21, v197
	v_lshl_add_u64 v[234:235], s[14:15], 0, v[170:171]
	s_mov_b32 m0, s20
	ds_read_b128 v[218:221], v0
	ds_read_b128 v[222:225], v0 offset:1024
	ds_read_b128 v[226:229], v0 offset:2048
	ds_read_b128 v[230:233], v0 offset:3072
	global_load_lds_dwordx4 v[234:235], off
	v_lshl_add_u64 v[236:237], s[14:15], 0, v[166:167]
	s_add_i32 m0, s20, 0x2000
	s_nop 0
	global_load_lds_dwordx4 v[236:237], off
	s_barrier
	s_waitcnt lgkmcnt(0)
	s_setprio 1
	s_waitcnt lgkmcnt(0)
	v_mfma_f32_16x16x32_bf16 v[80:83], v[218:221], v[148:151], v[80:83]
	v_mfma_f32_16x16x32_bf16 v[84:87], v[226:229], v[148:151], v[84:87]
	v_mfma_f32_16x16x32_bf16 v[88:91], v[218:221], v[156:159], v[88:91]
	v_mfma_f32_16x16x32_bf16 v[92:95], v[226:229], v[156:159], v[92:95]
	v_mfma_f32_16x16x32_bf16 v[96:99], v[218:221], v[176:179], v[96:99]
	v_mfma_f32_16x16x32_bf16 v[100:103], v[226:229], v[176:179], v[100:103]
	v_mfma_f32_16x16x32_bf16 v[104:107], v[218:221], v[210:213], v[104:107]
	v_mfma_f32_16x16x32_bf16 v[108:111], v[226:229], v[210:213], v[108:111]
	v_mfma_f32_16x16x32_bf16 v[80:83], v[222:225], v[152:155], v[80:83]
	v_mfma_f32_16x16x32_bf16 v[84:87], v[230:233], v[152:155], v[84:87]
	v_mfma_f32_16x16x32_bf16 v[88:91], v[222:225], v[160:163], v[88:91]
	v_mfma_f32_16x16x32_bf16 v[92:95], v[230:233], v[160:163], v[92:95]
	v_mfma_f32_16x16x32_bf16 v[96:99], v[222:225], v[206:209], v[96:99]
	v_mfma_f32_16x16x32_bf16 v[100:103], v[230:233], v[206:209], v[100:103]
	v_mfma_f32_16x16x32_bf16 v[104:107], v[222:225], v[214:217], v[104:107]
	v_mfma_f32_16x16x32_bf16 v[108:111], v[230:233], v[214:217], v[108:111]
	s_setprio 0
	s_mov_b32 m0, s8
	v_lshl_add_u64 v[238:239], s[12:13], 0, v[168:169]
	s_barrier
	ds_read_b128 v[148:151], v205 offset:16384
	ds_read_b128 v[152:155], v205 offset:17408
	ds_read_b128 v[156:159], v205 offset:18432
	ds_read_b128 v[160:163], v205 offset:19456
	ds_read_b128 v[176:179], v205 offset:20480
	ds_read_b128 v[206:209], v205 offset:21504
	ds_read_b128 v[210:213], v205 offset:22528
	ds_read_b128 v[214:217], v205 offset:23552
	global_load_lds_dwordx4 v[238:239], off
	v_lshl_add_u64 v[240:241], s[12:13], 0, v[164:165]
	s_mov_b32 m0, s9
	s_nop 0
	global_load_lds_dwordx4 v[240:241], off
	s_barrier
	s_waitcnt lgkmcnt(0)
	s_setprio 1
	s_waitcnt lgkmcnt(0)
	v_mfma_f32_16x16x32_bf16 v[112:115], v[132:135], v[148:151], v[112:115]
	v_mfma_f32_16x16x32_bf16 v[116:119], v[140:143], v[148:151], v[116:119]
	v_mfma_f32_16x16x32_bf16 v[120:123], v[132:135], v[156:159], v[120:123]
	v_mfma_f32_16x16x32_bf16 v[124:127], v[140:143], v[156:159], v[124:127]
	v_mfma_f32_16x16x32_bf16 v[128:131], v[132:135], v[176:179], v[128:131]
	v_mfma_f32_16x16x32_bf16 v[36:39], v[140:143], v[176:179], v[36:39]
	v_mfma_f32_16x16x32_bf16 v[40:43], v[132:135], v[210:213], v[40:43]
	v_mfma_f32_16x16x32_bf16 v[44:47], v[140:143], v[210:213], v[44:47]
	v_mfma_f32_16x16x32_bf16 v[112:115], v[136:139], v[152:155], v[112:115]
	v_mfma_f32_16x16x32_bf16 v[116:119], v[144:147], v[152:155], v[116:119]
	v_mfma_f32_16x16x32_bf16 v[120:123], v[136:139], v[160:163], v[120:123]
	v_mfma_f32_16x16x32_bf16 v[124:127], v[144:147], v[160:163], v[124:127]
	v_mfma_f32_16x16x32_bf16 v[128:131], v[136:139], v[206:209], v[128:131]
	v_mfma_f32_16x16x32_bf16 v[36:39], v[144:147], v[206:209], v[36:39]
	v_mfma_f32_16x16x32_bf16 v[40:43], v[136:139], v[214:217], v[40:43]
	v_mfma_f32_16x16x32_bf16 v[44:47], v[144:147], v[214:217], v[44:47]
	s_setprio 0
	s_barrier
; #define PG8_STAGE(bufoff, gbase, voff) do { _Pragma("unroll") for (int _i = 0; _i < 2; ++_i) \
;         __builtin_amdgcn_global_load_lds((const unsigned*)((const char*)(gbase) + (voff)[_i]), (LAS unsigned*)(lds + (bufoff) + ldsw + _i * 8192), 16, 0, 0); } while (0)
; #define PG8_LDA(dst, b, h) do { _Pragma("unroll") for (int m = 0; m < 4; ++m) _Pragma("unroll") for (int k = 0; k < 2; ++k) dst[m][k] = *(const LAS bf16x8*)(lds + PG8_SA(b, h) + aoff + m * 2048 + k * 1024); } while (0)
; #define PG8_LDB(dst, b, h) do { _Pragma("unroll") for (int n = 0; n < 2; ++n) _Pragma("unroll") for (int k = 0; k < 2; ++k) dst[n][k] = *(const LAS bf16x8*)(lds + PG8_SB(b, h) + boff + n * 2048 + k * 1024); } while (0)
; #define PG8_MMA(ai, bj, At, Bt) do { __builtin_amdgcn_s_setprio(1); _Pragma("unroll") for (int m = 0; m < 4; ++m) _Pragma("unroll") for (int n = 0; n < 2; ++n) _Pragma("unroll") for (int k = 0; k < 2; ++k) \
;         acc[ai][bj][m][n] = __builtin_amdgcn_mfma_f32_16x16x32_bf16(Bt[n][k], At[m][k], acc[ai][bj][m][n], 0, 0, 0); __builtin_amdgcn_s_setprio(0); } while (0)
; #define PG8_WAIT_V(n) asm volatile("s_waitcnt vmcnt(" #n ")" ::: "memory")
; #define PG8_WAIT_L(n) asm volatile("s_waitcnt lgkmcnt(" #n ")" ::: "memory")
; #define PG8_BAR __builtin_amdgcn_s_barrier()
; #define PG8_SCHED __builtin_amdgcn_sched_barrier(0)
; template <class Epi>
; __device__ __forceinline__ void gemm_phase(LAS unsigned char* lds, const Gemm g, const Epi& E) {
;     ...
;             PG8_STAGE(PG8_SB(0, 1), b2 + hstepB, voffB);
;             PG8_WAIT_V(6); PG8_BAR; PG8_MMA(1, 1, At, B1); PG8_BAR;
;             PG8_LDB(B0, 1, 0); PG8_SCHED; PG8_LDA(At, 1, 0); PG8_STAGE(PG8_SA(0, 1), a2 + hstepA, voffA);
;             PG8_WAIT_L(8); PG8_BAR; PG8_WAIT_L(0); PG8_MMA(0, 0, At, B0); PG8_BAR; PG8_SCHED;
;             PG8_LDB(B1, 1, 1); PG8_STAGE(PG8_SB(1, 0), b3, voffB);
;             PG8_BAR; PG8_WAIT_L(0); PG8_MMA(0, 1, At, B1); PG8_BAR;
;             PG8_LDA(At, 1, 1); PG8_STAGE(PG8_SA(1, 0), a3, voffA);
;             PG8_BAR; PG8_WAIT_L(0); PG8_MMA(1, 0, At, B0); PG8_BAR; PG8_SCHED;
	s_add_u32 s14, s14, s49
	s_addc_u32 s15, s15, 0
	s_add_i32 s20, s21, s7
	v_lshl_add_u64 v[242:243], s[14:15], 0, v[170:171]
	s_mov_b32 m0, s20
	v_lshl_add_u64 v[244:245], s[14:15], 0, v[166:167]
	global_load_lds_dwordx4 v[242:243], off
	s_add_i32 m0, s20, 0x2000
	s_nop 0
	global_load_lds_dwordx4 v[244:245], off
	s_waitcnt vmcnt(6)
	s_barrier
	s_setprio 1
	v_mfma_f32_16x16x32_bf16 v[2:5], v[218:221], v[148:151], v[4:7]
	v_mfma_f32_16x16x32_bf16 v[6:9], v[226:229], v[148:151], v[8:11]
	v_mfma_f32_16x16x32_bf16 v[12:15], v[218:221], v[156:159], v[12:15]
	v_mfma_f32_16x16x32_bf16 v[16:19], v[226:229], v[156:159], v[16:19]
	v_mfma_f32_16x16x32_bf16 v[20:23], v[218:221], v[176:179], v[20:23]
	v_mfma_f32_16x16x32_bf16 v[24:27], v[226:229], v[176:179], v[24:27]
	v_mfma_f32_16x16x32_bf16 v[28:31], v[218:221], v[210:213], v[28:31]
	v_mfma_f32_16x16x32_bf16 v[32:35], v[226:229], v[210:213], v[32:35]
	v_mfma_f32_16x16x32_bf16 v[2:5], v[222:225], v[152:155], v[2:5]
	v_mfma_f32_16x16x32_bf16 v[8:11], v[230:233], v[152:155], v[6:9]
	v_mfma_f32_16x16x32_bf16 v[12:15], v[222:225], v[160:163], v[12:15]
	v_mfma_f32_16x16x32_bf16 v[16:19], v[230:233], v[160:163], v[16:19]
	v_mfma_f32_16x16x32_bf16 v[20:23], v[222:225], v[206:209], v[20:23]
	v_mfma_f32_16x16x32_bf16 v[24:27], v[230:233], v[206:209], v[24:27]
	v_mfma_f32_16x16x32_bf16 v[28:31], v[222:225], v[214:217], v[28:31]
	v_mfma_f32_16x16x32_bf16 v[32:35], v[230:233], v[214:217], v[32:35]
	s_setprio 0
	s_add_i32 s14, 0, 0x18000
	v_add_u32_e32 v0, s14, v197
	s_barrier
	ds_read_b128 v[132:135], v0
	ds_read_b128 v[136:139], v0 offset:1024
	ds_read_b128 v[140:143], v0 offset:2048
	ds_read_b128 v[144:147], v0 offset:3072
	s_add_u32 s12, s12, s34
	s_addc_u32 s13, s13, s35
	s_mov_b32 m0, s2
	v_lshl_add_u64 v[6:7], s[12:13], 0, v[168:169]
	ds_read_b128 v[148:151], v205 offset:32768
	ds_read_b128 v[152:155], v205 offset:33792
	ds_read_b128 v[156:159], v205 offset:34816
	ds_read_b128 v[160:163], v205 offset:35840
	ds_read_b128 v[176:179], v205 offset:36864
	ds_read_b128 v[206:209], v205 offset:37888
	ds_read_b128 v[210:213], v205 offset:38912
	ds_read_b128 v[214:217], v205 offset:39936
	global_load_lds_dwordx4 v[6:7], off
	v_lshl_add_u64 v[6:7], s[12:13], 0, v[164:165]
	s_mov_b32 m0, s86
	s_nop 0
	global_load_lds_dwordx4 v[6:7], off
	s_waitcnt lgkmcnt(8)
	s_barrier
	s_waitcnt lgkmcnt(0)
	s_setprio 1
	s_waitcnt lgkmcnt(0)
	v_mfma_f32_16x16x32_bf16 v[48:51], v[132:135], v[148:151], v[48:51]
	v_mfma_f32_16x16x32_bf16 v[52:55], v[140:143], v[148:151], v[52:55]
	v_mfma_f32_16x16x32_bf16 v[56:59], v[132:135], v[156:159], v[56:59]
	v_mfma_f32_16x16x32_bf16 v[60:63], v[140:143], v[156:159], v[60:63]
	v_mfma_f32_16x16x32_bf16 v[64:67], v[132:135], v[176:179], v[64:67]
	v_mfma_f32_16x16x32_bf16 v[68:71], v[140:143], v[176:179], v[68:71]
	v_mfma_f32_16x16x32_bf16 v[72:75], v[132:135], v[210:213], v[72:75]
	v_mfma_f32_16x16x32_bf16 v[76:79], v[140:143], v[210:213], v[76:79]
	v_mfma_f32_16x16x32_bf16 v[48:51], v[136:139], v[152:155], v[48:51]
	v_mfma_f32_16x16x32_bf16 v[52:55], v[144:147], v[152:155], v[52:55]
	v_mfma_f32_16x16x32_bf16 v[56:59], v[136:139], v[160:163], v[56:59]
	v_mfma_f32_16x16x32_bf16 v[60:63], v[144:147], v[160:163], v[60:63]
	v_mfma_f32_16x16x32_bf16 v[64:67], v[136:139], v[206:209], v[64:67]
	v_mfma_f32_16x16x32_bf16 v[68:71], v[144:147], v[206:209], v[68:71]
	v_mfma_f32_16x16x32_bf16 v[72:75], v[136:139], v[214:217], v[72:75]
	v_mfma_f32_16x16x32_bf16 v[76:79], v[144:147], v[214:217], v[76:79]
	s_setprio 0
	s_barrier
	s_add_i32 s12, 0, 0x1c000
	s_add_i32 s13, s14, s7
	v_add_u32_e32 v0, s12, v197
	v_lshl_add_u64 v[6:7], v[234:235], 0, s[36:37]
	s_mov_b32 m0, s13
	ds_read_b128 v[218:221], v0
	ds_read_b128 v[222:225], v0 offset:1024
	ds_read_b128 v[226:229], v0 offset:2048
	ds_read_b128 v[230:233], v0 offset:3072
	global_load_lds_dwordx4 v[6:7], off
	v_lshl_add_u64 v[6:7], v[236:237], 0, s[36:37]
	s_add_i32 m0, s13, 0x2000
	s_nop 0
	global_load_lds_dwordx4 v[6:7], off
	s_barrier
	s_waitcnt lgkmcnt(0)
	s_setprio 1
	s_waitcnt lgkmcnt(0)
	v_mfma_f32_16x16x32_bf16 v[80:83], v[218:221], v[148:151], v[80:83]
	v_mfma_f32_16x16x32_bf16 v[84:87], v[226:229], v[148:151], v[84:87]
	v_mfma_f32_16x16x32_bf16 v[88:91], v[218:221], v[156:159], v[88:91]
	v_mfma_f32_16x16x32_bf16 v[92:95], v[226:229], v[156:159], v[92:95]
	v_mfma_f32_16x16x32_bf16 v[96:99], v[218:221], v[176:179], v[96:99]
	v_mfma_f32_16x16x32_bf16 v[100:103], v[226:229], v[176:179], v[100:103]
	v_mfma_f32_16x16x32_bf16 v[104:107], v[218:221], v[210:213], v[104:107]
	v_mfma_f32_16x16x32_bf16 v[108:111], v[226:229], v[210:213], v[108:111]
	v_mfma_f32_16x16x32_bf16 v[80:83], v[222:225], v[152:155], v[80:83]
	v_mfma_f32_16x16x32_bf16 v[84:87], v[230:233], v[152:155], v[84:87]
	v_mfma_f32_16x16x32_bf16 v[88:91], v[222:225], v[160:163], v[88:91]
	v_mfma_f32_16x16x32_bf16 v[92:95], v[230:233], v[160:163], v[92:95]
	v_mfma_f32_16x16x32_bf16 v[96:99], v[222:225], v[206:209], v[96:99]
	v_mfma_f32_16x16x32_bf16 v[100:103], v[230:233], v[206:209], v[100:103]
	v_mfma_f32_16x16x32_bf16 v[104:107], v[222:225], v[214:217], v[104:107]
	v_mfma_f32_16x16x32_bf16 v[108:111], v[230:233], v[214:217], v[108:111]
	s_setprio 0
	s_mov_b32 m0, s38
	v_lshl_add_u64 v[6:7], v[238:239], 0, s[36:37]
	s_barrier
	ds_read_b128 v[148:151], v205 offset:49152
	ds_read_b128 v[152:155], v205 offset:50176
	ds_read_b128 v[156:159], v205 offset:51200
	ds_read_b128 v[160:163], v205 offset:52224
	ds_read_b128 v[176:179], v205 offset:53248
	ds_read_b128 v[206:209], v205 offset:54272
	ds_read_b128 v[210:213], v205 offset:55296
	ds_read_b128 v[214:217], v205 offset:56320
	global_load_lds_dwordx4 v[6:7], off
	v_lshl_add_u64 v[6:7], v[240:241], 0, s[36:37]
	s_mov_b32 m0, s39
	s_nop 0
	global_load_lds_dwordx4 v[6:7], off
	s_barrier
; __device__ __forceinline__ unsigned pack2(float lo, float hi) { return (unsigned)f2bf(lo) | ((unsigned)f2bf(hi) << 16); }
; #define PG8_STAGE(bufoff, gbase, voff) do { _Pragma("unroll") for (int _i = 0; _i < 2; ++_i) \
;         __builtin_amdgcn_global_load_lds((const unsigned*)((const char*)(gbase) + (voff)[_i]), (LAS unsigned*)(lds + (bufoff) + ldsw + _i * 8192), 16, 0, 0); } while (0)
; #define PG8_MMA(ai, bj, At, Bt) do { __builtin_amdgcn_s_setprio(1); _Pragma("unroll") for (int m = 0; m < 4; ++m) _Pragma("unroll") for (int n = 0; n < 2; ++n) _Pragma("unroll") for (int k = 0; k < 2; ++k) \
;         acc[ai][bj][m][n] = __builtin_amdgcn_mfma_f32_16x16x32_bf16(Bt[n][k], At[m][k], acc[ai][bj][m][n], 0, 0, 0); __builtin_amdgcn_s_setprio(0); } while (0)
; #define PG8_WAIT_V(n) asm volatile("s_waitcnt vmcnt(" #n ")" ::: "memory")
; #define PG8_WAIT_L(n) asm volatile("s_waitcnt lgkmcnt(" #n ")" ::: "memory")
; #define PG8_BAR __builtin_amdgcn_s_barrier()
; #define PG8_SCHED __builtin_amdgcn_sched_barrier(0)
; template <class Epi>
; __device__ __forceinline__ void gemm_phase(LAS unsigned char* lds, const Gemm g, const Epi& E) {
;     ...
;             PG8_BAR; PG8_WAIT_L(0); PG8_MMA(1, 0, At, B0); PG8_BAR; PG8_SCHED;
;             PG8_STAGE(PG8_SB(1, 1), b3 + hstepB, voffB);
;             PG8_WAIT_V(6); PG8_BAR; PG8_MMA(1, 1, At, B1); PG8_BAR;
;         }
;         const bool is_mid = split && (chalf == 0);
;         if (is_mid) E.mid(acc, cur, wr, wc, fr, fq); else E(acc, cur, wr, wc, fr, fq);
;     __device__ __forceinline__ void operator()(const f32x4 (&acc)[2][2][4][2], const Unit& u, int wr, int wc, int fr, int fq) const {
;         EPIP_ROWS( uint4 o; o.x = pack2(v0[0], v0[1]); o.y = pack2(v0[2], v0[3]); o.z = pack2(v1[0], v1[1]); o.w = pack2(v1[2], v1[3]); *(uint4*)(O + row * ldc + col8 + co) = o; )
	s_waitcnt lgkmcnt(0)
	s_setprio 1
	s_waitcnt lgkmcnt(0)
	v_mfma_f32_16x16x32_bf16 v[112:115], v[132:135], v[148:151], v[112:115]
	v_mfma_f32_16x16x32_bf16 v[116:119], v[140:143], v[148:151], v[116:119]
	v_mfma_f32_16x16x32_bf16 v[120:123], v[132:135], v[156:159], v[120:123]
	v_mfma_f32_16x16x32_bf16 v[124:127], v[140:143], v[156:159], v[124:127]
	v_mfma_f32_16x16x32_bf16 v[128:131], v[132:135], v[176:179], v[128:131]
	v_mfma_f32_16x16x32_bf16 v[36:39], v[140:143], v[176:179], v[36:39]
	v_mfma_f32_16x16x32_bf16 v[40:43], v[132:135], v[210:213], v[40:43]
	v_mfma_f32_16x16x32_bf16 v[44:47], v[140:143], v[210:213], v[44:47]
	v_mfma_f32_16x16x32_bf16 v[112:115], v[136:139], v[152:155], v[112:115]
	v_mfma_f32_16x16x32_bf16 v[116:119], v[144:147], v[152:155], v[116:119]
	v_mfma_f32_16x16x32_bf16 v[120:123], v[136:139], v[160:163], v[120:123]
	v_mfma_f32_16x16x32_bf16 v[124:127], v[144:147], v[160:163], v[124:127]
	v_mfma_f32_16x16x32_bf16 v[128:131], v[136:139], v[206:209], v[128:131]
	v_mfma_f32_16x16x32_bf16 v[36:39], v[144:147], v[206:209], v[36:39]
	v_mfma_f32_16x16x32_bf16 v[40:43], v[136:139], v[214:217], v[40:43]
	v_mfma_f32_16x16x32_bf16 v[44:47], v[144:147], v[214:217], v[44:47]
	s_setprio 0
	s_barrier
	s_add_i32 s12, s12, s7
	v_lshl_add_u64 v[6:7], v[242:243], 0, s[36:37]
	s_mov_b32 m0, s12
	s_nop 0
	global_load_lds_dwordx4 v[6:7], off
	v_lshl_add_u64 v[6:7], v[244:245], 0, s[36:37]
	s_add_i32 m0, s12, 0x2000
	s_nop 0
	global_load_lds_dwordx4 v[6:7], off
	s_waitcnt vmcnt(6)
	s_barrier
	s_setprio 1
	v_mfma_f32_16x16x32_bf16 v[2:5], v[218:221], v[148:151], v[2:5]
	v_mfma_f32_16x16x32_bf16 v[8:11], v[226:229], v[148:151], v[8:11]
	v_mfma_f32_16x16x32_bf16 v[12:15], v[218:221], v[156:159], v[12:15]
	v_mfma_f32_16x16x32_bf16 v[16:19], v[226:229], v[156:159], v[16:19]
	v_mfma_f32_16x16x32_bf16 v[20:23], v[218:221], v[176:179], v[20:23]
	v_mfma_f32_16x16x32_bf16 v[24:27], v[226:229], v[176:179], v[24:27]
	v_mfma_f32_16x16x32_bf16 v[28:31], v[218:221], v[210:213], v[28:31]
	v_mfma_f32_16x16x32_bf16 v[32:35], v[226:229], v[210:213], v[32:35]
	v_mfma_f32_16x16x32_bf16 v[4:7], v[222:225], v[152:155], v[2:5]
	v_mfma_f32_16x16x32_bf16 v[8:11], v[230:233], v[152:155], v[8:11]
	v_mfma_f32_16x16x32_bf16 v[12:15], v[222:225], v[160:163], v[12:15]
	v_mfma_f32_16x16x32_bf16 v[16:19], v[230:233], v[160:163], v[16:19]
	v_mfma_f32_16x16x32_bf16 v[20:23], v[222:225], v[206:209], v[20:23]
	v_mfma_f32_16x16x32_bf16 v[24:27], v[230:233], v[206:209], v[24:27]
	v_mfma_f32_16x16x32_bf16 v[28:31], v[222:225], v[214:217], v[28:31]
	v_mfma_f32_16x16x32_bf16 v[32:35], v[230:233], v[214:217], v[32:35]
	s_setprio 0
	s_add_u32 s17, s17, 0x100
	s_addc_u32 s18, s18, 0
	s_add_u32 s0, s0, 0x100
	s_addc_u32 s1, s1, 0
	s_cmp_ge_u32 s19, s87
	s_mov_b32 s12, s19
	s_barrier
	s_cbranch_scc0 .LBB0_278
	s_cmp_lg_u32 s16, 0
	s_cselect_b64 s[12:13], -1, 0
	s_xor_b64 s[14:15], s[92:93], -1
	s_or_b64 s[24:25], s[14:15], s[12:13]
	s_mov_b64 s[0:1], -1
	s_and_b64 vcc, exec, s[24:25]
	s_cbranch_vccz .LBB0_352
	s_mov_b64 s[62:63], 0
	s_cmp_lt_i32 s53, 8
	s_mov_b64 s[12:13], 0
	s_cbranch_scc1 .LBB0_330
	s_mov_b64 s[14:15], -1
	s_mov_b64 s[0:1], 0
	s_cmp_gt_i32 s53, 11
	s_cbranch_scc0 .LBB0_288
	s_cmp_gt_i32 s53, 13
	s_cbranch_scc0 .LBB0_285
	s_cmp_eq_u32 s53, 14
	s_mov_b64 s[12:13], -1
	s_cbranch_scc0 .LBB0_356
	v_lshl_add_u32 v136, s61, 8, v196
	v_lshl_or_b32 v2, s44, 8, v204
	v_readlane_b32 s12, v249, 42
	v_and_b32_sdwa v133, v51, v185 dst_sel:DWORD dst_unused:UNUSED_PAD src0_sel:WORD_1 src1_sel:DWORD
	v_and_b32_sdwa v134, v49, v185 dst_sel:DWORD dst_unused:UNUSED_PAD src0_sel:WORD_1 src1_sel:DWORD
	v_ashrrev_i32_e32 v3, 31, v2
	v_readlane_b32 s13, v249, 43
	v_ashrrev_i32_e32 v137, 31, v136
	v_and_b32_sdwa v0, v50, v185 dst_sel:DWORD dst_unused:UNUSED_PAD src0_sel:WORD_1 src1_sel:DWORD
	v_and_b32_sdwa v132, v48, v185 dst_sel:DWORD dst_unused:UNUSED_PAD src0_sel:WORD_1 src1_sel:DWORD
	v_add3_u32 v133, v51, v133, s46
	v_add3_u32 v134, v49, v134, s46
	v_lshl_add_u64 v[138:139], v[2:3], 1, s[12:13]
	v_lshlrev_b64 v[2:3], 11, v[136:137]
	v_add3_u32 v132, v48, v132, s46
	v_add3_u32 v0, v50, v0, s46
	v_and_b32_e32 v133, 0xffff0000, v133
	v_and_b32_e32 v134, 0xffff0000, v134
	v_and_b32_sdwa v135, v55, v185 dst_sel:DWORD dst_unused:UNUSED_PAD src0_sel:WORD_1 src1_sel:DWORD
	v_and_b32_sdwa v137, v53, v185 dst_sel:DWORD dst_unused:UNUSED_PAD src0_sel:WORD_1 src1_sel:DWORD
	v_or_b32_sdwa v133, v133, v0 dst_sel:DWORD dst_unused:UNUSED_PAD src0_sel:DWORD src1_sel:WORD_1
	v_or_b32_sdwa v132, v134, v132 dst_sel:DWORD dst_unused:UNUSED_PAD src0_sel:DWORD src1_sel:WORD_1
	v_and_b32_sdwa v0, v54, v185 dst_sel:DWORD dst_unused:UNUSED_PAD src0_sel:WORD_1 src1_sel:DWORD
	v_and_b32_sdwa v134, v52, v185 dst_sel:DWORD dst_unused:UNUSED_PAD src0_sel:WORD_1 src1_sel:DWORD
	v_add3_u32 v135, v55, v135, s46
	v_add3_u32 v137, v53, v137, s46
	v_add3_u32 v134, v52, v134, s46
	v_add3_u32 v0, v54, v0, s46
	v_and_b32_e32 v135, 0xffff0000, v135
	v_and_b32_e32 v137, 0xffff0000, v137
	v_lshl_add_u64 v[2:3], v[138:139], 0, v[2:3]
	v_or_b32_sdwa v135, v135, v0 dst_sel:DWORD dst_unused:UNUSED_PAD src0_sel:DWORD src1_sel:WORD_1
	v_or_b32_sdwa v134, v137, v134 dst_sel:DWORD dst_unused:UNUSED_PAD src0_sel:DWORD src1_sel:WORD_1
	global_store_dwordx4 v[2:3], v[132:135], off
	v_and_b32_sdwa v0, v82, v185 dst_sel:DWORD dst_unused:UNUSED_PAD src0_sel:WORD_1 src1_sel:DWORD
	v_add3_u32 v0, v82, v0, s46
	v_and_b32_sdwa v133, v83, v185 dst_sel:DWORD dst_unused:UNUSED_PAD src0_sel:WORD_1 src1_sel:DWORD
	v_and_b32_sdwa v134, v81, v185 dst_sel:DWORD dst_unused:UNUSED_PAD src0_sel:WORD_1 src1_sel:DWORD
; __device__ __forceinline__ unsigned pack2(float lo, float hi) { return (unsigned)f2bf(lo) | ((unsigned)f2bf(hi) << 16); }
;     __device__ __forceinline__ void operator()(const f32x4 (&acc)[2][2][4][2], const Unit& u, int wr, int wc, int fr, int fq) const {
;         EPIP_ROWS( uint4 o; o.x = pack2(v0[0], v0[1]); o.y = pack2(v0[2], v0[3]); o.z = pack2(v1[0], v1[1]); o.w = pack2(v1[2], v1[3]); *(uint4*)(O + row * ldc + col8 + co) = o; )
	v_and_b32_sdwa v132, v80, v185 dst_sel:DWORD dst_unused:UNUSED_PAD src0_sel:WORD_1 src1_sel:DWORD
	v_add3_u32 v133, v83, v133, s46
	v_add3_u32 v134, v81, v134, s46
	v_add3_u32 v132, v80, v132, s46
	v_and_b32_e32 v133, 0xffff0000, v133
	v_and_b32_e32 v134, 0xffff0000, v134
	v_and_b32_sdwa v135, v87, v185 dst_sel:DWORD dst_unused:UNUSED_PAD src0_sel:WORD_1 src1_sel:DWORD
	v_and_b32_sdwa v137, v85, v185 dst_sel:DWORD dst_unused:UNUSED_PAD src0_sel:WORD_1 src1_sel:DWORD
	v_or_b32_sdwa v133, v133, v0 dst_sel:DWORD dst_unused:UNUSED_PAD src0_sel:DWORD src1_sel:WORD_1
	v_or_b32_sdwa v132, v134, v132 dst_sel:DWORD dst_unused:UNUSED_PAD src0_sel:DWORD src1_sel:WORD_1
	v_and_b32_sdwa v0, v86, v185 dst_sel:DWORD dst_unused:UNUSED_PAD src0_sel:WORD_1 src1_sel:DWORD
	v_and_b32_sdwa v134, v84, v185 dst_sel:DWORD dst_unused:UNUSED_PAD src0_sel:WORD_1 src1_sel:DWORD
	v_add3_u32 v135, v87, v135, s46
	v_add3_u32 v137, v85, v137, s46
	v_add3_u32 v134, v84, v134, s46
	v_add3_u32 v0, v86, v0, s46
	v_and_b32_e32 v135, 0xffff0000, v135
	v_and_b32_e32 v137, 0xffff0000, v137
	v_or_b32_sdwa v135, v135, v0 dst_sel:DWORD dst_unused:UNUSED_PAD src0_sel:DWORD src1_sel:WORD_1
	v_or_b32_sdwa v134, v137, v134 dst_sel:DWORD dst_unused:UNUSED_PAD src0_sel:DWORD src1_sel:WORD_1
	global_store_dwordx4 v[2:3], v[132:135], off offset:256
	v_and_b32_sdwa v0, v58, v185 dst_sel:DWORD dst_unused:UNUSED_PAD src0_sel:WORD_1 src1_sel:DWORD
	v_add3_u32 v0, v58, v0, s46
	v_or_b32_e32 v132, 16, v136
	v_ashrrev_i32_e32 v133, 31, v132
	v_lshlrev_b64 v[132:133], 11, v[132:133]
	v_lshl_add_u64 v[140:141], v[138:139], 0, v[132:133]
	v_and_b32_sdwa v133, v59, v185 dst_sel:DWORD dst_unused:UNUSED_PAD src0_sel:WORD_1 src1_sel:DWORD
	v_and_b32_sdwa v134, v57, v185 dst_sel:DWORD dst_unused:UNUSED_PAD src0_sel:WORD_1 src1_sel:DWORD
	v_and_b32_sdwa v132, v56, v185 dst_sel:DWORD dst_unused:UNUSED_PAD src0_sel:WORD_1 src1_sel:DWORD
	v_add3_u32 v133, v59, v133, s46
	v_add3_u32 v134, v57, v134, s46
	v_add3_u32 v132, v56, v132, s46
	v_and_b32_e32 v133, 0xffff0000, v133
	v_and_b32_e32 v134, 0xffff0000, v134
	v_and_b32_sdwa v135, v63, v185 dst_sel:DWORD dst_unused:UNUSED_PAD src0_sel:WORD_1 src1_sel:DWORD
	v_and_b32_sdwa v137, v61, v185 dst_sel:DWORD dst_unused:UNUSED_PAD src0_sel:WORD_1 src1_sel:DWORD
	v_or_b32_sdwa v133, v133, v0 dst_sel:DWORD dst_unused:UNUSED_PAD src0_sel:DWORD src1_sel:WORD_1
	v_or_b32_sdwa v132, v134, v132 dst_sel:DWORD dst_unused:UNUSED_PAD src0_sel:DWORD src1_sel:WORD_1
	v_and_b32_sdwa v0, v62, v185 dst_sel:DWORD dst_unused:UNUSED_PAD src0_sel:WORD_1 src1_sel:DWORD
	v_and_b32_sdwa v134, v60, v185 dst_sel:DWORD dst_unused:UNUSED_PAD src0_sel:WORD_1 src1_sel:DWORD
	v_add3_u32 v135, v63, v135, s46
	v_add3_u32 v137, v61, v137, s46
	v_add3_u32 v134, v60, v134, s46
	v_add3_u32 v0, v62, v0, s46
	v_and_b32_e32 v135, 0xffff0000, v135
	v_and_b32_e32 v137, 0xffff0000, v137
	v_or_b32_sdwa v135, v135, v0 dst_sel:DWORD dst_unused:UNUSED_PAD src0_sel:DWORD src1_sel:WORD_1
	v_or_b32_sdwa v134, v137, v134 dst_sel:DWORD dst_unused:UNUSED_PAD src0_sel:DWORD src1_sel:WORD_1
	global_store_dwordx4 v[140:141], v[132:135], off
	v_and_b32_sdwa v0, v90, v185 dst_sel:DWORD dst_unused:UNUSED_PAD src0_sel:WORD_1 src1_sel:DWORD
	v_add3_u32 v0, v90, v0, s46
	v_and_b32_sdwa v133, v91, v185 dst_sel:DWORD dst_unused:UNUSED_PAD src0_sel:WORD_1 src1_sel:DWORD
	v_and_b32_sdwa v134, v89, v185 dst_sel:DWORD dst_unused:UNUSED_PAD src0_sel:WORD_1 src1_sel:DWORD
	v_and_b32_sdwa v132, v88, v185 dst_sel:DWORD dst_unused:UNUSED_PAD src0_sel:WORD_1 src1_sel:DWORD
	v_add3_u32 v133, v91, v133, s46
	v_add3_u32 v134, v89, v134, s46
	v_add3_u32 v132, v88, v132, s46
	v_and_b32_e32 v133, 0xffff0000, v133
	v_and_b32_e32 v134, 0xffff0000, v134
	v_and_b32_sdwa v135, v95, v185 dst_sel:DWORD dst_unused:UNUSED_PAD src0_sel:WORD_1 src1_sel:DWORD
	v_and_b32_sdwa v137, v93, v185 dst_sel:DWORD dst_unused:UNUSED_PAD src0_sel:WORD_1 src1_sel:DWORD
	v_or_b32_sdwa v133, v133, v0 dst_sel:DWORD dst_unused:UNUSED_PAD src0_sel:DWORD src1_sel:WORD_1
	v_or_b32_sdwa v132, v134, v132 dst_sel:DWORD dst_unused:UNUSED_PAD src0_sel:DWORD src1_sel:WORD_1
	v_and_b32_sdwa v0, v94, v185 dst_sel:DWORD dst_unused:UNUSED_PAD src0_sel:WORD_1 src1_sel:DWORD
	v_and_b32_sdwa v134, v92, v185 dst_sel:DWORD dst_unused:UNUSED_PAD src0_sel:WORD_1 src1_sel:DWORD
	v_add3_u32 v135, v95, v135, s46
	v_add3_u32 v137, v93, v137, s46
	v_add3_u32 v134, v92, v134, s46
	v_add3_u32 v0, v94, v0, s46
	v_and_b32_e32 v135, 0xffff0000, v135
	v_and_b32_e32 v137, 0xffff0000, v137
	v_or_b32_sdwa v135, v135, v0 dst_sel:DWORD dst_unused:UNUSED_PAD src0_sel:DWORD src1_sel:WORD_1
	v_or_b32_sdwa v134, v137, v134 dst_sel:DWORD dst_unused:UNUSED_PAD src0_sel:DWORD src1_sel:WORD_1
	global_store_dwordx4 v[140:141], v[132:135], off offset:256
	v_and_b32_sdwa v0, v66, v185 dst_sel:DWORD dst_unused:UNUSED_PAD src0_sel:WORD_1 src1_sel:DWORD
	v_add3_u32 v0, v66, v0, s46
	v_or_b32_e32 v132, 32, v136
	v_ashrrev_i32_e32 v133, 31, v132
	v_lshlrev_b64 v[132:133], 11, v[132:133]
	v_lshl_add_u64 v[140:141], v[138:139], 0, v[132:133]
	v_and_b32_sdwa v133, v67, v185 dst_sel:DWORD dst_unused:UNUSED_PAD src0_sel:WORD_1 src1_sel:DWORD
	v_and_b32_sdwa v134, v65, v185 dst_sel:DWORD dst_unused:UNUSED_PAD src0_sel:WORD_1 src1_sel:DWORD
	v_and_b32_sdwa v132, v64, v185 dst_sel:DWORD dst_unused:UNUSED_PAD src0_sel:WORD_1 src1_sel:DWORD
	v_add3_u32 v133, v67, v133, s46
	v_add3_u32 v134, v65, v134, s46
	v_add3_u32 v132, v64, v132, s46
	v_and_b32_e32 v133, 0xffff0000, v133
	v_and_b32_e32 v134, 0xffff0000, v134
	v_and_b32_sdwa v135, v71, v185 dst_sel:DWORD dst_unused:UNUSED_PAD src0_sel:WORD_1 src1_sel:DWORD
; __device__ __forceinline__ unsigned pack2(float lo, float hi) { return (unsigned)f2bf(lo) | ((unsigned)f2bf(hi) << 16); }
;     __device__ __forceinline__ void operator()(const f32x4 (&acc)[2][2][4][2], const Unit& u, int wr, int wc, int fr, int fq) const {
;         EPIP_ROWS( uint4 o; o.x = pack2(v0[0], v0[1]); o.y = pack2(v0[2], v0[3]); o.z = pack2(v1[0], v1[1]); o.w = pack2(v1[2], v1[3]); *(uint4*)(O + row * ldc + col8 + co) = o; )
	v_and_b32_sdwa v137, v69, v185 dst_sel:DWORD dst_unused:UNUSED_PAD src0_sel:WORD_1 src1_sel:DWORD
	v_or_b32_sdwa v133, v133, v0 dst_sel:DWORD dst_unused:UNUSED_PAD src0_sel:DWORD src1_sel:WORD_1
	v_or_b32_sdwa v132, v134, v132 dst_sel:DWORD dst_unused:UNUSED_PAD src0_sel:DWORD src1_sel:WORD_1
	v_and_b32_sdwa v0, v70, v185 dst_sel:DWORD dst_unused:UNUSED_PAD src0_sel:WORD_1 src1_sel:DWORD
	v_and_b32_sdwa v134, v68, v185 dst_sel:DWORD dst_unused:UNUSED_PAD src0_sel:WORD_1 src1_sel:DWORD
	v_add3_u32 v135, v71, v135, s46
	v_add3_u32 v137, v69, v137, s46
	v_add3_u32 v134, v68, v134, s46
	v_add3_u32 v0, v70, v0, s46
	v_and_b32_e32 v135, 0xffff0000, v135
	v_and_b32_e32 v137, 0xffff0000, v137
	v_or_b32_sdwa v135, v135, v0 dst_sel:DWORD dst_unused:UNUSED_PAD src0_sel:DWORD src1_sel:WORD_1
	v_or_b32_sdwa v134, v137, v134 dst_sel:DWORD dst_unused:UNUSED_PAD src0_sel:DWORD src1_sel:WORD_1
	global_store_dwordx4 v[140:141], v[132:135], off
	v_and_b32_sdwa v0, v98, v185 dst_sel:DWORD dst_unused:UNUSED_PAD src0_sel:WORD_1 src1_sel:DWORD
	v_add3_u32 v0, v98, v0, s46
	v_and_b32_sdwa v133, v99, v185 dst_sel:DWORD dst_unused:UNUSED_PAD src0_sel:WORD_1 src1_sel:DWORD
	v_and_b32_sdwa v134, v97, v185 dst_sel:DWORD dst_unused:UNUSED_PAD src0_sel:WORD_1 src1_sel:DWORD
	v_and_b32_sdwa v132, v96, v185 dst_sel:DWORD dst_unused:UNUSED_PAD src0_sel:WORD_1 src1_sel:DWORD
	v_add3_u32 v133, v99, v133, s46
	v_add3_u32 v134, v97, v134, s46
	v_add3_u32 v132, v96, v132, s46
	v_and_b32_e32 v133, 0xffff0000, v133
	v_and_b32_e32 v134, 0xffff0000, v134
	v_and_b32_sdwa v135, v103, v185 dst_sel:DWORD dst_unused:UNUSED_PAD src0_sel:WORD_1 src1_sel:DWORD
	v_and_b32_sdwa v137, v101, v185 dst_sel:DWORD dst_unused:UNUSED_PAD src0_sel:WORD_1 src1_sel:DWORD
	v_or_b32_sdwa v133, v133, v0 dst_sel:DWORD dst_unused:UNUSED_PAD src0_sel:DWORD src1_sel:WORD_1
	v_or_b32_sdwa v132, v134, v132 dst_sel:DWORD dst_unused:UNUSED_PAD src0_sel:DWORD src1_sel:WORD_1
	v_and_b32_sdwa v0, v102, v185 dst_sel:DWORD dst_unused:UNUSED_PAD src0_sel:WORD_1 src1_sel:DWORD
	v_and_b32_sdwa v134, v100, v185 dst_sel:DWORD dst_unused:UNUSED_PAD src0_sel:WORD_1 src1_sel:DWORD
	v_add3_u32 v135, v103, v135, s46
	v_add3_u32 v137, v101, v137, s46
	v_add3_u32 v134, v100, v134, s46
	v_add3_u32 v0, v102, v0, s46
	v_and_b32_e32 v135, 0xffff0000, v135
	v_and_b32_e32 v137, 0xffff0000, v137
	v_or_b32_sdwa v135, v135, v0 dst_sel:DWORD dst_unused:UNUSED_PAD src0_sel:DWORD src1_sel:WORD_1
	v_or_b32_sdwa v134, v137, v134 dst_sel:DWORD dst_unused:UNUSED_PAD src0_sel:DWORD src1_sel:WORD_1
	global_store_dwordx4 v[140:141], v[132:135], off offset:256
	v_and_b32_sdwa v0, v74, v185 dst_sel:DWORD dst_unused:UNUSED_PAD src0_sel:WORD_1 src1_sel:DWORD
	v_add3_u32 v0, v74, v0, s46
	v_or_b32_e32 v132, 48, v136
	v_ashrrev_i32_e32 v133, 31, v132
	v_lshlrev_b64 v[132:133], 11, v[132:133]
	v_lshl_add_u64 v[136:137], v[138:139], 0, v[132:133]
	v_and_b32_sdwa v133, v75, v185 dst_sel:DWORD dst_unused:UNUSED_PAD src0_sel:WORD_1 src1_sel:DWORD
	v_and_b32_sdwa v134, v73, v185 dst_sel:DWORD dst_unused:UNUSED_PAD src0_sel:WORD_1 src1_sel:DWORD
	v_and_b32_sdwa v132, v72, v185 dst_sel:DWORD dst_unused:UNUSED_PAD src0_sel:WORD_1 src1_sel:DWORD
	v_add3_u32 v133, v75, v133, s46
	v_add3_u32 v134, v73, v134, s46
	v_add3_u32 v132, v72, v132, s46
	v_and_b32_e32 v133, 0xffff0000, v133
	v_and_b32_e32 v134, 0xffff0000, v134
	v_and_b32_sdwa v135, v79, v185 dst_sel:DWORD dst_unused:UNUSED_PAD src0_sel:WORD_1 src1_sel:DWORD
	v_and_b32_sdwa v138, v77, v185 dst_sel:DWORD dst_unused:UNUSED_PAD src0_sel:WORD_1 src1_sel:DWORD
	v_or_b32_sdwa v133, v133, v0 dst_sel:DWORD dst_unused:UNUSED_PAD src0_sel:DWORD src1_sel:WORD_1
	v_or_b32_sdwa v132, v134, v132 dst_sel:DWORD dst_unused:UNUSED_PAD src0_sel:DWORD src1_sel:WORD_1
	v_and_b32_sdwa v0, v78, v185 dst_sel:DWORD dst_unused:UNUSED_PAD src0_sel:WORD_1 src1_sel:DWORD
	v_and_b32_sdwa v134, v76, v185 dst_sel:DWORD dst_unused:UNUSED_PAD src0_sel:WORD_1 src1_sel:DWORD
	v_add3_u32 v135, v79, v135, s46
	v_add3_u32 v138, v77, v138, s46
	v_add3_u32 v134, v76, v134, s46
	v_add3_u32 v0, v78, v0, s46
	v_and_b32_e32 v135, 0xffff0000, v135
	v_and_b32_e32 v138, 0xffff0000, v138
	v_or_b32_sdwa v135, v135, v0 dst_sel:DWORD dst_unused:UNUSED_PAD src0_sel:DWORD src1_sel:WORD_1
	v_or_b32_sdwa v134, v138, v134 dst_sel:DWORD dst_unused:UNUSED_PAD src0_sel:DWORD src1_sel:WORD_1
	global_store_dwordx4 v[136:137], v[132:135], off
	v_and_b32_sdwa v0, v106, v185 dst_sel:DWORD dst_unused:UNUSED_PAD src0_sel:WORD_1 src1_sel:DWORD
	v_add3_u32 v0, v106, v0, s46
	v_and_b32_sdwa v133, v107, v185 dst_sel:DWORD dst_unused:UNUSED_PAD src0_sel:WORD_1 src1_sel:DWORD
	v_and_b32_sdwa v134, v105, v185 dst_sel:DWORD dst_unused:UNUSED_PAD src0_sel:WORD_1 src1_sel:DWORD
	v_and_b32_sdwa v132, v104, v185 dst_sel:DWORD dst_unused:UNUSED_PAD src0_sel:WORD_1 src1_sel:DWORD
	v_add3_u32 v133, v107, v133, s46
	v_add3_u32 v134, v105, v134, s46
	v_add3_u32 v132, v104, v132, s46
	v_and_b32_e32 v133, 0xffff0000, v133
	v_and_b32_e32 v134, 0xffff0000, v134
	v_and_b32_sdwa v135, v111, v185 dst_sel:DWORD dst_unused:UNUSED_PAD src0_sel:WORD_1 src1_sel:DWORD
	v_and_b32_sdwa v138, v109, v185 dst_sel:DWORD dst_unused:UNUSED_PAD src0_sel:WORD_1 src1_sel:DWORD
	v_or_b32_sdwa v133, v133, v0 dst_sel:DWORD dst_unused:UNUSED_PAD src0_sel:DWORD src1_sel:WORD_1
	v_or_b32_sdwa v132, v134, v132 dst_sel:DWORD dst_unused:UNUSED_PAD src0_sel:DWORD src1_sel:WORD_1
	v_and_b32_sdwa v0, v110, v185 dst_sel:DWORD dst_unused:UNUSED_PAD src0_sel:WORD_1 src1_sel:DWORD
	v_and_b32_sdwa v134, v108, v185 dst_sel:DWORD dst_unused:UNUSED_PAD src0_sel:WORD_1 src1_sel:DWORD
	v_add3_u32 v135, v111, v135, s46
; __device__ __forceinline__ unsigned pack2(float lo, float hi) { return (unsigned)f2bf(lo) | ((unsigned)f2bf(hi) << 16); }
;     __device__ __forceinline__ void operator()(const f32x4 (&acc)[2][2][4][2], const Unit& u, int wr, int wc, int fr, int fq) const {
;         EPIP_ROWS( uint4 o; o.x = pack2(v0[0], v0[1]); o.y = pack2(v0[2], v0[3]); o.z = pack2(v1[0], v1[1]); o.w = pack2(v1[2], v1[3]); *(uint4*)(O + row * ldc + col8 + co) = o; )
	v_add3_u32 v138, v109, v138, s46
	v_add3_u32 v134, v108, v134, s46
	v_add3_u32 v0, v110, v0, s46
	v_and_b32_e32 v135, 0xffff0000, v135
	v_and_b32_e32 v138, 0xffff0000, v138
	v_or_b32_sdwa v135, v135, v0 dst_sel:DWORD dst_unused:UNUSED_PAD src0_sel:DWORD src1_sel:WORD_1
	v_or_b32_sdwa v134, v138, v134 dst_sel:DWORD dst_unused:UNUSED_PAD src0_sel:DWORD src1_sel:WORD_1
	global_store_dwordx4 v[136:137], v[132:135], off offset:256
	v_and_b32_sdwa v0, v114, v185 dst_sel:DWORD dst_unused:UNUSED_PAD src0_sel:WORD_1 src1_sel:DWORD
	v_and_b32_sdwa v138, v117, v185 dst_sel:DWORD dst_unused:UNUSED_PAD src0_sel:WORD_1 src1_sel:DWORD
	v_and_b32_sdwa v134, v113, v185 dst_sel:DWORD dst_unused:UNUSED_PAD src0_sel:WORD_1 src1_sel:DWORD
	v_and_b32_sdwa v132, v112, v185 dst_sel:DWORD dst_unused:UNUSED_PAD src0_sel:WORD_1 src1_sel:DWORD
	v_and_b32_sdwa v133, v115, v185 dst_sel:DWORD dst_unused:UNUSED_PAD src0_sel:WORD_1 src1_sel:DWORD
	v_add3_u32 v134, v113, v134, s46
	v_add3_u32 v132, v112, v132, s46
	v_add3_u32 v133, v115, v133, s46
	v_and_b32_e32 v134, 0xffff0000, v134
	s_mov_b64 s[12:13], 0x40000
	v_add3_u32 v0, v114, v0, s46
	v_and_b32_e32 v133, 0xffff0000, v133
	v_or_b32_sdwa v132, v134, v132 dst_sel:DWORD dst_unused:UNUSED_PAD src0_sel:DWORD src1_sel:WORD_1
	v_and_b32_sdwa v134, v116, v185 dst_sel:DWORD dst_unused:UNUSED_PAD src0_sel:WORD_1 src1_sel:DWORD
	v_and_b32_sdwa v135, v119, v185 dst_sel:DWORD dst_unused:UNUSED_PAD src0_sel:WORD_1 src1_sel:DWORD
	v_add3_u32 v138, v117, v138, s46
	v_lshl_add_u64 v[136:137], v[2:3], 0, s[12:13]
	v_or_b32_sdwa v133, v133, v0 dst_sel:DWORD dst_unused:UNUSED_PAD src0_sel:DWORD src1_sel:WORD_1
	v_and_b32_sdwa v0, v118, v185 dst_sel:DWORD dst_unused:UNUSED_PAD src0_sel:WORD_1 src1_sel:DWORD
	v_add3_u32 v134, v116, v134, s46
	v_add3_u32 v135, v119, v135, s46
	v_and_b32_e32 v138, 0xffff0000, v138
	s_mov_b32 s12, 0x40000
	v_add3_u32 v0, v118, v0, s46
	v_and_b32_e32 v135, 0xffff0000, v135
	v_or_b32_sdwa v134, v138, v134 dst_sel:DWORD dst_unused:UNUSED_PAD src0_sel:DWORD src1_sel:WORD_1
	v_add_co_u32_e32 v138, vcc, s12, v2
	v_or_b32_sdwa v135, v135, v0 dst_sel:DWORD dst_unused:UNUSED_PAD src0_sel:DWORD src1_sel:WORD_1
	s_nop 0
	v_addc_co_u32_e32 v139, vcc, 0, v3, vcc
	global_store_dwordx4 v[138:139], v[132:135], off
	v_and_b32_sdwa v0, v6, v185 dst_sel:DWORD dst_unused:UNUSED_PAD src0_sel:WORD_1 src1_sel:DWORD
	v_add3_u32 v0, v6, v0, s46
	v_and_b32_sdwa v133, v7, v185 dst_sel:DWORD dst_unused:UNUSED_PAD src0_sel:WORD_1 src1_sel:DWORD
	v_and_b32_sdwa v134, v5, v185 dst_sel:DWORD dst_unused:UNUSED_PAD src0_sel:WORD_1 src1_sel:DWORD
	v_and_b32_sdwa v132, v4, v185 dst_sel:DWORD dst_unused:UNUSED_PAD src0_sel:WORD_1 src1_sel:DWORD
	v_add3_u32 v133, v7, v133, s46
	v_add3_u32 v134, v5, v134, s46
	v_add3_u32 v132, v4, v132, s46
	v_and_b32_e32 v133, 0xffff0000, v133
	v_and_b32_e32 v134, 0xffff0000, v134
	v_and_b32_sdwa v135, v11, v185 dst_sel:DWORD dst_unused:UNUSED_PAD src0_sel:WORD_1 src1_sel:DWORD
	v_and_b32_sdwa v138, v9, v185 dst_sel:DWORD dst_unused:UNUSED_PAD src0_sel:WORD_1 src1_sel:DWORD
	v_or_b32_sdwa v133, v133, v0 dst_sel:DWORD dst_unused:UNUSED_PAD src0_sel:DWORD src1_sel:WORD_1
	v_or_b32_sdwa v132, v134, v132 dst_sel:DWORD dst_unused:UNUSED_PAD src0_sel:DWORD src1_sel:WORD_1
	v_and_b32_sdwa v0, v10, v185 dst_sel:DWORD dst_unused:UNUSED_PAD src0_sel:WORD_1 src1_sel:DWORD
	v_and_b32_sdwa v134, v8, v185 dst_sel:DWORD dst_unused:UNUSED_PAD src0_sel:WORD_1 src1_sel:DWORD
	v_add3_u32 v135, v11, v135, s46
	v_add3_u32 v138, v9, v138, s46
	v_add3_u32 v134, v8, v134, s46
	v_add3_u32 v0, v10, v0, s46
	v_and_b32_e32 v135, 0xffff0000, v135
	v_and_b32_e32 v138, 0xffff0000, v138
	v_or_b32_sdwa v135, v135, v0 dst_sel:DWORD dst_unused:UNUSED_PAD src0_sel:DWORD src1_sel:WORD_1
	v_or_b32_sdwa v134, v138, v134 dst_sel:DWORD dst_unused:UNUSED_PAD src0_sel:DWORD src1_sel:WORD_1
	global_store_dwordx4 v[136:137], v[132:135], off offset:256
	v_and_b32_sdwa v0, v122, v185 dst_sel:DWORD dst_unused:UNUSED_PAD src0_sel:WORD_1 src1_sel:DWORD
	v_and_b32_sdwa v138, v125, v185 dst_sel:DWORD dst_unused:UNUSED_PAD src0_sel:WORD_1 src1_sel:DWORD
	v_and_b32_sdwa v134, v121, v185 dst_sel:DWORD dst_unused:UNUSED_PAD src0_sel:WORD_1 src1_sel:DWORD
	v_and_b32_sdwa v132, v120, v185 dst_sel:DWORD dst_unused:UNUSED_PAD src0_sel:WORD_1 src1_sel:DWORD
	v_and_b32_sdwa v133, v123, v185 dst_sel:DWORD dst_unused:UNUSED_PAD src0_sel:WORD_1 src1_sel:DWORD
	v_add3_u32 v134, v121, v134, s46
	v_add3_u32 v132, v120, v132, s46
	v_add3_u32 v133, v123, v133, s46
	v_and_b32_e32 v134, 0xffff0000, v134
	s_mov_b64 s[12:13], 0x48000
	v_add3_u32 v0, v122, v0, s46
	v_and_b32_e32 v133, 0xffff0000, v133
	v_or_b32_sdwa v132, v134, v132 dst_sel:DWORD dst_unused:UNUSED_PAD src0_sel:DWORD src1_sel:WORD_1
	v_and_b32_sdwa v134, v124, v185 dst_sel:DWORD dst_unused:UNUSED_PAD src0_sel:WORD_1 src1_sel:DWORD
	v_and_b32_sdwa v135, v127, v185 dst_sel:DWORD dst_unused:UNUSED_PAD src0_sel:WORD_1 src1_sel:DWORD
	v_add3_u32 v138, v125, v138, s46
	v_lshl_add_u64 v[136:137], v[2:3], 0, s[12:13]
	v_or_b32_sdwa v133, v133, v0 dst_sel:DWORD dst_unused:UNUSED_PAD src0_sel:DWORD src1_sel:WORD_1
	v_and_b32_sdwa v0, v126, v185 dst_sel:DWORD dst_unused:UNUSED_PAD src0_sel:WORD_1 src1_sel:DWORD
	v_add3_u32 v134, v124, v134, s46
	v_add3_u32 v135, v127, v135, s46
	v_and_b32_e32 v138, 0xffff0000, v138
	s_mov_b32 s12, 0x48000
	v_add3_u32 v0, v126, v0, s46
	v_and_b32_e32 v135, 0xffff0000, v135
	v_or_b32_sdwa v134, v138, v134 dst_sel:DWORD dst_unused:UNUSED_PAD src0_sel:DWORD src1_sel:WORD_1
	v_add_co_u32_e32 v138, vcc, s12, v2
	v_or_b32_sdwa v135, v135, v0 dst_sel:DWORD dst_unused:UNUSED_PAD src0_sel:DWORD src1_sel:WORD_1
; __device__ __forceinline__ unsigned pack2(float lo, float hi) { return (unsigned)f2bf(lo) | ((unsigned)f2bf(hi) << 16); }
;     __device__ __forceinline__ void operator()(const f32x4 (&acc)[2][2][4][2], const Unit& u, int wr, int wc, int fr, int fq) const {
;         EPIP_ROWS( uint4 o; o.x = pack2(v0[0], v0[1]); o.y = pack2(v0[2], v0[3]); o.z = pack2(v1[0], v1[1]); o.w = pack2(v1[2], v1[3]); *(uint4*)(O + row * ldc + col8 + co) = o; )
	s_nop 0
	v_addc_co_u32_e32 v139, vcc, 0, v3, vcc
	global_store_dwordx4 v[138:139], v[132:135], off
	v_and_b32_sdwa v0, v14, v185 dst_sel:DWORD dst_unused:UNUSED_PAD src0_sel:WORD_1 src1_sel:DWORD
	v_add3_u32 v0, v14, v0, s46
	v_and_b32_sdwa v133, v15, v185 dst_sel:DWORD dst_unused:UNUSED_PAD src0_sel:WORD_1 src1_sel:DWORD
	v_and_b32_sdwa v134, v13, v185 dst_sel:DWORD dst_unused:UNUSED_PAD src0_sel:WORD_1 src1_sel:DWORD
	v_and_b32_sdwa v132, v12, v185 dst_sel:DWORD dst_unused:UNUSED_PAD src0_sel:WORD_1 src1_sel:DWORD
	v_add3_u32 v133, v15, v133, s46
	v_add3_u32 v134, v13, v134, s46
	v_add3_u32 v132, v12, v132, s46
	v_and_b32_e32 v133, 0xffff0000, v133
	v_and_b32_e32 v134, 0xffff0000, v134
	v_and_b32_sdwa v135, v19, v185 dst_sel:DWORD dst_unused:UNUSED_PAD src0_sel:WORD_1 src1_sel:DWORD
	v_and_b32_sdwa v138, v17, v185 dst_sel:DWORD dst_unused:UNUSED_PAD src0_sel:WORD_1 src1_sel:DWORD
	v_or_b32_sdwa v133, v133, v0 dst_sel:DWORD dst_unused:UNUSED_PAD src0_sel:DWORD src1_sel:WORD_1
	v_or_b32_sdwa v132, v134, v132 dst_sel:DWORD dst_unused:UNUSED_PAD src0_sel:DWORD src1_sel:WORD_1
	v_and_b32_sdwa v0, v18, v185 dst_sel:DWORD dst_unused:UNUSED_PAD src0_sel:WORD_1 src1_sel:DWORD
	v_and_b32_sdwa v134, v16, v185 dst_sel:DWORD dst_unused:UNUSED_PAD src0_sel:WORD_1 src1_sel:DWORD
	v_add3_u32 v135, v19, v135, s46
	v_add3_u32 v138, v17, v138, s46
	v_add3_u32 v134, v16, v134, s46
	v_add3_u32 v0, v18, v0, s46
	v_and_b32_e32 v135, 0xffff0000, v135
	v_and_b32_e32 v138, 0xffff0000, v138
	v_or_b32_sdwa v135, v135, v0 dst_sel:DWORD dst_unused:UNUSED_PAD src0_sel:DWORD src1_sel:WORD_1
	v_or_b32_sdwa v134, v138, v134 dst_sel:DWORD dst_unused:UNUSED_PAD src0_sel:DWORD src1_sel:WORD_1
	global_store_dwordx4 v[136:137], v[132:135], off offset:256
	v_and_b32_sdwa v0, v130, v185 dst_sel:DWORD dst_unused:UNUSED_PAD src0_sel:WORD_1 src1_sel:DWORD
	v_and_b32_sdwa v138, v37, v185 dst_sel:DWORD dst_unused:UNUSED_PAD src0_sel:WORD_1 src1_sel:DWORD
	v_and_b32_sdwa v134, v129, v185 dst_sel:DWORD dst_unused:UNUSED_PAD src0_sel:WORD_1 src1_sel:DWORD
	v_and_b32_sdwa v132, v128, v185 dst_sel:DWORD dst_unused:UNUSED_PAD src0_sel:WORD_1 src1_sel:DWORD
	v_and_b32_sdwa v133, v131, v185 dst_sel:DWORD dst_unused:UNUSED_PAD src0_sel:WORD_1 src1_sel:DWORD
	v_add3_u32 v134, v129, v134, s46
	v_add3_u32 v132, v128, v132, s46
	v_add3_u32 v133, v131, v133, s46
	v_and_b32_e32 v134, 0xffff0000, v134
	s_mov_b64 s[12:13], 0x50000
	v_add3_u32 v0, v130, v0, s46
	v_and_b32_e32 v133, 0xffff0000, v133
	v_or_b32_sdwa v132, v134, v132 dst_sel:DWORD dst_unused:UNUSED_PAD src0_sel:DWORD src1_sel:WORD_1
	v_and_b32_sdwa v134, v36, v185 dst_sel:DWORD dst_unused:UNUSED_PAD src0_sel:WORD_1 src1_sel:DWORD
	v_and_b32_sdwa v135, v39, v185 dst_sel:DWORD dst_unused:UNUSED_PAD src0_sel:WORD_1 src1_sel:DWORD
	v_add3_u32 v138, v37, v138, s46
	v_lshl_add_u64 v[136:137], v[2:3], 0, s[12:13]
	v_or_b32_sdwa v133, v133, v0 dst_sel:DWORD dst_unused:UNUSED_PAD src0_sel:DWORD src1_sel:WORD_1
	v_and_b32_sdwa v0, v38, v185 dst_sel:DWORD dst_unused:UNUSED_PAD src0_sel:WORD_1 src1_sel:DWORD
	v_add3_u32 v134, v36, v134, s46
	v_add3_u32 v135, v39, v135, s46
	v_and_b32_e32 v138, 0xffff0000, v138
	s_mov_b32 s12, 0x50000
	v_add3_u32 v0, v38, v0, s46
	v_and_b32_e32 v135, 0xffff0000, v135
	v_or_b32_sdwa v134, v138, v134 dst_sel:DWORD dst_unused:UNUSED_PAD src0_sel:DWORD src1_sel:WORD_1
	v_add_co_u32_e32 v138, vcc, s12, v2
	v_or_b32_sdwa v135, v135, v0 dst_sel:DWORD dst_unused:UNUSED_PAD src0_sel:DWORD src1_sel:WORD_1
	s_nop 0
	v_addc_co_u32_e32 v139, vcc, 0, v3, vcc
	global_store_dwordx4 v[138:139], v[132:135], off
	v_and_b32_sdwa v0, v22, v185 dst_sel:DWORD dst_unused:UNUSED_PAD src0_sel:WORD_1 src1_sel:DWORD
	v_add3_u32 v0, v22, v0, s46
	v_and_b32_sdwa v133, v23, v185 dst_sel:DWORD dst_unused:UNUSED_PAD src0_sel:WORD_1 src1_sel:DWORD
	v_and_b32_sdwa v134, v21, v185 dst_sel:DWORD dst_unused:UNUSED_PAD src0_sel:WORD_1 src1_sel:DWORD
	v_and_b32_sdwa v132, v20, v185 dst_sel:DWORD dst_unused:UNUSED_PAD src0_sel:WORD_1 src1_sel:DWORD
	v_add3_u32 v133, v23, v133, s46
	v_add3_u32 v134, v21, v134, s46
	v_add3_u32 v132, v20, v132, s46
	v_and_b32_e32 v133, 0xffff0000, v133
	v_and_b32_e32 v134, 0xffff0000, v134
	v_and_b32_sdwa v135, v27, v185 dst_sel:DWORD dst_unused:UNUSED_PAD src0_sel:WORD_1 src1_sel:DWORD
	v_and_b32_sdwa v138, v25, v185 dst_sel:DWORD dst_unused:UNUSED_PAD src0_sel:WORD_1 src1_sel:DWORD
; __device__ __forceinline__ unsigned pack2(float lo, float hi) { return (unsigned)f2bf(lo) | ((unsigned)f2bf(hi) << 16); }
;     __device__ __forceinline__ void operator()(const f32x4 (&acc)[2][2][4][2], const Unit& u, int wr, int wc, int fr, int fq) const {
;         EPIP_ROWS( uint4 o; o.x = pack2(v0[0], v0[1]); o.y = pack2(v0[2], v0[3]); o.z = pack2(v1[0], v1[1]); o.w = pack2(v1[2], v1[3]); *(uint4*)(O + row * ldc + col8 + co) = o; )
	v_or_b32_sdwa v133, v133, v0 dst_sel:DWORD dst_unused:UNUSED_PAD src0_sel:DWORD src1_sel:WORD_1
	v_or_b32_sdwa v132, v134, v132 dst_sel:DWORD dst_unused:UNUSED_PAD src0_sel:DWORD src1_sel:WORD_1
	v_and_b32_sdwa v0, v26, v185 dst_sel:DWORD dst_unused:UNUSED_PAD src0_sel:WORD_1 src1_sel:DWORD
	v_and_b32_sdwa v134, v24, v185 dst_sel:DWORD dst_unused:UNUSED_PAD src0_sel:WORD_1 src1_sel:DWORD
	v_add3_u32 v135, v27, v135, s46
	v_add3_u32 v138, v25, v138, s46
	v_add3_u32 v134, v24, v134, s46
	v_add3_u32 v0, v26, v0, s46
	v_and_b32_e32 v135, 0xffff0000, v135
	v_and_b32_e32 v138, 0xffff0000, v138
	v_or_b32_sdwa v135, v135, v0 dst_sel:DWORD dst_unused:UNUSED_PAD src0_sel:DWORD src1_sel:WORD_1
	v_or_b32_sdwa v134, v138, v134 dst_sel:DWORD dst_unused:UNUSED_PAD src0_sel:DWORD src1_sel:WORD_1
	global_store_dwordx4 v[136:137], v[132:135], off offset:256
	v_and_b32_sdwa v0, v42, v185 dst_sel:DWORD dst_unused:UNUSED_PAD src0_sel:WORD_1 src1_sel:DWORD
	s_mov_b64 s[12:13], 0x58000
	v_and_b32_sdwa v133, v43, v185 dst_sel:DWORD dst_unused:UNUSED_PAD src0_sel:WORD_1 src1_sel:DWORD
	v_and_b32_sdwa v134, v41, v185 dst_sel:DWORD dst_unused:UNUSED_PAD src0_sel:WORD_1 src1_sel:DWORD
	v_and_b32_sdwa v132, v40, v185 dst_sel:DWORD dst_unused:UNUSED_PAD src0_sel:WORD_1 src1_sel:DWORD
	v_add3_u32 v133, v43, v133, s46
	v_add3_u32 v134, v41, v134, s46
	v_add3_u32 v132, v40, v132, s46
	v_add3_u32 v0, v42, v0, s46
	v_and_b32_e32 v133, 0xffff0000, v133
	v_and_b32_e32 v134, 0xffff0000, v134
	v_and_b32_sdwa v135, v47, v185 dst_sel:DWORD dst_unused:UNUSED_PAD src0_sel:WORD_1 src1_sel:DWORD
	v_and_b32_sdwa v138, v45, v185 dst_sel:DWORD dst_unused:UNUSED_PAD src0_sel:WORD_1 src1_sel:DWORD
	v_lshl_add_u64 v[136:137], v[2:3], 0, s[12:13]
	v_or_b32_sdwa v133, v133, v0 dst_sel:DWORD dst_unused:UNUSED_PAD src0_sel:DWORD src1_sel:WORD_1
	v_or_b32_sdwa v132, v134, v132 dst_sel:DWORD dst_unused:UNUSED_PAD src0_sel:DWORD src1_sel:WORD_1
	v_and_b32_sdwa v0, v46, v185 dst_sel:DWORD dst_unused:UNUSED_PAD src0_sel:WORD_1 src1_sel:DWORD
	v_and_b32_sdwa v134, v44, v185 dst_sel:DWORD dst_unused:UNUSED_PAD src0_sel:WORD_1 src1_sel:DWORD
	v_add3_u32 v135, v47, v135, s46
	v_add3_u32 v138, v45, v138, s46
	s_mov_b32 s12, 0x58000
	v_add3_u32 v134, v44, v134, s46
	v_add3_u32 v0, v46, v0, s46
	v_and_b32_e32 v135, 0xffff0000, v135
	v_and_b32_e32 v138, 0xffff0000, v138
	v_add_co_u32_e32 v2, vcc, s12, v2
	v_or_b32_sdwa v135, v135, v0 dst_sel:DWORD dst_unused:UNUSED_PAD src0_sel:DWORD src1_sel:WORD_1
	v_or_b32_sdwa v134, v138, v134 dst_sel:DWORD dst_unused:UNUSED_PAD src0_sel:DWORD src1_sel:WORD_1
	v_addc_co_u32_e32 v3, vcc, 0, v3, vcc
	global_store_dwordx4 v[2:3], v[132:135], off
	v_and_b32_sdwa v3, v31, v185 dst_sel:DWORD dst_unused:UNUSED_PAD src0_sel:WORD_1 src1_sel:DWORD
	v_and_b32_sdwa v0, v30, v185 dst_sel:DWORD dst_unused:UNUSED_PAD src0_sel:WORD_1 src1_sel:DWORD
	v_and_b32_sdwa v132, v29, v185 dst_sel:DWORD dst_unused:UNUSED_PAD src0_sel:WORD_1 src1_sel:DWORD
	v_add3_u32 v3, v31, v3, s46
	v_and_b32_sdwa v2, v28, v185 dst_sel:DWORD dst_unused:UNUSED_PAD src0_sel:WORD_1 src1_sel:DWORD
	v_add3_u32 v0, v30, v0, s46
	v_add3_u32 v132, v29, v132, s46
	v_and_b32_e32 v3, 0xffff0000, v3
	v_add3_u32 v2, v28, v2, s46
	v_and_b32_e32 v132, 0xffff0000, v132
	v_or_b32_sdwa v133, v3, v0 dst_sel:DWORD dst_unused:UNUSED_PAD src0_sel:DWORD src1_sel:WORD_1
	v_and_b32_sdwa v3, v35, v185 dst_sel:DWORD dst_unused:UNUSED_PAD src0_sel:WORD_1 src1_sel:DWORD
	v_and_b32_sdwa v134, v33, v185 dst_sel:DWORD dst_unused:UNUSED_PAD src0_sel:WORD_1 src1_sel:DWORD
	v_or_b32_sdwa v132, v132, v2 dst_sel:DWORD dst_unused:UNUSED_PAD src0_sel:DWORD src1_sel:WORD_1
	v_and_b32_sdwa v0, v34, v185 dst_sel:DWORD dst_unused:UNUSED_PAD src0_sel:WORD_1 src1_sel:DWORD
	v_and_b32_sdwa v2, v32, v185 dst_sel:DWORD dst_unused:UNUSED_PAD src0_sel:WORD_1 src1_sel:DWORD
	v_add3_u32 v3, v35, v3, s46
	v_add3_u32 v134, v33, v134, s46
	v_add3_u32 v2, v32, v2, s46
	v_add3_u32 v0, v34, v0, s46
	v_and_b32_e32 v3, 0xffff0000, v3
	v_and_b32_e32 v134, 0xffff0000, v134
	v_or_b32_sdwa v135, v3, v0 dst_sel:DWORD dst_unused:UNUSED_PAD src0_sel:DWORD src1_sel:WORD_1
	v_or_b32_sdwa v134, v134, v2 dst_sel:DWORD dst_unused:UNUSED_PAD src0_sel:DWORD src1_sel:WORD_1
	global_store_dwordx4 v[136:137], v[132:135], off offset:256
	s_mov_b64 s[12:13], 0
	s_mov_b64 s[14:15], 0

; template <class Epi>
; __device__ __forceinline__ void gemm_phase(LAS unsigned char* lds, const Gemm g, const Epi& E) {
;     ...
;         if (is_mid) E.mid(acc, cur, wr, wc, fr, fq); else E(acc, cur, wr, wc, fr, fq);
;         if (!has_next) break;
.LBB0_323:
	s_or_b64 exec, exec, s[14:15]
	s_waitcnt vmcnt(0)
	s_mov_b64 s[12:13], 0

; __device__ __forceinline__ void fast_barrier(unsigned* bar, unsigned target) {
;     asm volatile("s_waitcnt vmcnt(0)" ::: "memory");
;     __syncthreads();
;     if (threadIdx.x == 0) {
;         __builtin_amdgcn_fence(__ATOMIC_RELEASE, "agent");
;         asm volatile("s_waitcnt vmcnt(0)" ::: "memory");
;         (void)__hip_atomic_fetch_add(bar, 1u, __ATOMIC_RELAXED, __HIP_MEMORY_SCOPE_AGENT);
;         unsigned spins = 0;
;         while (__hip_atomic_load(bar, __ATOMIC_RELAXED, __HIP_MEMORY_SCOPE_AGENT) < target) { __builtin_amdgcn_s_sleep(1); if (++spins > (1u << 24)) break; }
;         __builtin_amdgcn_fence(__ATOMIC_ACQUIRE, "agent");
;         asm volatile("s_waitcnt vmcnt(0)" ::: "memory");
;     }
;     __syncthreads();
; }
; __global__ void __launch_bounds__(512, 2) fwd_megakernel(Params p, int ph_lo, int ph_hi) {
;     extern __shared__ __attribute__((aligned(16))) unsigned char shm[];
;     cg::grid_group grid = cg::this_grid();
;     unsigned nbar = 0;
;     for (int ph = ph_lo; ph < ph_hi; ++ph) {
;         KP kp = (KP)__builtin_amdgcn_kernarg_segment_ptr();
;         asm volatile("" : "+s"(kp));
;         run_phase(kp, ph, shm);
;         if (ph + 1 < ph_hi) {
;             if (ph == ph_lo) grid.sync();
;             else { ++nbar; fast_barrier((unsigned*)(kp->ws + OFF_BAR), nbar * gridDim.x); }
.LBB0_478:
	s_add_i32 s2, s80, 1
	s_cmp_ge_i32 s2, s63
	s_mov_b64 s[0:1], -1
	s_cbranch_scc1 .LBB0_5
	s_cmp_lg_u32 s80, s62
	s_waitcnt vmcnt(0)
	s_waitcnt lgkmcnt(0)
	s_add_i32 s10, s79, 1
	s_waitcnt vmcnt(0)
	s_barrier
	s_mov_b64 s[0:1], exec
	v_readlane_b32 s4, v249, 4
	v_readlane_b32 s5, v249, 5
	s_and_b64 s[4:5], s[0:1], s[4:5]
	s_mov_b64 exec, s[4:5]
	s_cbranch_execz .LBB0_497
	s_load_dwordx2 s[4:5], s[82:83], 0x108
	s_mov_b64 s[6:7], exec
	buffer_wbl2 sc1
	s_waitcnt lgkmcnt(0)
	s_waitcnt vmcnt(0)
	v_mbcnt_lo_u32_b32 v0, s6, 0
	s_add_u32 s4, s4, 0.5
	v_mbcnt_hi_u32_b32 v0, s7, v0
	s_addc_u32 s5, s5, 0
	v_cmp_eq_u32_e32 vcc, 0, v0
	s_and_saveexec_b64 s[8:9], vcc
	s_cbranch_execz .LBB0_483
	s_bcnt1_i32_b64 s6, s[6:7]
	v_mov_b32_e32 v0, s6
	global_atomic_add v1, v0, s[4:5]
